# GEMM stage tiles re-laid out: each LDS-DMA covers 8 full 128B rows (was 16 half rows), conflict-free XOR swizzle
# speedup vs baseline: 1.0012x; 1.0012x over previous
; #define PG8_STAGE(bufoff, gbase, voff) do { _Pragma("unroll") for (int _i = 0; _i < 2; ++_i) \
;         __builtin_amdgcn_global_load_lds((const unsigned*)((const char*)(gbase) + (voff)[_i]), (LAS unsigned*)(lds + (bufoff) + ldsw + _i * 8192), 16, 0, 0); } while (0)
; template <class Epi, class Sched, bool ALIGN_EPI = false, bool SP2 = false>
; __device__ __forceinline__ void gemm_phase(LAS unsigned char* lds, const Gemm g, const Sched& S, const Epi& E) {
;     const int tid = threadIdx.x, wid = __builtin_amdgcn_readfirstlane(tid >> 6), lane = tid & 63, wr = wid >> 2, wc = wid & 3, fr = lane & 15, fq = lane >> 4;
;     const int K = g.K, nt = K / BK;
;     unsigned voffA[2], voffB[2];
; #pragma unroll
;     for (int i = 0; i < 2; ++i) { int R, C; stage_rc(tid * 16 + i * 8192, R, C); const int Rq = Epi::PERM ? perm32(R & 31) : (R & 31); const int Rb = Epi::COLS64 ? (64 * (R >> 5) + Rq) : ((R & ~31) + Rq);
;         voffA[i] = (unsigned)(R * g.lda + C) * 2u; voffB[i] = (unsigned)(Rb * g.ldb + C) * 2u; }
;     const size_t kstep = (size_t)(BK * 2);
;     const size_t hsA = (size_t)HALF * g.lda * 2, hsB = (size_t)(Epi::COLS64 ? 32 : HALF) * g.ldb * 2;
;     const size_t tsA = 2 * hsA, tsB = (size_t)BM * g.ldb * 2;
;     const unsigned ldsw = (unsigned)wid * 1024u;
;     const int aoff = lds_byte(wr * 64 + fr, fq * 8), boff = lds_byte(wc * 32 + fr, fq * 8);
;     ...
;     Unit cur, nxt; int ui = 0;
;     if (!S.next(0, cur)) return;
;     f32x4 acc[2][2][4][2];
; #pragma unroll
;     for (int a = 0; a < 2; ++a)
; #pragma unroll
;         for (int b = 0; b < 2; ++b)
; #pragma unroll
;             for (int m = 0; m < 4; ++m)
; #pragma unroll
;                 for (int n = 0; n < 2; ++n) acc[a][b][m][n] = (f32x4){0.f, 0.f, 0.f, 0.f};
;     bf16x8 At[4][2], B0[2][2], B1[2][2];
;     const char* cA = (const char*)g.A + (size_t)cur.pm * tsA; const char* cB = (const char*)g.Bt + (size_t)cur.pn * tsB;
;     S.a_ready(cur);
;     if constexpr (SP2) {
;         PG8_STAGE(PG8_SB(0, 0), cB, voffB); PG8_STAGE(PG8_SB(0, 1), cB + hsB, voffB); PG8_STAGE(PG8_SA(0, 0), cA, voffA); PG8_STAGE(PG8_SA(0, 1), cA + hsA, voffA);
;         if (wr == 1) PG8_BAR;
;         PG8_WAIT_V(2); PG8_BAR;
;         PG8_STAGE(PG8_SB(1, 0), cB + kstep, voffB); PG8_STAGE(PG8_SA(1, 0), cA + kstep, voffA); PG8_STAGE(PG8_SB(1, 1), cB + hsB + kstep, voffB);
;         PG8_WAIT_V(6); PG8_BAR;
.LBB0_51:
	s_andn2_b64 vcc, exec, s[0:1]
	s_cbranch_vccnz .LBB0_135
	v_lshrrev_b32_e32 v4, 1, v202
	v_lshrrev_b32_e32 v5, 5, v202
	v_lshlrev_b32_e32 v0, 4, v202
	v_and_b32_e32 v1, 32, v202
	v_bfe_u32 v3, v202, 2, 4
	v_and_b32_e32 v4, 24, v4
	v_and_b32_e32 v5, 4, v5
	v_bfe_u32 v6, v202, 2, 2
	s_waitcnt vmcnt(9)
	v_lshrrev_b32_e32 v11, 3, v202
	s_movk_i32 s1, 0x70
	v_lshrrev_b32_e32 v2, 2, v202
	v_bitop3_b32 v8, v0, v1, 48 bitop3:0x6c
	v_and_b32_e32 v9, 64, v202
	v_or3_b32 v4, v5, v6, v4
	v_and_or_b32 v5, v11, s1, v3
	s_movk_i32 s1, 0xc0
	v_or_b32_e32 v1, v8, v9
	v_and_or_b32 v2, v2, s1, v4
	v_lshrrev_b32_e32 v1, 1, v1
	v_mul_u32_u24_e32 v2, 0x1040, v2
	v_or_b32_e32 v2, v2, v1
	v_add_u32_e32 v0, 0x2000, v0
	v_lshrrev_b32_e32 v2, 7, v0
	s_movk_i32 s1, 0xf0
	s_lshr_b32 s0, s4, 6
	v_and_or_b32 v2, v2, s1, v3
	v_lshrrev_b32_e32 v0, 6, v0
	s_movk_i32 s1, 0x1c0
	v_and_or_b32 v0, v0, s1, v4
	s_lshr_b32 s1, s4, 8
	s_lshl_b32 s67, s0, 10
	s_mul_i32 s6, s66, 0x208000
	s_mul_hi_i32 s7, s66, 0x208000
	s_add_u32 s6, s64, s6
	s_addc_u32 s7, s65, s7
	s_add_i32 s68, s67, 0
	v_mul_u32_u24_e32 v0, 0x1040, v0
	s_add_i32 m0, s68, 0x10000
	v_or_b32_e32 v0, v0, v1
	v_lshrrev_b32_e32 v247, 6, v202
	v_bfe_u32 v242, v202, 3, 3
	v_and_b32_e32 v243, 7, v202
	v_xor_b32_e32 v243, v243, v242
	v_lshlrev_b32_e32 v243, 4, v243
	v_lshl_add_u32 v244, v247, 3, v242
	v_mul_u32_u24_e32 v244, 0x2080, v244
	v_add_u32_e32 v132, v244, v243
	v_add_u32_e32 v136, 0x82000, v132
	v_lshrrev_b32_e32 v245, 2, v247
	v_lshlrev_b32_e32 v245, 6, v245
	v_and_b32_e32 v246, 1, v247
	v_lshl_add_u32 v245, v246, 4, v245
	v_bfe_u32 v246, v247, 1, 1
	v_lshl_add_u32 v245, v246, 2, v245
	v_lshrrev_b32_e32 v246, 2, v242
	v_lshl_add_u32 v245, v246, 3, v245
	v_and_b32_e32 v246, 3, v242
	v_add_u32_e32 v245, v245, v246
	v_mul_u32_u24_e32 v245, 0x2080, v245
	v_add_u32_e32 v134, v245, v243
	v_add_u32_e32 v138, 0x104000, v134
	global_load_lds_dwordx4 v134, s[6:7]
	s_add_i32 m0, s68, 0x12000
	s_add_u32 s8, s6, 0x41000
	global_load_lds_dwordx4 v138, s[6:7]
	s_addc_u32 s9, s7, 0
	s_add_i32 m0, s68, 0x14000
	s_mul_i32 s20, s88, 0x208000
	global_load_lds_dwordx4 v134, s[8:9]
	s_add_i32 m0, s68, 0x16000
	v_mul_u32_u24_e32 v10, 0x1040, v5
	s_mul_hi_i32 s5, s88, 0x208000
	s_add_u32 s62, s34, s20
	v_or_b32_e32 v5, v1, v10
	v_mul_u32_u24_e32 v12, 0x1040, v2
	s_addc_u32 s63, s35, s5
	s_add_i32 s69, s68, 0x2000
	v_or_b32_e32 v2, v12, v1
	global_load_lds_dwordx4 v138, s[8:9]
	s_mov_b32 m0, s68
	s_add_u32 s8, s62, 0x104000
	global_load_lds_dwordx4 v132, s[62:63]
	s_mov_b32 m0, s69
	s_addc_u32 s9, s63, 0
	s_add_i32 s70, s68, 0x4000
	global_load_lds_dwordx4 v136, s[62:63]
	s_mov_b32 m0, s70
	s_add_i32 s71, s68, 0x6000
	global_load_lds_dwordx4 v132, s[8:9]
	s_mov_b32 m0, s71
	v_mov_b32_e32 v141, 0
	global_load_lds_dwordx4 v136, s[8:9]
	v_mov_b32_e32 v135, v141
	v_mov_b32_e32 v139, v141
	v_mov_b32_e32 v133, v141
	v_mov_b32_e32 v137, v141
	s_cmp_eq_u32 s1, 1
	s_mov_b32 s21, 0
	v_lshl_add_u64 v[6:7], s[6:7], 0, v[134:135]
	v_lshl_add_u64 v[4:5], s[6:7], 0, v[138:139]
	v_lshl_add_u64 v[0:1], s[62:63], 0, v[132:133]
	s_cselect_b64 s[38:39], -1, 0
	s_cmp_lg_u32 s1, 1
	v_lshl_add_u64 v[2:3], s[62:63], 0, v[136:137]
	s_cbranch_scc1 .LBB0_54
	s_barrier
.LBB0_54:
	s_lshl_b32 s5, s33, 11
	s_mov_b64 s[46:47], 0x80
	s_add_i32 s5, s5, 0
	s_and_b32 s72, s0, 3
	s_add_i32 m0, s68, 0x18000
	v_lshl_add_u64 v[6:7], v[6:7], 0, s[46:47]
	s_add_i32 s5, s5, 0x20000
	s_lshl_b32 s73, s1, 6
	s_lshl_b32 s8, s1, 13
	s_lshl_b32 s9, s72, 12
	s_waitcnt vmcnt(2)
	s_barrier
	global_load_lds_dwordx4 v[6:7], off
	v_lshl_add_u64 v[4:5], v[4:5], 0, s[46:47]
	s_add_i32 m0, s68, 0x1a000
	s_add_i32 s76, s68, 0x8000
	s_add_i32 s77, s68, 0xa000
	global_load_lds_dwordx4 v[4:5], off
	v_lshl_add_u64 v[0:1], v[0:1], 0, s[46:47]
	s_mov_b32 m0, s76
	s_add_u32 s0, s6, 0x41080
	global_load_lds_dwordx4 v[0:1], off
	v_lshl_add_u64 v[0:1], v[2:3], 0, s[46:47]
	s_mov_b32 m0, s77
	s_addc_u32 s1, s7, 0
	global_load_lds_dwordx4 v[0:1], off
	s_add_i32 m0, s68, 0x1c000
	v_lshl_add_u64 v[0:1], s[0:1], 0, v[134:135]
	global_load_lds_dwordx4 v[0:1], off
	v_lshl_add_u64 v[0:1], s[0:1], 0, v[138:139]
	s_add_i32 m0, s68, 0x1e000
	v_bfe_u32 v2, v202, 4, 2
	global_load_lds_dwordx4 v[0:1], off
	v_and_b32_e32 v154, 15, v202
	v_lshlrev_b32_e32 v0, 4, v2
	v_lshlrev_b32_e32 v4, 2, v202
	v_lshlrev_b32_e32 v5, 6, v202
	s_movk_i32 s0, 0x3c0
	v_lshl_or_b32 v3, v154, 6, v0
	v_and_b32_e32 v4, 32, v4
	v_and_or_b32 v0, v5, s0, v0
	v_lshrrev_b32_e32 v1, 4, v202
	v_bitop3_b32 v3, v3, s8, v4 bitop3:0xde
	v_bitop3_b32 v156, s9, v0, v4 bitop3:0xf6
	v_and_b32_e32 v4, 7, v202
	s_waitcnt vmcnt(6)
	s_cmpk_lt_u32 s4, 0x100
	v_bfe_u32 v157, v202, 3, 3
	v_lshlrev_b32_e32 v0, 3, v4
	v_bitop3_b32 v1, v1, v4, 3 bitop3:0x6c
	v_bitop3_b32 v4, v2, v4, 4 bitop3:0x36
	v_bitop3_b32 v5, v11, v202, 7 bitop3:0x28
	v_add_u16_e32 v7, v8, v9
	s_cselect_b64 s[50:51], -1, 0
	s_lshl_b32 s4, s72, 6
	v_lshlrev_b32_e32 v1, 4, v1
	v_lshlrev_b32_e32 v4, 4, v4
	v_lshlrev_b32_e32 v5, 4, v5
	v_cmp_eq_u32_e64 s[0:1], 0, v2
	v_lshl_add_u32 v2, v154, 7, s5
	v_lshl_add_u32 v6, v157, 7, s5
	v_lshrrev_b16_e32 v7, 1, v7
	s_add_i32 s82, 0, 0x10000
	s_add_i32 s83, 0, 0x14000
	v_lshlrev_b32_e32 v140, 1, v0
	v_mbcnt_lo_u32_b32 v0, -1, 0
	s_ashr_i32 s79, s3, 31
	s_ashr_i32 s80, s2, 31
	v_mov_b32_e32 v142, v132
	v_mov_b32_e32 v143, v141
	v_mov_b32_e32 v144, v136
	v_mov_b32_e32 v145, v141
	v_mov_b64_e32 v[146:147], 0x700
	v_mov_b64_e32 v[148:149], 0x6ff
	s_movk_i32 s81, 0xe1
	v_add_u32_e32 v158, s82, v156
	v_add_u32_e32 v159, s83, v156
	v_add_u32_e32 v160, 0, v3
	v_and_b32_e32 v242, 15, v202
	v_bfe_u32 v243, v202, 4, 2
	v_and_b32_e32 v244, 7, v242
	v_xor_b32_e32 v243, v243, v244
	v_lshlrev_b32_e32 v243, 4, v243
	v_lshl_add_u32 v243, v244, 7, v243
	v_lshrrev_b32_e32 v244, 3, v242
	v_lshl_add_u32 v243, v244, 10, v243
	v_lshrrev_b32_e32 v247, 6, v202
	v_lshrrev_b32_e32 v244, 2, v247
	v_lshl_add_u32 v160, v244, 13, v243
	v_and_b32_e32 v244, 3, v247
	v_lshl_add_u32 v156, v244, 12, v243
	v_xor_b32_e32 v250, 64, v160
	v_add_u32_e32 v158, 0x10000, v156
	v_add_u32_e32 v159, 0x14000, v156
	v_xor_b32_e32 v251, 64, v158
	v_xor_b32_e32 v252, 64, v159
	s_movk_i32 s84, 0x3800
	s_lshl_b32 s20, s4, 1
	v_add_u32_e32 v161, v2, v1
	v_add_u32_e32 v162, v2, v4
	v_add_u32_e32 v163, v6, v5
	v_mbcnt_hi_u32_b32 v164, -1, v0
	s_mov_b32 s85, s21
	s_barrier
	s_waitcnt vmcnt(0)
	s_branch .LBB0_57

; #define PG8_STAGE(bufoff, gbase, voff) do { _Pragma("unroll") for (int _i = 0; _i < 2; ++_i) \
;         __builtin_amdgcn_global_load_lds((const unsigned*)((const char*)(gbase) + (voff)[_i]), (LAS unsigned*)(lds + (bufoff) + ldsw + _i * 8192), 16, 0, 0); } while (0)
; #define PG8_LDA(dst, b, h) do { _Pragma("unroll") for (int m = 0; m < 4; ++m) _Pragma("unroll") for (int k = 0; k < 2; ++k) dst[m][k] = *(const LAS bf16x8*)(lds + PG8_SA(b, h) + aoff + m * 2048 + k * 1024); } while (0)
; #define PG8_LDB(dst, b, h) do { _Pragma("unroll") for (int n = 0; n < 2; ++n) _Pragma("unroll") for (int k = 0; k < 2; ++k) dst[n][k] = *(const LAS bf16x8*)(lds + PG8_SB(b, h) + boff + n * 2048 + k * 1024); } while (0)
; #define PG8_MMA(ai, bj, At, Bt) do { __builtin_amdgcn_s_setprio(3); _Pragma("unroll") for (int m = 0; m < 4; ++m) _Pragma("unroll") for (int n = 0; n < 2; ++n) _Pragma("unroll") for (int k = 0; k < 2; ++k) \
;         acc[ai][bj][m][n] = __builtin_amdgcn_mfma_f32_16x16x32_bf16(Bt[n][k], At[m][k], acc[ai][bj][m][n], 0, 0, 0); __builtin_amdgcn_s_setprio(0); } while (0)
; #define PG8_WAIT_V(n) asm volatile("s_waitcnt vmcnt(" #n ")" ::: "memory")
; #define PG8_WAIT_L(n) asm volatile("s_waitcnt lgkmcnt(" #n ")" ::: "memory")
; #define PG8_BAR __builtin_amdgcn_s_barrier()
; #define PG8_SCHED __builtin_amdgcn_sched_barrier(0)
; template <class Epi, class Sched, bool ALIGN_EPI = false, bool SP2 = false>
; __device__ __forceinline__ void gemm_phase(LAS unsigned char* lds, const Gemm g, const Sched& S, const Epi& E) {
;     ...
;             const char* a1 = cA + (size_t)(t + 1) * kstep;
;             const char* a2 = last ? nA : cA + (size_t)(t + 2) * kstep; const char* b2 = last ? nB : cB + (size_t)(t + 2) * kstep;
;             const char* a3 = a2 + kstep; const char* b3 = b2 + kstep;
;             if (last && has_next) S.a_ready(nxt);
;             if constexpr (Epi::MID) { if (t == nt / 2) E.mid(acc, cur, wr, wc, fr, fq); }
;             if constexpr (SP2) {
;             PG8_LDB(B0, 0, 0); PG8_LDB(B1, 0, 1); PG8_SCHED; PG8_LDA(At, 0, 0); PG8_STAGE(PG8_SA(1, 1), a1 + hsA, voffA);
;             PG8_WAIT_V(8); PG8_WAIT_L(0); PG8_BAR; PG8_MMA(0, 0, At, B0); PG8_MMA(0, 1, At, B1); PG8_BAR; PG8_SCHED;
;             PG8_LDA(At, 0, 1); PG8_STAGE(PG8_SB(0, 0), b2, voffB); PG8_STAGE(PG8_SB(0, 1), b2 + hsB, voffB); PG8_STAGE(PG8_SA(0, 0), a2, voffA);
.LBB0_64:
	ds_read_b128 v[128:131], v158
	ds_read_b128 v[150:153], v251
	ds_read_b128 v[166:169], v158 offset:2048
	ds_read_b128 v[170:173], v251 offset:2048
	ds_read_b128 v[174:177], v159
	ds_read_b128 v[178:181], v252
	ds_read_b128 v[182:185], v159 offset:2048
	ds_read_b128 v[186:189], v252 offset:2048
	s_add_u32 s6, s4, 0xffefc080
	s_addc_u32 s7, s5, -1
	s_cmp_eq_u32 s91, 60
	s_cselect_b32 s63, s59, s7
	s_cselect_b32 s62, s58, s6
	s_cselect_b32 s7, s61, s90
	s_cselect_b32 s6, s60, s89
	v_lshl_add_u64 v[226:227], s[4:5], 0, v[142:143]
	s_add_i32 m0, s68, 0xc000
	ds_read_b128 v[190:193], v160
	ds_read_b128 v[194:197], v250
	ds_read_b128 v[198:201], v160 offset:2048
	ds_read_b128 v[206:209], v250 offset:2048
	ds_read_b128 v[210:213], v160 offset:4096
	ds_read_b128 v[214:217], v250 offset:4096
	ds_read_b128 v[218:221], v160 offset:6144
	ds_read_b128 v[222:225], v250 offset:6144
	global_load_lds_dwordx4 v[226:227], off
	v_lshl_add_u64 v[226:227], s[4:5], 0, v[144:145]
	s_add_i32 m0, s68, 0xe000
	s_nop 0
	global_load_lds_dwordx4 v[226:227], off
	s_waitcnt vmcnt(8)
	s_waitcnt lgkmcnt(0)
	s_barrier
	s_setprio 3
	s_waitcnt lgkmcnt(0)
	v_mfma_f32_16x16x32_bf16 v[124:127], v[128:131], v[190:193], v[124:127]
	v_mfma_f32_16x16x32_bf16 v[120:123], v[166:169], v[190:193], v[120:123]
	v_mfma_f32_16x16x32_bf16 v[108:111], v[128:131], v[198:201], v[108:111]
	v_mfma_f32_16x16x32_bf16 v[104:107], v[166:169], v[198:201], v[104:107]
	v_mfma_f32_16x16x32_bf16 v[92:95], v[128:131], v[210:213], v[92:95]
	v_mfma_f32_16x16x32_bf16 v[88:91], v[166:169], v[210:213], v[88:91]
	v_mfma_f32_16x16x32_bf16 v[76:79], v[128:131], v[218:221], v[76:79]
	v_mfma_f32_16x16x32_bf16 v[72:75], v[166:169], v[218:221], v[72:75]
	v_mfma_f32_16x16x32_bf16 v[124:127], v[150:153], v[194:197], v[124:127]
	v_mfma_f32_16x16x32_bf16 v[120:123], v[170:173], v[194:197], v[120:123]
	v_mfma_f32_16x16x32_bf16 v[108:111], v[150:153], v[206:209], v[108:111]
	v_mfma_f32_16x16x32_bf16 v[104:107], v[170:173], v[206:209], v[104:107]
	v_mfma_f32_16x16x32_bf16 v[92:95], v[150:153], v[214:217], v[92:95]
	v_mfma_f32_16x16x32_bf16 v[88:91], v[170:173], v[214:217], v[88:91]
	v_mfma_f32_16x16x32_bf16 v[76:79], v[150:153], v[222:225], v[76:79]
	v_mfma_f32_16x16x32_bf16 v[72:75], v[170:173], v[222:225], v[72:75]
	s_setprio 0
	s_setprio 3
	v_mfma_f32_16x16x32_bf16 v[116:119], v[174:177], v[190:193], v[116:119]
	v_mfma_f32_16x16x32_bf16 v[112:115], v[182:185], v[190:193], v[112:115]
	v_mfma_f32_16x16x32_bf16 v[100:103], v[174:177], v[198:201], v[100:103]
	v_mfma_f32_16x16x32_bf16 v[96:99], v[182:185], v[198:201], v[96:99]
	v_mfma_f32_16x16x32_bf16 v[84:87], v[174:177], v[210:213], v[84:87]
	v_mfma_f32_16x16x32_bf16 v[80:83], v[182:185], v[210:213], v[80:83]
	v_mfma_f32_16x16x32_bf16 v[68:71], v[174:177], v[218:221], v[68:71]
	v_mfma_f32_16x16x32_bf16 v[64:67], v[182:185], v[218:221], v[64:67]
	v_mfma_f32_16x16x32_bf16 v[116:119], v[178:181], v[194:197], v[116:119]
	v_mfma_f32_16x16x32_bf16 v[112:115], v[186:189], v[194:197], v[112:115]
	v_mfma_f32_16x16x32_bf16 v[100:103], v[178:181], v[206:209], v[100:103]
	v_mfma_f32_16x16x32_bf16 v[96:99], v[186:189], v[206:209], v[96:99]
	v_mfma_f32_16x16x32_bf16 v[84:87], v[178:181], v[214:217], v[84:87]
	v_mfma_f32_16x16x32_bf16 v[80:83], v[186:189], v[214:217], v[80:83]
	v_mfma_f32_16x16x32_bf16 v[68:71], v[178:181], v[222:225], v[68:71]
	v_mfma_f32_16x16x32_bf16 v[64:67], v[186:189], v[222:225], v[64:67]
	s_setprio 0
	s_barrier
	s_add_i32 s92, s82, s67
	v_lshl_add_u64 v[226:227], s[6:7], 0, v[134:135]
	s_mov_b32 m0, s92
	ds_read_b128 v[190:193], v160 offset:16384
	ds_read_b128 v[194:197], v250 offset:16384
	ds_read_b128 v[198:201], v160 offset:18432
	ds_read_b128 v[206:209], v250 offset:18432
	ds_read_b128 v[210:213], v160 offset:20480
	ds_read_b128 v[214:217], v250 offset:20480
	ds_read_b128 v[218:221], v160 offset:22528
	ds_read_b128 v[222:225], v250 offset:22528
	global_load_lds_dwordx4 v[226:227], off
	s_add_i32 m0, s92, 0x2000
	s_add_u32 s92, s6, 0x41000
	v_lshl_add_u64 v[228:229], s[6:7], 0, v[138:139]
	s_addc_u32 s93, s7, 0
	s_add_i32 s94, s83, s67
	global_load_lds_dwordx4 v[228:229], off
	v_lshl_add_u64 v[230:231], s[92:93], 0, v[134:135]
	s_mov_b32 m0, s94
	v_lshl_add_u64 v[232:233], s[62:63], 0, v[136:137]
	global_load_lds_dwordx4 v[230:231], off
	v_lshl_add_u64 v[230:231], s[92:93], 0, v[138:139]
	s_add_i32 m0, s94, 0x2000
	s_nop 0
	global_load_lds_dwordx4 v[230:231], off
	v_lshl_add_u64 v[230:231], s[62:63], 0, v[132:133]
	s_mov_b32 m0, s68
	s_nop 0
	global_load_lds_dwordx4 v[230:231], off
	s_mov_b32 m0, s69
	s_nop 0
	global_load_lds_dwordx4 v[232:233], off
	s_waitcnt vmcnt(8)
	s_waitcnt lgkmcnt(0)
	s_barrier
; #define PG8_STAGE(bufoff, gbase, voff) do { _Pragma("unroll") for (int _i = 0; _i < 2; ++_i) \
;         __builtin_amdgcn_global_load_lds((const unsigned*)((const char*)(gbase) + (voff)[_i]), (LAS unsigned*)(lds + (bufoff) + ldsw + _i * 8192), 16, 0, 0); } while (0)
; #define PG8_LDA(dst, b, h) do { _Pragma("unroll") for (int m = 0; m < 4; ++m) _Pragma("unroll") for (int k = 0; k < 2; ++k) dst[m][k] = *(const LAS bf16x8*)(lds + PG8_SA(b, h) + aoff + m * 2048 + k * 1024); } while (0)
; #define PG8_LDB(dst, b, h) do { _Pragma("unroll") for (int n = 0; n < 2; ++n) _Pragma("unroll") for (int k = 0; k < 2; ++k) dst[n][k] = *(const LAS bf16x8*)(lds + PG8_SB(b, h) + boff + n * 2048 + k * 1024); } while (0)
; #define PG8_MMA(ai, bj, At, Bt) do { __builtin_amdgcn_s_setprio(3); _Pragma("unroll") for (int m = 0; m < 4; ++m) _Pragma("unroll") for (int n = 0; n < 2; ++n) _Pragma("unroll") for (int k = 0; k < 2; ++k) \
;         acc[ai][bj][m][n] = __builtin_amdgcn_mfma_f32_16x16x32_bf16(Bt[n][k], At[m][k], acc[ai][bj][m][n], 0, 0, 0); __builtin_amdgcn_s_setprio(0); } while (0)
; #define PG8_WAIT_V(n) asm volatile("s_waitcnt vmcnt(" #n ")" ::: "memory")
; #define PG8_WAIT_L(n) asm volatile("s_waitcnt lgkmcnt(" #n ")" ::: "memory")
; #define PG8_BAR __builtin_amdgcn_s_barrier()
; #define PG8_SCHED __builtin_amdgcn_sched_barrier(0)
; template <class Epi, class Sched, bool ALIGN_EPI = false, bool SP2 = false>
; __device__ __forceinline__ void gemm_phase(LAS unsigned char* lds, const Gemm g, const Sched& S, const Epi& E) {
;     ...
;             PG8_WAIT_V(8); PG8_WAIT_L(0); PG8_BAR; PG8_MMA(1, 0, At, B0); PG8_MMA(1, 1, At, B1); PG8_BAR; PG8_SCHED;
;             PG8_LDB(B0, 1, 0); PG8_LDB(B1, 1, 1); PG8_SCHED; PG8_LDA(At, 1, 0); PG8_STAGE(PG8_SA(0, 1), a2 + hsA, voffA);
;             PG8_WAIT_V(8); PG8_WAIT_L(0); PG8_BAR; PG8_MMA(0, 0, At, B0); PG8_MMA(0, 1, At, B1); PG8_BAR; PG8_SCHED;
	s_setprio 3
	s_waitcnt lgkmcnt(0)
	v_mfma_f32_16x16x32_bf16 v[60:63], v[128:131], v[190:193], v[60:63]
	v_mfma_f32_16x16x32_bf16 v[56:59], v[166:169], v[190:193], v[56:59]
	v_mfma_f32_16x16x32_bf16 v[44:47], v[128:131], v[198:201], v[44:47]
	v_mfma_f32_16x16x32_bf16 v[40:43], v[166:169], v[198:201], v[40:43]
	v_mfma_f32_16x16x32_bf16 v[28:31], v[128:131], v[210:213], v[28:31]
	v_mfma_f32_16x16x32_bf16 v[24:27], v[166:169], v[210:213], v[24:27]
	v_mfma_f32_16x16x32_bf16 v[12:15], v[128:131], v[218:221], v[12:15]
	v_mfma_f32_16x16x32_bf16 v[8:11], v[166:169], v[218:221], v[8:11]
	v_mfma_f32_16x16x32_bf16 v[60:63], v[150:153], v[194:197], v[60:63]
	v_mfma_f32_16x16x32_bf16 v[56:59], v[170:173], v[194:197], v[56:59]
	v_mfma_f32_16x16x32_bf16 v[44:47], v[150:153], v[206:209], v[44:47]
	v_mfma_f32_16x16x32_bf16 v[40:43], v[170:173], v[206:209], v[40:43]
	v_mfma_f32_16x16x32_bf16 v[28:31], v[150:153], v[214:217], v[28:31]
	v_mfma_f32_16x16x32_bf16 v[24:27], v[170:173], v[214:217], v[24:27]
	v_mfma_f32_16x16x32_bf16 v[12:15], v[150:153], v[222:225], v[12:15]
	v_mfma_f32_16x16x32_bf16 v[8:11], v[170:173], v[222:225], v[8:11]
	s_setprio 0
	s_setprio 3
	v_mfma_f32_16x16x32_bf16 v[52:55], v[174:177], v[190:193], v[52:55]
	v_mfma_f32_16x16x32_bf16 v[48:51], v[182:185], v[190:193], v[48:51]
	v_mfma_f32_16x16x32_bf16 v[36:39], v[174:177], v[198:201], v[36:39]
	v_mfma_f32_16x16x32_bf16 v[32:35], v[182:185], v[198:201], v[32:35]
	v_mfma_f32_16x16x32_bf16 v[20:23], v[174:177], v[210:213], v[20:23]
	v_mfma_f32_16x16x32_bf16 v[16:19], v[182:185], v[210:213], v[16:19]
	v_mfma_f32_16x16x32_bf16 v[4:7], v[174:177], v[218:221], v[4:7]
	v_mfma_f32_16x16x32_bf16 v[0:3], v[182:185], v[218:221], v[0:3]
	v_mfma_f32_16x16x32_bf16 v[52:55], v[178:181], v[194:197], v[52:55]
	v_mfma_f32_16x16x32_bf16 v[48:51], v[186:189], v[194:197], v[48:51]
	v_mfma_f32_16x16x32_bf16 v[36:39], v[178:181], v[206:209], v[36:39]
	v_mfma_f32_16x16x32_bf16 v[32:35], v[186:189], v[206:209], v[32:35]
	v_mfma_f32_16x16x32_bf16 v[20:23], v[178:181], v[214:217], v[20:23]
	v_mfma_f32_16x16x32_bf16 v[16:19], v[186:189], v[214:217], v[16:19]
	v_mfma_f32_16x16x32_bf16 v[4:7], v[178:181], v[222:225], v[4:7]
	v_mfma_f32_16x16x32_bf16 v[0:3], v[186:189], v[222:225], v[0:3]
	s_setprio 0
	s_barrier
	s_add_i32 s92, 0, 0x18000
	v_add_u32_e32 v165, s92, v156
	v_xor_b32_e32 v253, 64, v165
	s_add_i32 s93, 0, 0x1c000
	ds_read_b128 v[128:131], v165
	ds_read_b128 v[150:153], v253
	ds_read_b128 v[166:169], v165 offset:2048
	ds_read_b128 v[170:173], v253 offset:2048
	v_add_u32_e32 v165, s93, v156
	v_xor_b32_e32 v253, 64, v165
	ds_read_b128 v[174:177], v165
	ds_read_b128 v[178:181], v253
	ds_read_b128 v[182:185], v165 offset:2048
	ds_read_b128 v[186:189], v253 offset:2048
	s_add_u32 s62, s62, 0x104000
	s_addc_u32 s63, s63, 0
	s_mov_b32 m0, s70
	v_lshl_add_u64 v[234:235], s[62:63], 0, v[132:133]
	ds_read_b128 v[190:193], v160 offset:32768
	ds_read_b128 v[194:197], v250 offset:32768
	ds_read_b128 v[198:201], v160 offset:34816
	ds_read_b128 v[206:209], v250 offset:34816
	ds_read_b128 v[210:213], v160 offset:36864
	ds_read_b128 v[214:217], v250 offset:36864
	ds_read_b128 v[218:221], v160 offset:38912
	ds_read_b128 v[222:225], v250 offset:38912
	global_load_lds_dwordx4 v[234:235], off
	v_lshl_add_u64 v[234:235], s[62:63], 0, v[136:137]
	s_mov_b32 m0, s71
	s_nop 0
	global_load_lds_dwordx4 v[234:235], off
	s_waitcnt vmcnt(8)
	s_waitcnt lgkmcnt(0)
	s_barrier
	s_setprio 3
	s_waitcnt lgkmcnt(0)
	v_mfma_f32_16x16x32_bf16 v[124:127], v[128:131], v[190:193], v[124:127]
	v_mfma_f32_16x16x32_bf16 v[120:123], v[166:169], v[190:193], v[120:123]
	v_mfma_f32_16x16x32_bf16 v[108:111], v[128:131], v[198:201], v[108:111]
	v_mfma_f32_16x16x32_bf16 v[104:107], v[166:169], v[198:201], v[104:107]
	v_mfma_f32_16x16x32_bf16 v[92:95], v[128:131], v[210:213], v[92:95]
	v_mfma_f32_16x16x32_bf16 v[88:91], v[166:169], v[210:213], v[88:91]
	v_mfma_f32_16x16x32_bf16 v[76:79], v[128:131], v[218:221], v[76:79]
	v_mfma_f32_16x16x32_bf16 v[72:75], v[166:169], v[218:221], v[72:75]
	v_mfma_f32_16x16x32_bf16 v[124:127], v[150:153], v[194:197], v[124:127]
	v_mfma_f32_16x16x32_bf16 v[120:123], v[170:173], v[194:197], v[120:123]
	v_mfma_f32_16x16x32_bf16 v[108:111], v[150:153], v[206:209], v[108:111]
	v_mfma_f32_16x16x32_bf16 v[104:107], v[170:173], v[206:209], v[104:107]
	v_mfma_f32_16x16x32_bf16 v[92:95], v[150:153], v[214:217], v[92:95]
	v_mfma_f32_16x16x32_bf16 v[88:91], v[170:173], v[214:217], v[88:91]
	v_mfma_f32_16x16x32_bf16 v[76:79], v[150:153], v[222:225], v[76:79]
	v_mfma_f32_16x16x32_bf16 v[72:75], v[170:173], v[222:225], v[72:75]
	s_setprio 0
	s_setprio 3
	v_mfma_f32_16x16x32_bf16 v[116:119], v[174:177], v[190:193], v[116:119]
	v_mfma_f32_16x16x32_bf16 v[112:115], v[182:185], v[190:193], v[112:115]
	v_mfma_f32_16x16x32_bf16 v[100:103], v[174:177], v[198:201], v[100:103]
	v_mfma_f32_16x16x32_bf16 v[96:99], v[182:185], v[198:201], v[96:99]
	v_mfma_f32_16x16x32_bf16 v[84:87], v[174:177], v[210:213], v[84:87]
	v_mfma_f32_16x16x32_bf16 v[80:83], v[182:185], v[210:213], v[80:83]
	v_mfma_f32_16x16x32_bf16 v[68:71], v[174:177], v[218:221], v[68:71]
	v_mfma_f32_16x16x32_bf16 v[64:67], v[182:185], v[218:221], v[64:67]
	v_mfma_f32_16x16x32_bf16 v[116:119], v[178:181], v[194:197], v[116:119]
	v_mfma_f32_16x16x32_bf16 v[112:115], v[186:189], v[194:197], v[112:115]
	v_mfma_f32_16x16x32_bf16 v[100:103], v[178:181], v[206:209], v[100:103]
	v_mfma_f32_16x16x32_bf16 v[96:99], v[186:189], v[206:209], v[96:99]
	v_mfma_f32_16x16x32_bf16 v[84:87], v[178:181], v[214:217], v[84:87]
	v_mfma_f32_16x16x32_bf16 v[80:83], v[186:189], v[214:217], v[80:83]
	v_mfma_f32_16x16x32_bf16 v[68:71], v[178:181], v[222:225], v[68:71]
	v_mfma_f32_16x16x32_bf16 v[64:67], v[186:189], v[222:225], v[64:67]
	s_setprio 0
	s_barrier
; #define PG8_STAGE(bufoff, gbase, voff) do { _Pragma("unroll") for (int _i = 0; _i < 2; ++_i) \
;         __builtin_amdgcn_global_load_lds((const unsigned*)((const char*)(gbase) + (voff)[_i]), (LAS unsigned*)(lds + (bufoff) + ldsw + _i * 8192), 16, 0, 0); } while (0)
; #define PG8_LDA(dst, b, h) do { _Pragma("unroll") for (int m = 0; m < 4; ++m) _Pragma("unroll") for (int k = 0; k < 2; ++k) dst[m][k] = *(const LAS bf16x8*)(lds + PG8_SA(b, h) + aoff + m * 2048 + k * 1024); } while (0)
; #define PG8_MMA(ai, bj, At, Bt) do { __builtin_amdgcn_s_setprio(3); _Pragma("unroll") for (int m = 0; m < 4; ++m) _Pragma("unroll") for (int n = 0; n < 2; ++n) _Pragma("unroll") for (int k = 0; k < 2; ++k) \
;         acc[ai][bj][m][n] = __builtin_amdgcn_mfma_f32_16x16x32_bf16(Bt[n][k], At[m][k], acc[ai][bj][m][n], 0, 0, 0); __builtin_amdgcn_s_setprio(0); } while (0)
; #define PG8_WAIT_V(n) asm volatile("s_waitcnt vmcnt(" #n ")" ::: "memory")
; #define PG8_WAIT_L(n) asm volatile("s_waitcnt lgkmcnt(" #n ")" ::: "memory")
; #define PG8_BAR __builtin_amdgcn_s_barrier()
; #define PG8_SCHED __builtin_amdgcn_sched_barrier(0)
; template <class Epi, class Sched, bool ALIGN_EPI = false, bool SP2 = false>
; __device__ __forceinline__ void gemm_phase(LAS unsigned char* lds, const Gemm g, const Sched& S, const Epi& E) {
;     ...
;             PG8_LDA(At, 1, 1); PG8_STAGE(PG8_SB(1, 0), b3, voffB); PG8_STAGE(PG8_SB(1, 1), b3 + hsB, voffB); PG8_STAGE(PG8_SA(1, 0), a3, voffA);
;             PG8_WAIT_V(8); PG8_WAIT_L(0); PG8_BAR; PG8_MMA(1, 0, At, B0); PG8_MMA(1, 1, At, B1); PG8_BAR; PG8_SCHED;
	s_add_i32 s62, s92, s67
	v_lshl_add_u64 v[226:227], v[226:227], 0, s[46:47]
	s_mov_b32 m0, s62
	ds_read_b128 v[190:193], v160 offset:49152
	ds_read_b128 v[194:197], v250 offset:49152
	ds_read_b128 v[198:201], v160 offset:51200
	ds_read_b128 v[206:209], v250 offset:51200
	ds_read_b128 v[210:213], v160 offset:53248
	ds_read_b128 v[214:217], v250 offset:53248
	ds_read_b128 v[218:221], v160 offset:55296
	ds_read_b128 v[222:225], v250 offset:55296
	global_load_lds_dwordx4 v[226:227], off
	s_add_i32 m0, s62, 0x2000
	s_add_u32 s6, s6, 0x41080
	v_lshl_add_u64 v[226:227], v[228:229], 0, s[46:47]
	s_addc_u32 s7, s7, 0
	s_add_i32 s62, s93, s67
	global_load_lds_dwordx4 v[226:227], off
	v_lshl_add_u64 v[226:227], s[6:7], 0, v[134:135]
	s_mov_b32 m0, s62
	s_nop 0
	global_load_lds_dwordx4 v[226:227], off
	v_lshl_add_u64 v[226:227], s[6:7], 0, v[138:139]
	s_add_i32 m0, s62, 0x2000
	s_nop 0
	global_load_lds_dwordx4 v[226:227], off
	v_lshl_add_u64 v[226:227], v[230:231], 0, s[46:47]
	s_mov_b32 m0, s76
	s_nop 0
	global_load_lds_dwordx4 v[226:227], off
	v_lshl_add_u64 v[226:227], v[232:233], 0, s[46:47]
	s_mov_b32 m0, s77
	s_nop 0
	global_load_lds_dwordx4 v[226:227], off
	s_waitcnt vmcnt(8)
	s_waitcnt lgkmcnt(0)
	s_barrier
	s_setprio 3
	s_waitcnt lgkmcnt(0)
	v_mfma_f32_16x16x32_bf16 v[60:63], v[128:131], v[190:193], v[60:63]
	v_mfma_f32_16x16x32_bf16 v[56:59], v[166:169], v[190:193], v[56:59]
	v_mfma_f32_16x16x32_bf16 v[44:47], v[128:131], v[198:201], v[44:47]
	v_mfma_f32_16x16x32_bf16 v[40:43], v[166:169], v[198:201], v[40:43]
	v_mfma_f32_16x16x32_bf16 v[28:31], v[128:131], v[210:213], v[28:31]
	v_mfma_f32_16x16x32_bf16 v[24:27], v[166:169], v[210:213], v[24:27]
	v_mfma_f32_16x16x32_bf16 v[12:15], v[128:131], v[218:221], v[12:15]
	v_mfma_f32_16x16x32_bf16 v[8:11], v[166:169], v[218:221], v[8:11]
	v_mfma_f32_16x16x32_bf16 v[60:63], v[150:153], v[194:197], v[60:63]
	v_mfma_f32_16x16x32_bf16 v[56:59], v[170:173], v[194:197], v[56:59]
	v_mfma_f32_16x16x32_bf16 v[44:47], v[150:153], v[206:209], v[44:47]
	v_mfma_f32_16x16x32_bf16 v[40:43], v[170:173], v[206:209], v[40:43]
	v_mfma_f32_16x16x32_bf16 v[28:31], v[150:153], v[214:217], v[28:31]
	v_mfma_f32_16x16x32_bf16 v[24:27], v[170:173], v[214:217], v[24:27]
	v_mfma_f32_16x16x32_bf16 v[12:15], v[150:153], v[222:225], v[12:15]
	v_mfma_f32_16x16x32_bf16 v[8:11], v[170:173], v[222:225], v[8:11]
	s_setprio 0
	s_setprio 3
	v_mfma_f32_16x16x32_bf16 v[52:55], v[174:177], v[190:193], v[52:55]
	v_mfma_f32_16x16x32_bf16 v[48:51], v[182:185], v[190:193], v[48:51]
	v_mfma_f32_16x16x32_bf16 v[36:39], v[174:177], v[198:201], v[36:39]
	v_mfma_f32_16x16x32_bf16 v[32:35], v[182:185], v[198:201], v[32:35]
	v_mfma_f32_16x16x32_bf16 v[20:23], v[174:177], v[210:213], v[20:23]
	v_mfma_f32_16x16x32_bf16 v[16:19], v[182:185], v[210:213], v[16:19]
	v_mfma_f32_16x16x32_bf16 v[4:7], v[174:177], v[218:221], v[4:7]
	v_mfma_f32_16x16x32_bf16 v[0:3], v[182:185], v[218:221], v[0:3]
	v_mfma_f32_16x16x32_bf16 v[52:55], v[178:181], v[194:197], v[52:55]
	v_mfma_f32_16x16x32_bf16 v[48:51], v[186:189], v[194:197], v[48:51]
	v_mfma_f32_16x16x32_bf16 v[36:39], v[178:181], v[206:209], v[36:39]
	v_mfma_f32_16x16x32_bf16 v[32:35], v[186:189], v[206:209], v[32:35]
	v_mfma_f32_16x16x32_bf16 v[20:23], v[178:181], v[214:217], v[20:23]
	v_mfma_f32_16x16x32_bf16 v[16:19], v[186:189], v[214:217], v[16:19]
	v_mfma_f32_16x16x32_bf16 v[4:7], v[178:181], v[222:225], v[4:7]
	v_mfma_f32_16x16x32_bf16 v[0:3], v[186:189], v[222:225], v[0:3]
	s_setprio 0
	s_barrier
	s_add_i32 s91, s91, 2
	s_add_u32 s4, s4, 0x100
	s_addc_u32 s5, s5, 0
	s_add_u32 s89, s89, 0x100
	s_addc_u32 s90, s90, 0
	s_cmp_gt_u32 s91, 61
	s_cbranch_scc0 .LBB0_64
	s_and_b64 vcc, exec, s[50:51]
	s_cbranch_vccz .LBB0_67
	s_barrier

; __device__ __forceinline__ unsigned cvt_pk_bf16(float lo, float hi) { unsigned r; asm volatile("v_cvt_pk_bf16_f32 %0, %1, %2" : "=v"(r) : "v"(lo), "v"(hi)); return r; }
; __device__ __forceinline__ float bf_lo(unsigned w) { return __uint_as_float(w << 16); }
; __device__ __forceinline__ float bf_hi(unsigned w) { return __uint_as_float(w & 0xffff0000u); }
; __device__ __forceinline__ void attn_stream(LAS unsigned char* lds, const MixArgs& A, ConvJob& J, int vcu, int G, int tid, int wid, int lane) {
;     ...
;             float ss = 0.f;
; #pragma unroll
;             for (int s = 0; s < 4; ++s) ss += sumsq8(qraw[s]);
;             ss += __shfl_xor(ss, 16); ss += __shfl_xor(ss, 32);
;             const float rn = (1.0f / sqrtf(ss * (1.0f / 128.0f) + EPS)) * 0.08838834764831845f;
; #pragma unroll
;             for (int s = 0; s < 4; ++s) {
;                 const f32x4 g0 = *(const f32x4*)(A.qg + 32 * s + 8 * fq) * *(const f32x4*)(A.kg + 32 * s + 8 * fq), g1 = *(const f32x4*)(A.qg + 32 * s + 8 * fq + 4) * *(const f32x4*)(A.kg + 32 * s + 8 * fq + 4);
;                 const u32x4 w = qraw[s]; u32x4 o;
;                 o.x = cvt_pk_bf16(bf_lo(w.x) * rn * g0[0], bf_hi(w.x) * rn * g0[1]); o.y = cvt_pk_bf16(bf_lo(w.y) * rn * g0[2], bf_hi(w.y) * rn * g0[3]);
;                 o.z = cvt_pk_bf16(bf_lo(w.z) * rn * g1[0], bf_hi(w.z) * rn * g1[1]); o.w = cvt_pk_bf16(bf_lo(w.w) * rn * g1[2], bf_hi(w.w) * rn * g1[3]);
;                 qf[s] = __builtin_bit_cast(bf16x8, o); }
;             sinkv = A.sink[h]; mrun = sinkv; lpart = 0.f;
.LBB0_158:
	s_waitcnt vmcnt(3)
	v_and_b32_e32 v111, 0xffff0000, v13
	v_and_b32_e32 v110, 0xffff0000, v12
	v_lshlrev_b32_e32 v109, 16, v13
	v_lshlrev_b32_e32 v108, 16, v12
	v_pk_mul_f32 v[80:81], v[110:111], v[110:111]
	v_and_b32_e32 v115, 0xffff0000, v15
	v_and_b32_e32 v114, 0xffff0000, v14
	v_pk_fma_f32 v[80:81], v[108:109], v[108:109], v[80:81]
	v_lshlrev_b32_e32 v113, 16, v15
	v_lshlrev_b32_e32 v112, 16, v14
	v_pk_mul_f32 v[82:83], v[114:115], v[114:115]
	v_add_f32_e32 v80, v80, v81
	v_pk_fma_f32 v[82:83], v[112:113], v[112:113], v[82:83]
	s_waitcnt vmcnt(2)
	v_and_b32_e32 v121, 0xffff0000, v17
	v_add_f32_e32 v80, v82, v80
	v_and_b32_e32 v120, 0xffff0000, v16
	v_pk_add_f32 v[116:117], v[82:83], v[80:81] op_sel_hi:[1,0]
	v_lshlrev_b32_e32 v119, 16, v17
	v_lshlrev_b32_e32 v118, 16, v16
	v_pk_mul_f32 v[80:81], v[120:121], v[120:121]
	v_and_b32_e32 v125, 0xffff0000, v19
	v_and_b32_e32 v124, 0xffff0000, v18
	v_pk_fma_f32 v[80:81], v[118:119], v[118:119], v[80:81]
	v_lshlrev_b32_e32 v123, 16, v19
	v_lshlrev_b32_e32 v122, 16, v18
	v_pk_mul_f32 v[82:83], v[124:125], v[124:125]
	v_add_f32_e32 v80, v80, v81
	v_pk_fma_f32 v[82:83], v[122:123], v[122:123], v[82:83]
	s_waitcnt vmcnt(1)
	v_lshlrev_b32_e32 v88, 16, v24
	v_add_f32_e32 v80, v82, v80
	v_pk_add_f32 v[126:127], v[82:83], v[80:81] op_sel_hi:[1,0]
	v_and_b32_e32 v89, 0xffff0000, v24
	v_mul_f32_e32 v80, v88, v88
	v_pk_fma_f32 v[128:129], v[88:89], v[88:89], v[80:81] op_sel_hi:[1,1,0]
	global_load_dwordx4 v[80:83], v[162:163], off offset:16
	global_load_dwordx4 v[84:87], v[162:163], off
	global_load_dwordx4 v[100:103], v[164:165], off offset:16
	global_load_dwordx4 v[104:107], v[164:165], off
	v_lshlrev_b32_e32 v90, 16, v25
	v_and_b32_e32 v91, 0xffff0000, v25
	v_mul_f32_e32 v92, v90, v90
	s_waitcnt lgkmcnt(0)
	v_pk_fma_f32 v[130:131], v[90:91], v[90:91], v[92:93] op_sel_hi:[1,1,0]
	s_waitcnt vmcnt(4)
	v_lshlrev_b32_e32 v134, 16, v33
	v_and_b32_e32 v135, 0xffff0000, v33
	v_and_b32_e32 v97, 0xffff0000, v26
	v_and_b32_e32 v96, 0xffff0000, v32
	v_mul_f32_e32 v128, v134, v134
	v_mul_f32_e32 v130, v135, v135
	v_lshlrev_b32_e32 v95, 16, v26
	v_lshlrev_b32_e32 v94, 16, v32
	v_and_b32_e32 v99, 0xffff0000, v27
	v_and_b32_e32 v98, 0xffff0000, v34
	v_pk_mul_f32 v[132:133], v[96:97], v[96:97]
	v_lshlrev_b32_e32 v136, 16, v35
	v_and_b32_e32 v137, 0xffff0000, v35
	v_lshlrev_b32_e32 v93, 16, v27
	v_lshlrev_b32_e32 v92, 16, v34
	v_pk_fma_f32 v[132:133], v[94:95], v[94:95], v[132:133]
	v_pk_add_f32 v[128:129], v[128:129], v[130:131]
	v_pk_mul_f32 v[130:131], v[98:99], v[98:99]
	v_mul_f32_e32 v126, v136, v136
	v_mul_f32_e32 v116, v137, v137
	v_pk_add_f32 v[128:129], v[132:133], v[128:129]
	v_pk_fma_f32 v[130:131], v[92:93], v[92:93], v[130:131]
	v_pk_add_f32 v[116:117], v[126:127], v[116:117]
	v_pk_add_f32 v[128:129], v[130:131], v[128:129]
	s_waitcnt vmcnt(1)
	v_pk_mul_f32 v[102:103], v[82:83], v[102:103]
	v_pk_add_f32 v[116:117], v[128:129], v[116:117]
	s_waitcnt vmcnt(0)
	v_pk_mul_f32 v[84:85], v[84:85], v[104:105]
	v_add_f32_e32 v116, v116, v117
	ds_bpermute_b32 v117, v218, v116
	v_pk_mul_f32 v[82:83], v[80:81], v[100:101]
	v_pk_mul_f32 v[86:87], v[86:87], v[106:107]
	s_waitcnt lgkmcnt(0)
	v_add_f32_e32 v116, v116, v117
	ds_bpermute_b32 v117, v219, v116
	s_waitcnt lgkmcnt(0)
	v_add_f32_e32 v116, v116, v117
	v_fmamk_f32 v116, v116, 0x3c000000, v233
	v_mul_f32_e32 v117, 0x4f800000, v116
	v_cmp_gt_f32_e32 vcc, s43, v116
	s_nop 1
	v_cndmask_b32_e32 v116, v116, v117, vcc
	v_sqrt_f32_e32 v117, v116
	s_nop 0
	v_add_u32_e32 v126, -1, v117
	v_fma_f32 v127, -v126, v117, v116
	v_cmp_ge_f32_e64 s[10:11], 0, v127
	v_add_u32_e32 v127, 1, v117
	s_nop 0
	v_cndmask_b32_e64 v126, v117, v126, s[10:11]
	v_fma_f32 v117, -v127, v117, v116
	v_cmp_lt_f32_e64 s[10:11], 0, v117
	s_nop 1
	v_cndmask_b32_e64 v117, v126, v127, s[10:11]
	v_mul_f32_e32 v126, 0x37800000, v117
	v_cndmask_b32_e32 v117, v117, v126, vcc
	v_cmp_class_f32_e32 vcc, v116, v234
	s_nop 1
	v_cndmask_b32_e32 v116, v117, v116, vcc
	v_div_scale_f32 v117, s[10:11], v116, v116, 1.0
	v_rcp_f32_e32 v126, v117
	s_lshl_b64 s[10:11], s[58:59], 2
	s_add_u32 s10, s48, s10
	s_addc_u32 s11, s49, s11
	v_fma_f32 v127, -v117, v126, 1.0
	v_fmac_f32_e32 v126, v127, v126
	v_div_scale_f32 v127, vcc, 1.0, v116, 1.0
	v_mul_f32_e32 v128, v127, v126
	v_fma_f32 v129, -v117, v128, v127
	v_fmac_f32_e32 v128, v129, v126
	v_fma_f32 v117, -v117, v128, v127
	v_div_fmas_f32 v117, v117, v126, v128
	v_div_fixup_f32 v116, v117, v116, 1.0
	v_mul_f32_e32 v116, 0x3db504f3, v116
	v_mul_f32_e32 v80, v116, v108
	v_mul_f32_e32 v81, v116, v110
	v_mul_f32_e32 v80, v84, v80
	v_mul_f32_e32 v81, v85, v81
	v_cvt_pk_bf16_f32 v80, v80, v81
	v_mul_f32_e32 v81, v116, v109
	v_mul_f32_e32 v84, v116, v111
	v_mul_f32_e32 v81, v86, v81
	v_mul_f32_e32 v84, v87, v84
	v_cvt_pk_bf16_f32 v81, v81, v84
	v_mul_f32_e32 v84, v116, v112
	v_mul_f32_e32 v82, v82, v84
	v_mul_f32_e32 v84, v116, v114
	v_mul_f32_e32 v83, v83, v84
	v_cvt_pk_bf16_f32 v82, v82, v83
	v_mul_f32_e32 v83, v116, v113
	v_mul_f32_e32 v84, v116, v115
	v_mul_f32_e32 v83, v102, v83
	v_mul_f32_e32 v84, v103, v84
	v_cvt_pk_bf16_f32 v83, v83, v84
	global_load_dwordx4 v[84:87], v[164:165], off offset:128
	global_load_dwordx4 v[100:103], v[162:163], off offset:128
	global_load_dwordx4 v[104:107], v[162:163], off offset:144
	global_load_dwordx4 v[108:111], v[164:165], off offset:144
	v_mul_f32_e32 v112, v116, v118
	v_mul_f32_e32 v113, v116, v120
	v_mul_f32_e32 v114, v116, v119
	v_mul_f32_e32 v115, v116, v121
	v_mul_f32_e32 v117, v116, v122
	v_mul_f32_e32 v118, v116, v124
	v_mul_f32_e32 v119, v116, v123
	v_mul_f32_e32 v120, v116, v125
	v_mul_f32_e32 v95, v116, v95
	v_mul_f32_e32 v97, v116, v97
	v_mul_f32_e32 v93, v116, v93
	v_mul_f32_e32 v99, v116, v99
	v_mul_f32_e32 v121, v116, v92
	v_mul_f32_e32 v122, v116, v98
	v_mul_f32_e32 v123, v116, v136
	s_waitcnt vmcnt(2)
; __device__ __forceinline__ unsigned cvt_pk_bf16(float lo, float hi) { unsigned r; asm volatile("v_cvt_pk_bf16_f32 %0, %1, %2" : "=v"(r) : "v"(lo), "v"(hi)); return r; }
; __device__ __forceinline__ float bf_lo(unsigned w) { return __uint_as_float(w << 16); }
; __device__ __forceinline__ float bf_hi(unsigned w) { return __uint_as_float(w & 0xffff0000u); }
; __device__ __forceinline__ void attn_stream(LAS unsigned char* lds, const MixArgs& A, ConvJob& J, int vcu, int G, int tid, int wid, int lane) {
;     ...
;             for (int s = 0; s < 4; ++s) {
;                 const f32x4 g0 = *(const f32x4*)(A.qg + 32 * s + 8 * fq) * *(const f32x4*)(A.kg + 32 * s + 8 * fq), g1 = *(const f32x4*)(A.qg + 32 * s + 8 * fq + 4) * *(const f32x4*)(A.kg + 32 * s + 8 * fq + 4);
;                 const u32x4 w = qraw[s]; u32x4 o;
;                 o.x = cvt_pk_bf16(bf_lo(w.x) * rn * g0[0], bf_hi(w.x) * rn * g0[1]); o.y = cvt_pk_bf16(bf_lo(w.y) * rn * g0[2], bf_hi(w.y) * rn * g0[3]);
;                 o.z = cvt_pk_bf16(bf_lo(w.z) * rn * g1[0], bf_hi(w.z) * rn * g1[1]); o.w = cvt_pk_bf16(bf_lo(w.w) * rn * g1[2], bf_hi(w.w) * rn * g1[3]);
;                 qf[s] = __builtin_bit_cast(bf16x8, o); }
;             sinkv = A.sink[h]; mrun = sinkv; lpart = 0.f;
; #pragma unroll
;             for (int c = 0; c < 8; ++c) oacc[c] = (f32x4){0.f, 0.f, 0.f, 0.f};
	v_pk_mul_f32 v[86:87], v[102:103], v[86:87]
	v_pk_mul_f32 v[84:85], v[100:101], v[84:85]
	s_waitcnt vmcnt(0)
	v_pk_mul_f32 v[100:101], v[106:107], v[110:111]
	v_pk_mul_f32 v[102:103], v[104:105], v[108:109]
	v_mul_f32_e32 v84, v112, v84
	v_mul_f32_e32 v85, v113, v85
	v_mul_f32_e32 v86, v114, v86
	v_mul_f32_e32 v87, v115, v87
	v_mul_f32_e32 v102, v117, v102
	v_mul_f32_e32 v103, v118, v103
	v_mul_f32_e32 v100, v119, v100
	v_mul_f32_e32 v101, v120, v101
	v_cvt_pk_bf16_f32 v84, v84, v85
	v_cvt_pk_bf16_f32 v85, v86, v87
	v_cvt_pk_bf16_f32 v86, v102, v103
	v_cvt_pk_bf16_f32 v87, v100, v101
	global_load_dwordx4 v[100:103], v[164:165], off offset:256
	global_load_dwordx4 v[104:107], v[162:163], off offset:256
	global_load_dwordx4 v[108:111], v[162:163], off offset:272
	global_load_dwordx4 v[112:115], v[164:165], off offset:272
	v_mul_f32_e32 v117, v116, v88
	v_mul_f32_e32 v118, v116, v89
	v_mul_f32_e32 v119, v116, v90
	v_mul_f32_e32 v120, v116, v91
	s_waitcnt vmcnt(2)
	v_pk_mul_f32 v[88:89], v[106:107], v[102:103]
	v_pk_mul_f32 v[90:91], v[104:105], v[100:101]
	s_waitcnt vmcnt(0)
	v_pk_mul_f32 v[100:101], v[110:111], v[114:115]
	v_pk_mul_f32 v[102:103], v[108:109], v[112:113]
	v_mul_f32_e32 v90, v117, v90
	v_mul_f32_e32 v91, v118, v91
	v_mul_f32_e32 v104, v119, v88
	v_mul_f32_e32 v89, v120, v89
	v_mul_f32_e32 v95, v95, v102
	v_mul_f32_e32 v97, v97, v103
	v_mul_f32_e32 v93, v93, v100
	v_mul_f32_e32 v99, v99, v101
	v_cvt_pk_bf16_f32 v88, v90, v91
	v_cvt_pk_bf16_f32 v89, v104, v89
	v_cvt_pk_bf16_f32 v90, v95, v97
	v_cvt_pk_bf16_f32 v91, v93, v99
	global_load_dwordx4 v[100:103], v[164:165], off offset:384
	global_load_dwordx4 v[104:107], v[162:163], off offset:384
	global_load_dwordx4 v[108:111], v[162:163], off offset:400
	global_load_dwordx4 v[112:115], v[164:165], off offset:400
	v_mul_f32_e32 v117, v116, v94
	v_mul_f32_e32 v118, v116, v96
	v_mul_f32_e32 v120, v116, v135
	v_mul_f32_e32 v119, v116, v134
	v_mul_f32_e32 v116, v116, v137
	s_waitcnt vmcnt(2)
	v_pk_mul_f32 v[92:93], v[106:107], v[102:103]
	v_pk_mul_f32 v[94:95], v[104:105], v[100:101]
	s_waitcnt vmcnt(0)
	v_pk_mul_f32 v[96:97], v[110:111], v[114:115]
	v_pk_mul_f32 v[98:99], v[108:109], v[112:113]
	v_mul_f32_e32 v94, v117, v94
	v_mul_f32_e32 v95, v118, v95
	v_mul_f32_e32 v93, v120, v93
	v_mul_f32_e32 v100, v119, v92
	v_mul_f32_e32 v98, v121, v98
	v_mul_f32_e32 v99, v122, v99
	v_mul_f32_e32 v96, v123, v96
	v_mul_f32_e32 v97, v116, v97
	v_cvt_pk_bf16_f32 v92, v94, v95
	v_cvt_pk_bf16_f32 v93, v100, v93
	v_cvt_pk_bf16_f32 v94, v98, v99
	v_cvt_pk_bf16_f32 v95, v96, v97
	global_load_dword v167, v157, s[10:11]
	v_mov_b32_e32 v99, 0
	v_mov_b32_e32 v98, v99
	v_mov_b32_e32 v97, v99
	v_mov_b32_e32 v96, v99
	v_mov_b32_e32 v103, v99
	v_mov_b32_e32 v102, v99
	v_mov_b32_e32 v101, v99
	v_mov_b32_e32 v100, v99
	v_mov_b32_e32 v107, v99
	v_mov_b32_e32 v106, v99
	v_mov_b32_e32 v105, v99
	v_mov_b32_e32 v104, v99
	v_mov_b32_e32 v111, v99
	v_mov_b32_e32 v110, v99
	v_mov_b32_e32 v109, v99
	v_mov_b32_e32 v108, v99
	v_mov_b32_e32 v115, v99
	v_mov_b32_e32 v114, v99
	v_mov_b32_e32 v113, v99
	v_mov_b32_e32 v112, v99
	v_mov_b32_e32 v119, v99
	v_mov_b32_e32 v118, v99
	v_mov_b32_e32 v117, v99
	v_mov_b32_e32 v116, v99
	v_mov_b32_e32 v123, v99
	v_mov_b32_e32 v122, v99
	v_mov_b32_e32 v121, v99
	v_mov_b32_e32 v120, v99
	v_mov_b32_e32 v127, v99
	v_mov_b32_e32 v126, v99
	v_mov_b32_e32 v125, v99
	v_mov_b32_e32 v124, v99
	v_mov_b32_e32 v236, v99
	s_waitcnt vmcnt(0)
	v_mov_b32_e32 v235, v167

; #define ATT_LOADKV(b_, blk_, kb_, h_) do { const bf16_t* kp_ = A.Z + ((size_t)(b_) * SEQ + (size_t)((blk_) - 1 + (kb_)) * 128 + skey) * INW + O_K + ((h_) >> 2) * 128 + 8 * spart; \
;         _Pragma("unroll") for (int i = 0; i < 4; ++i) { kr[i] = *(const u32x4*)(kp_ + 32 * i); vr[i] = *(const u32x4*)(kp_ + (O_V - O_K) + 32 * i); } } while (0)
; #define ATT_LOADQ(b_, blk_, h_) do { const bf16_t* qp_ = A.Z + ((size_t)(b_) * SEQ + (size_t)(blk_) * 128 + arow) * INW + (h_) * 128 + 8 * fq; \
;         _Pragma("unroll") for (int s = 0; s < 4; ++s) qraw[s] = *(const u32x4*)(qp_ + 32 * s); } while (0)
; __device__ __forceinline__ void conv_load(const ConvJob& J, int idx, f32x4 (&v)[8], int lane) {
;     const bool second = idx >= 32768; const int r = idx & 32767;
;     const float* W = second ? J.w2 : J.w1; const int N = second ? D : FF, nb = second ? 128 : 512;
;     const int k0 = 64 * (r / nb), n0 = 32 * (r % nb);
;     const float* p = W + (size_t)(k0 + 8 * (lane >> 3)) * N + n0 + 4 * (lane & 7);
; #pragma unroll
;     for (int i = 0; i < 8; ++i) v[i] = __builtin_nontemporal_load((const f32x4*)(p + (size_t)i * N));
; __device__ __forceinline__ void attn_stream(LAS unsigned char* lds, const MixArgs& A, ConvJob& J, int vcu, int G, int tid, int wid, int lane) {
;     ...
;         int nkb = kb + 1, nu = u, nh = h, nb_ = b, nblk = blk, nkhi = khi; bool nfirst = false, nvalid = true;
;         if (nkb > khi) { nu = u + G; nfirst = true;
;             if (nu < NU) { nh = nu & 15; const int nbb = nu >> 4; nb_ = nbb / NBLK; nblk = nbb % NBLK; nkb = (nblk == 0) ? 1 : 0; nkhi = (nblk == NBLK - 1) ? 1 : 2; } else nvalid = false; }
;         const bool last = (kb == khi);
;         if (nvalid) { ATT_LOADKV(nb_, nblk, nkb, nh); if (nfirst) ATT_LOADQ(nb_, nblk, nh); }
;         f32x4 cv[8]; const int cidx = J.next; const bool cdo = cidx < CONV_BLOCKS;
;         if (cdo) conv_load(J, cidx, cv, lane);
.LBB0_163:
	s_xor_b64 s[70:71], s[10:11], -1
	s_and_b64 vcc, exec, s[70:71]
	s_cbranch_vccnz .LBB0_166
	s_ashr_i32 s67, s66, 31
	s_lshl_b64 s[72:73], s[66:67], 12
	s_add_i32 s67, s90, s68
	s_add_i32 s94, s67, -1
	s_ashr_i32 s95, s94, 31
	s_lshl_b64 s[94:95], s[94:95], 7
	s_waitcnt vmcnt(7)
	v_mov_b32_e32 v1, s73
	v_or_b32_e32 v0, s72, v148
	v_lshl_add_u64 v[0:1], v[0:1], 0, s[94:95]
	v_mov_b64_e32 v[2:3], s[18:19]
	v_mad_u64_u32 v[2:3], s[94:95], v0, s83, v[2:3]
	s_lshl_b32 s67, s91, 6
	v_mad_i32_i24 v3, v1, s83, v3
	s_and_b32 s94, s67, 0x300
	s_mov_b32 s95, s59
	v_lshl_add_u64 v[0:1], v[2:3], 0, s[94:95]
	v_lshl_add_u64 v[0:1], v[0:1], 0, v[156:157]
	s_waitcnt vmcnt(1)
	v_add_co_u32_e32 v4, vcc, 0x1000, v0
	s_waitcnt vmcnt(0)
	v_lshl_add_u64 v[44:45], v[0:1], 0, s[60:61]
	v_addc_co_u32_e32 v5, vcc, 0, v1, vcc
	global_load_dwordx4 v[0:3], v[44:45], off offset:64
	global_load_dwordx4 v[8:11], v[44:45], off offset:128
	global_load_dwordx4 v[36:39], v[44:45], off offset:1088
	global_load_dwordx4 v[40:43], v[44:45], off offset:1152
	global_load_dwordx4 v[20:23], v[44:45], off offset:1024
	global_load_dwordx4 v[28:31], v[44:45], off offset:192
	s_nop 0
	global_load_dwordx4 v[4:7], v[4:5], off
	s_nop 0
	global_load_dwordx4 v[44:47], v[44:45], off offset:1216
	s_andn2_b64 vcc, exec, s[44:45]
	s_cbranch_vccnz .LBB0_166
	s_ashr_i32 s69, s68, 31
	s_lshl_b64 s[94:95], s[68:69], 7
	s_add_u32 s72, s94, s72
	s_addc_u32 s73, s95, s73
	v_lshl_add_u64 v[12:13], s[72:73], 0, v[150:151]
	v_mov_b64_e32 v[14:15], s[18:19]
	v_mad_u64_u32 v[14:15], s[72:73], v12, s83, v[14:15]
	v_mad_i32_i24 v15, v13, s83, v15
	s_lshl_b32 s72, s91, 8
	s_mov_b32 s73, s59
	v_lshl_add_u64 v[12:13], v[14:15], 0, s[72:73]
	v_lshlrev_b32_e32 v14, 1, v153
	v_mov_b32_e32 v15, v157
	v_lshl_add_u64 v[32:33], v[12:13], 0, v[14:15]
	global_load_dwordx4 v[12:15], v[32:33], off
	global_load_dwordx4 v[16:19], v[32:33], off offset:64
	global_load_dwordx4 v[24:27], v[32:33], off offset:128
	s_nop 0
	global_load_dwordx4 v[32:35], v[32:33], off offset:192
.LBB0_166:
	s_cmp_lt_i32 s81, 0x10000
	s_cselect_b64 s[72:73], -1, 0
	s_cmp_gt_i32 s81, 0xffff
	s_cbranch_scc1 .LBB0_168
	s_and_b32 s67, s81, 0x7fff
	s_cmpk_gt_i32 s81, 0x7fff
	s_cselect_b32 s69, s27, s25
	s_cselect_b32 s93, s26, s24
	s_waitcnt vmcnt(7)
	v_mov_b32_e32 v49, s69
	s_cselect_b32 s69, 7, 9
	v_mov_b32_e32 v48, s93
	s_cselect_b32 s93, s85, 0x1ff
	s_cselect_b32 s96, 12, 14
	s_lshr_b32 s67, s67, s69
	v_lshl_or_b32 v50, s67, 6, v158
	v_mov_b32_e32 v51, v157
	s_and_b32 s67, s93, s81
	v_lshlrev_b64 v[50:51], s96, v[50:51]
	v_lshl_add_u64 v[48:49], v[50:51], 2, v[48:49]
	s_lshl_b32 s94, s67, 7
	s_mov_b32 s95, s59
	v_lshl_add_u64 v[48:49], v[48:49], 0, s[94:95]
	v_lshlrev_b32_e32 v50, 2, v160
	v_mov_b32_e32 v51, v157
	s_waitcnt vmcnt(1)
	v_lshl_add_u64 v[72:73], v[48:49], 0, v[50:51]
	s_lshl_b64 s[94:95], 1, s96
	v_lshl_add_u64 v[52:53], s[94:95], 2, v[72:73]
	s_lshl_b64 s[94:95], 2, s96
	v_lshl_add_u64 v[56:57], s[94:95], 2, v[72:73]
	s_lshl_b64 s[94:95], 3, s96
	v_lshl_add_u64 v[60:61], s[94:95], 2, v[72:73]
	s_lshl_b64 s[94:95], 4, s96
	v_lshl_add_u64 v[64:65], s[94:95], 2, v[72:73]
	s_lshl_b64 s[94:95], 5, s96
	v_lshl_add_u64 v[68:69], s[94:95], 2, v[72:73]
	s_lshl_b64 s[94:95], 6, s96
	v_lshl_add_u64 v[74:75], s[94:95], 2, v[72:73]
	s_lshl_b64 s[94:95], 7, s96
	s_waitcnt vmcnt(0)
	v_lshl_add_u64 v[76:77], s[94:95], 2, v[72:73]
	global_load_dwordx4 v[48:51], v[72:73], off nt
	s_nop 0
	global_load_dwordx4 v[52:55], v[52:53], off nt
	s_nop 0
	global_load_dwordx4 v[56:59], v[56:57], off nt
	s_nop 0
	global_load_dwordx4 v[60:63], v[60:61], off nt
	s_nop 0
	global_load_dwordx4 v[64:67], v[64:65], off nt
	s_nop 0
	global_load_dwordx4 v[68:71], v[68:69], off nt
	s_nop 0
	global_load_dwordx4 v[72:75], v[74:75], off nt
	s_nop 0
	global_load_dwordx4 v[76:79], v[76:77], off nt

; __device__ __forceinline__ void attn_stream(LAS unsigned char* lds, const MixArgs& A, ConvJob& J, int vcu, int G, int tid, int wid, int lane) {
;     ...
;         if (nvalid) {
;             ATT_WRITEKV(buf ^ 1);
.LBB0_175:
	s_waitcnt vmcnt(1)
	v_and_b32_e32 v129, 0xffff0000, v4
	v_lshlrev_b32_e32 v128, 16, v4
	s_waitcnt lgkmcnt(0)
	v_and_b32_e32 v131, 0xffff0000, v5
	v_mul_f32_e32 v129, v129, v129
	v_lshlrev_b32_e32 v130, 16, v5
	v_fmac_f32_e32 v129, v128, v128
	v_mul_f32_e32 v128, v131, v131
	v_and_b32_e32 v133, 0xffff0000, v6
	v_fmac_f32_e32 v128, v130, v130
	v_lshlrev_b32_e32 v132, 16, v6
	v_add_f32_e32 v128, v129, v128
	v_mul_f32_e32 v129, v133, v133
	v_and_b32_e32 v135, 0xffff0000, v7
	v_fmac_f32_e32 v129, v132, v132
	v_lshlrev_b32_e32 v134, 16, v7
	v_add_f32_e32 v128, v129, v128
	v_mul_f32_e32 v129, v135, v135
	v_fmac_f32_e32 v129, v134, v134
	v_and_b32_e32 v130, 0xffff0000, v0
	v_add_f32_e32 v128, v129, v128
	v_lshlrev_b32_e32 v129, 16, v0
	v_and_b32_e32 v132, 0xffff0000, v1
	v_mul_f32_e32 v130, v130, v130
	v_lshlrev_b32_e32 v131, 16, v1
	v_fmac_f32_e32 v130, v129, v129
	v_mul_f32_e32 v129, v132, v132
	v_and_b32_e32 v134, 0xffff0000, v2
	v_fmac_f32_e32 v129, v131, v131
	v_lshlrev_b32_e32 v133, 16, v2
	v_add_f32_e32 v129, v130, v129
	v_mul_f32_e32 v130, v134, v134
	v_and_b32_e32 v136, 0xffff0000, v3
	v_fmac_f32_e32 v130, v133, v133
	v_lshlrev_b32_e32 v135, 16, v3
	v_add_f32_e32 v129, v130, v129
	v_mul_f32_e32 v130, v136, v136
	v_fmac_f32_e32 v130, v135, v135
	v_add_f32_e32 v129, v130, v129
	v_and_b32_e32 v130, 0xffff0000, v8
	v_add_f32_e32 v128, v128, v129
	v_lshlrev_b32_e32 v129, 16, v8
	v_and_b32_e32 v132, 0xffff0000, v9
	v_mul_f32_e32 v130, v130, v130
	v_lshlrev_b32_e32 v131, 16, v9
	v_fmac_f32_e32 v130, v129, v129
	v_mul_f32_e32 v129, v132, v132
	v_and_b32_e32 v134, 0xffff0000, v10
	v_fmac_f32_e32 v129, v131, v131
	v_lshlrev_b32_e32 v133, 16, v10
	v_add_f32_e32 v129, v130, v129
	v_mul_f32_e32 v130, v134, v134
	v_and_b32_e32 v136, 0xffff0000, v11
	v_fmac_f32_e32 v130, v133, v133
	v_lshlrev_b32_e32 v135, 16, v11
	v_add_f32_e32 v129, v130, v129
	v_mul_f32_e32 v130, v136, v136
	v_fmac_f32_e32 v130, v135, v135
	v_add_f32_e32 v129, v130, v129
	v_and_b32_e32 v130, 0xffff0000, v28
	v_add_f32_e32 v128, v128, v129
	v_lshlrev_b32_e32 v129, 16, v28
	v_and_b32_e32 v132, 0xffff0000, v29
	v_mul_f32_e32 v130, v130, v130
	v_lshlrev_b32_e32 v131, 16, v29
	v_fmac_f32_e32 v130, v129, v129
	v_mul_f32_e32 v129, v132, v132
	v_and_b32_e32 v134, 0xffff0000, v30
	v_fmac_f32_e32 v129, v131, v131
	v_lshlrev_b32_e32 v133, 16, v30
	v_add_f32_e32 v129, v130, v129
	v_mul_f32_e32 v130, v134, v134
	v_and_b32_e32 v136, 0xffff0000, v31
	v_fmac_f32_e32 v130, v133, v133
	v_lshlrev_b32_e32 v135, 16, v31
	v_add_f32_e32 v129, v130, v129
	v_mul_f32_e32 v130, v136, v136
	v_fmac_f32_e32 v130, v135, v135
	v_add_f32_e32 v129, v130, v129
	v_add_f32_e32 v128, v128, v129
	ds_bpermute_b32 v129, v149, v128
	s_waitcnt lgkmcnt(0)
	v_add_f32_e32 v128, v128, v129
	ds_bpermute_b32 v129, v161, v128
	s_and_saveexec_b64 s[62:63], s[0:1]
	s_cbranch_execz .LBB0_177
	s_waitcnt lgkmcnt(0)
	v_add_f32_e32 v128, v128, v129
	v_fmamk_f32 v128, v128, 0x3c000000, v233
	v_mul_f32_e32 v129, 0x4f800000, v128
	v_cmp_gt_f32_e32 vcc, s43, v128
	s_nop 1
	v_cndmask_b32_e32 v128, v128, v129, vcc
	v_sqrt_f32_e32 v129, v128
	s_nop 0
	v_add_u32_e32 v130, -1, v129
	v_fma_f32 v132, -v130, v129, v128
	v_add_u32_e32 v131, 1, v129
	v_cmp_ge_f32_e64 s[10:11], 0, v132
	s_nop 1
	v_cndmask_b32_e64 v130, v129, v130, s[10:11]
	v_fma_f32 v129, -v131, v129, v128
	v_cmp_lt_f32_e64 s[10:11], 0, v129
	s_nop 1
	v_cndmask_b32_e64 v129, v130, v131, s[10:11]
	v_mul_f32_e32 v130, 0x37800000, v129
	v_cndmask_b32_e32 v129, v129, v130, vcc
	v_cmp_class_f32_e32 vcc, v128, v234
	s_nop 1
	v_cndmask_b32_e32 v128, v129, v128, vcc
	v_div_scale_f32 v129, s[10:11], v128, v128, 1.0
	v_rcp_f32_e32 v130, v129
	s_lshl_b32 s10, s88, 9
	s_xor_b32 s10, s10, 0x200
	v_fma_f32 v131, -v129, v130, 1.0
	v_fmac_f32_e32 v130, v131, v130
	v_div_scale_f32 v131, vcc, 1.0, v128, 1.0
	v_mul_f32_e32 v132, v131, v130
	v_fma_f32 v133, -v129, v132, v131
	v_fmac_f32_e32 v132, v133, v130
	v_fma_f32 v129, -v129, v132, v131
	v_div_fmas_f32 v129, v129, v130, v132
	v_div_fixup_f32 v128, v129, v128, 1.0
	v_add_u32_e32 v129, s10, v215
	ds_write_b32 v129, v128
.LBB0_177:
	s_or_b64 exec, exec, s[62:63]
	s_xor_b32 s10, s88, 1
	s_mul_i32 s10, s10, 0x10800
	s_add_i32 s10, s10, 0
	v_add_u32_e32 v128, s10, v205
	s_waitcnt lgkmcnt(0)
	v_add_u32_e32 v129, s10, v206
	v_add_u32_e32 v130, v128, v152
	ds_write_b128 v130, v[4:7]
	v_add_u32_e32 v130, v129, v207
	ds_write_b128 v130, v[20:23] offset:34816
	v_add_u32_e32 v130, v128, v208
	ds_write_b128 v130, v[0:3]
	v_add_u32_e32 v130, v129, v209
	ds_write_b128 v130, v[36:39] offset:34816
	v_add_u32_e32 v130, v128, v210
	ds_write_b128 v130, v[8:11]
	v_add_u32_e32 v130, v129, v211
	v_add_u32_e32 v128, v128, v212
	ds_write_b128 v130, v[40:43] offset:34816
	ds_write_b128 v128, v[28:31]
	v_add_u32_e32 v128, v129, v213
	s_waitcnt vmcnt(0)
	ds_write_b128 v128, v[44:47] offset:34816
	s_andn2_b64 vcc, exec, s[72:73]
	s_cbranch_vccnz .LBB0_171

; #define GM_LOADV(bb_, hh_) do { const size_t t_ = (size_t)(bb_) * 128 + skey; const bf16_t* vp_ = A.Z + t_ * INW + O_G + (hh_) * 128 + 8 * spart; \
;         _Pragma("unroll") for (int i = 0; i < 4; ++i) vr[i] = *(const u32x4*)(vp_ + 32 * i); \
;         pa = *(const f32x4*)(A.VSS + t_ * 32 + 8 * spart); pb = *(const f32x4*)(A.VSS + t_ * 32 + 8 * spart + 4); } while (0)
; __device__ __forceinline__ void attn_stream(LAS unsigned char* lds, const MixArgs& A, ConvJob& J, int vcu, int G, int tid, int wid, int lane) {
;     ...
;         buf ^= 1; kb = nkb; u = nu; h = nh; b = nb_; blk = nblk; khi = nkhi; first = nfirst;
;     }
; __device__ __forceinline__ void gmlp_stream(LAS unsigned char* lds, const MixArgs& A, ConvJob& J, int vcu, int G, int tid, int wid, int lane) {
;     ...
;     if (vcu >= NU) return;
;     int u = vcu, hh = u & 15, bb = u >> 4;
;     u32x4 vr[4]; f32x4 pa, pb;
;     ...
;     GM_LOADV(bb, hh);
;     u32x2 uu[8];
;     { const bf16_t* up0 = A.Z + ((size_t)bb * 128 + trow) * INW + O_U + hh * 128 + 4 * fq;
; #pragma unroll
;       for (int c = 0; c < 8; ++c) uu[c] = *(const u32x2*)(up0 + 16 * c); }
;     __syncthreads();
;     GM_WRITEV(0, hh);
.LBB0_179:
	v_mov_b32_e32 v167, v169
	s_mov_b32 s65, s92
	s_mov_b32 s63, s90
	s_mov_b32 s62, s68
	s_mov_b32 s64, s66
	s_mov_b32 s58, s91
	s_andn2_b64 vcc, exec, s[44:45]
	s_cbranch_vccz .LBB0_152
	s_branch .LBB0_159
.LBB0_180:
	s_andn2_b64 vcc, exec, s[50:51]
	s_waitcnt vmcnt(0)
	v_and_b32_e32 v72, 56, v202
	s_cbranch_vccnz .LBB0_197
	s_ashr_i32 s48, s78, 4
	s_ashr_i32 s49, s48, 31
	v_mov_b32_e32 v153, 0
	s_lshl_b64 s[0:1], s[48:49], 7
	v_mov_b32_e32 v149, v153
	s_waitcnt lgkmcnt(0)
	v_lshl_add_u64 v[0:1], s[0:1], 0, v[148:149]
	s_movk_i32 s56, 0x3800
	v_mov_b64_e32 v[12:13], s[18:19]
	s_and_b32 s42, s78, 15
	v_mad_u64_u32 v[2:3], s[4:5], v0, s56, v[12:13]
	s_mov_b32 s7, 0
	v_mad_i32_i24 v3, v1, s56, v3
	s_lshl_b32 s6, s42, 8
	v_lshl_add_u64 v[2:3], v[2:3], 0, s[6:7]
	v_lshlrev_b64 v[0:1], 7, v[0:1]
	v_lshl_add_u64 v[14:15], v[2:3], 0, v[152:153]
	v_lshl_add_u64 v[0:1], s[40:41], 0, v[0:1]
	v_lshlrev_b32_e32 v152, 5, v159
	v_lshl_add_u64 v[0:1], v[0:1], 0, v[152:153]
	global_load_dwordx4 v[4:7], v[0:1], off
	s_nop 0
	global_load_dwordx4 v[0:3], v[0:1], off offset:16
	v_mov_b32_e32 v151, v153
	v_lshl_add_u64 v[18:19], s[0:1], 0, v[150:151]
	s_movk_i32 s57, 0x2000
	v_mad_u64_u32 v[12:13], s[0:1], v18, s56, v[12:13]
	v_and_b32_e32 v74, 12, v148
	v_add_co_u32_e32 v8, vcc, s57, v14
	v_mad_i32_i24 v13, v19, s56, v13
	v_lshlrev_b32_e32 v16, 1, v74
	v_mov_b32_e32 v17, v153
	v_addc_co_u32_e32 v9, vcc, 0, v15, vcc
	v_lshl_add_u64 v[12:13], v[12:13], 0, s[6:7]
	s_movk_i32 s58, 0x1000
	s_lshl_b32 s4, s42, 9
	global_load_dwordx4 v[8:11], v[8:9], off offset:2048
	v_lshl_add_u64 v[12:13], v[12:13], 0, v[16:17]
	s_mov_b64 s[8:9], 0x2800
	s_mov_b64 s[10:11], 0x1800
	s_add_u32 s4, s12, s4
	v_add_co_u32_e32 v26, vcc, s58, v12
	s_addc_u32 s5, s13, 0
	v_lshl_add_u64 v[20:21], v[14:15], 0, s[8:9]
	v_lshl_add_u64 v[24:25], v[12:13], 0, s[10:11]
	v_addc_co_u32_e32 v27, vcc, 0, v13, vcc
	global_load_dwordx4 v[12:15], v[20:21], off offset:64
	global_load_dwordx4 v[16:19], v[20:21], off offset:128
	s_nop 0
	global_load_dwordx4 v[20:23], v[20:21], off offset:192
	s_nop 0
	global_load_dwordx2 v[114:115], v[24:25], off offset:32
	global_load_dwordx2 v[112:113], v[24:25], off offset:64
	global_load_dwordx2 v[110:111], v[24:25], off offset:96
	global_load_dwordx2 v[108:109], v[24:25], off offset:128
	global_load_dwordx2 v[116:117], v[26:27], off offset:2048
	global_load_dwordx2 v[106:107], v[24:25], off offset:160
	global_load_dwordx2 v[104:105], v[24:25], off offset:192
	global_load_dwordx2 v[102:103], v[24:25], off offset:224
	s_barrier
	global_load_dwordx4 v[24:27], v152, s[4:5]
	global_load_dwordx4 v[28:31], v152, s[4:5] offset:16
	v_mbcnt_lo_u32_b32 v32, -1, 0
	v_mbcnt_hi_u32_b32 v41, -1, v32
	v_and_b32_e32 v33, 64, v41
	v_xor_b32_e32 v32, 1, v41
	v_add_u32_e32 v71, 64, v33
	v_cmp_lt_i32_e32 vcc, v32, v71
	v_mov_b32_e32 v87, 0x358637bd
	s_mov_b32 s59, 0xf800000
	v_cndmask_b32_e32 v32, v41, v32, vcc
	v_lshlrev_b32_e32 v73, 2, v32
	v_mov_b32_e32 v120, 0x260
	v_and_b32_e32 v96, 12, v202
	v_bfe_u32 v97, v202, 4, 2
	v_lshlrev_b32_e32 v76, 1, v154
	s_mov_b32 s60, -1
	s_movk_i32 s61, 0x7f
	s_mov_b64 s[44:45], 0x1000
	s_movk_i32 s62, 0x4040
	v_mov_b32_e32 v125, 0
	s_mov_b32 s63, 0
	v_mov_b32_e32 v56, v153
	v_mov_b32_e32 v57, v153
	v_mov_b32_e32 v58, v153
	v_mov_b32_e32 v59, v153
	v_mov_b32_e32 v60, v153
	v_mov_b32_e32 v61, v153
	v_mov_b32_e32 v62, v153
	v_mov_b32_e32 v63, v153
	v_mov_b32_e32 v64, v153
	v_mov_b32_e32 v65, v153
	v_mov_b32_e32 v66, v153
	v_mov_b32_e32 v67, v153
	v_mov_b32_e32 v68, v153
	v_mov_b32_e32 v69, v153
	v_mov_b32_e32 v70, v153
	s_waitcnt vmcnt(15)
	v_mov_b32_e32 v32, v4
	s_waitcnt vmcnt(14)
	v_mov_b32_e32 v33, v0
	v_mov_b32_e32 v34, v5
	v_mov_b32_e32 v35, v1
	v_mov_b32_e32 v36, v6
	v_mov_b32_e32 v37, v2
	v_mov_b32_e32 v38, v7
	v_mov_b32_e32 v39, v3
	v_pk_add_f32 v[32:33], v[32:33], v[34:35]
	v_pk_add_f32 v[34:35], v[36:37], v[38:39]
	s_waitcnt vmcnt(12)
	v_lshlrev_b32_e32 v40, 16, v13
	v_pk_add_f32 v[32:33], v[32:33], v[34:35]
	v_xor_b32_e32 v34, 2, v41
	v_add_f32_e32 v32, v32, v33
	ds_bpermute_b32 v33, v73, v32
	v_cmp_lt_i32_e32 vcc, v34, v71
	v_and_b32_e32 v42, 0xffff0000, v13
	v_lshlrev_b32_e32 v43, 16, v14
	v_cndmask_b32_e32 v34, v41, v34, vcc
	v_lshlrev_b32_e32 v75, 2, v34
	s_waitcnt lgkmcnt(0)
	v_add_f32_e32 v32, v32, v33
	ds_bpermute_b32 v33, v75, v32
	v_lshlrev_b32_e32 v34, 16, v8
	v_and_b32_e32 v44, 0xffff0000, v14
	v_lshlrev_b32_e32 v45, 16, v15
	v_and_b32_e32 v46, 0xffff0000, v15
	s_waitcnt lgkmcnt(0)
	v_add_f32_e32 v32, v32, v33
	v_fmamk_f32 v32, v32, 0x3a000000, v87
	v_mul_f32_e32 v33, 0x4f800000, v32
	v_cmp_gt_f32_e32 vcc, s59, v32
	s_waitcnt vmcnt(11)
	v_lshlrev_b32_e32 v50, 16, v17
	v_and_b32_e32 v51, 0xffff0000, v17
	v_cndmask_b32_e32 v32, v32, v33, vcc
	v_sqrt_f32_e32 v33, v32
	v_lshlrev_b32_e32 v52, 16, v18
	v_and_b32_e32 v53, 0xffff0000, v18
	v_lshlrev_b32_e32 v54, 16, v19
	v_add_u32_e32 v35, -1, v33
	v_add_u32_e32 v36, 1, v33
	v_fma_f32 v37, -v35, v33, v32
	v_fma_f32 v38, -v36, v33, v32
	v_cmp_ge_f32_e64 s[0:1], 0, v37
	v_and_b32_e32 v55, 0xffff0000, v19
	s_nop 0
	v_cndmask_b32_e64 v33, v33, v35, s[0:1]
	v_cmp_lt_f32_e64 s[0:1], 0, v38
	s_nop 1
	v_cndmask_b32_e64 v33, v33, v36, s[0:1]
	v_mul_f32_e32 v35, 0x37800000, v33
	v_cndmask_b32_e32 v33, v33, v35, vcc
	v_cmp_class_f32_e32 vcc, v32, v120
	v_and_b32_e32 v36, 0xffff0000, v8
	s_nop 0
	v_cndmask_b32_e32 v32, v33, v32, vcc
	v_div_scale_f32 v33, s[0:1], v32, v32, 1.0
	v_rcp_f32_e32 v35, v33
	v_div_scale_f32 v37, vcc, 1.0, v32, 1.0
	v_cmp_gt_u32_e64 s[0:1], 16, v155
	v_fma_f32 v38, -v33, v35, 1.0
	v_fmac_f32_e32 v35, v38, v35
	v_mul_f32_e32 v38, v37, v35
	v_fma_f32 v39, -v33, v38, v37
	v_fmac_f32_e32 v38, v39, v35
	v_fma_f32 v33, -v33, v38, v37
	v_div_fmas_f32 v33, v33, v35, v38
	v_div_fixup_f32 v77, v33, v32, 1.0
	v_mul_f32_e32 v32, v77, v34
	s_waitcnt vmcnt(1)
; __device__ __forceinline__ void gmlp_stream(LAS unsigned char* lds, const MixArgs& A, ConvJob& J, int vcu, int G, int tid, int wid, int lane) {
;     ...
;     int buf = 0, w_head = -1; bf16x8 wf[4]; float bsv = 0.f;
;     for (;;) {
;         if (hh != w_head) {
	v_mul_f32_e32 v24, v24, v32
	v_mul_f32_e32 v32, v77, v36
	v_mul_f32_e32 v25, v25, v32
	v_cvt_pk_bf16_f32 v24, v24, v25
	v_lshlrev_b32_e32 v25, 16, v9
	v_mul_f32_e32 v25, v77, v25
	v_mul_f32_e32 v25, v26, v25
	v_and_b32_e32 v26, 0xffff0000, v9
	v_mul_f32_e32 v26, v77, v26
	v_mul_f32_e32 v26, v27, v26
	v_cvt_pk_bf16_f32 v25, v25, v26
	v_lshlrev_b32_e32 v26, 16, v10
	v_and_b32_e32 v27, 0xffff0000, v10
	v_mul_f32_e32 v26, v77, v26
	v_mul_f32_e32 v27, v77, v27
	s_waitcnt vmcnt(0)
	v_mul_f32_e32 v26, v28, v26
	v_mul_f32_e32 v27, v29, v27
	v_cvt_pk_bf16_f32 v26, v26, v27
	v_lshlrev_b32_e32 v27, 16, v11
	v_and_b32_e32 v28, 0xffff0000, v11
	v_mul_f32_e32 v27, v77, v27
	v_mul_f32_e32 v28, v77, v28
	v_mul_f32_e32 v27, v30, v27
	v_mul_f32_e32 v28, v31, v28
	v_cvt_pk_bf16_f32 v27, v27, v28
	global_load_dwordx4 v[28:31], v152, s[4:5] offset:128
	global_load_dwordx4 v[32:35], v152, s[4:5] offset:144
	v_lshlrev_b32_e32 v38, 8, v148
	v_bitop3_b32 v36, v97, v159, v96 bitop3:0x36
	v_add_u32_e32 v121, 0, v38
	v_lshlrev_b32_e32 v122, 4, v36
	v_lshlrev_b32_e32 v37, 16, v12
	v_and_b32_e32 v39, 0xffff0000, v12
	v_add_u32_e32 v36, v121, v122
	v_mul_f32_e32 v37, v77, v37
	v_mul_f32_e32 v39, v77, v39
	v_mul_f32_e32 v40, v77, v40
	v_mul_f32_e32 v42, v77, v42
	v_mul_f32_e32 v43, v77, v43
	v_mul_f32_e32 v44, v77, v44
	v_mul_f32_e32 v45, v77, v45
	v_mul_f32_e32 v46, v77, v46
	ds_write_b128 v36, v[24:27] offset:34816
	v_mul_f32_e32 v50, v77, v50
	v_mul_f32_e32 v51, v77, v51
	v_mul_f32_e32 v52, v77, v52
	v_mul_f32_e32 v53, v77, v53
	v_mul_f32_e32 v54, v77, v54
	v_mul_f32_e32 v55, v77, v55
	s_waitcnt vmcnt(1)
	v_mul_f32_e32 v24, v37, v28
	v_mul_f32_e32 v25, v39, v29
	v_mul_f32_e32 v26, v40, v30
	v_mul_f32_e32 v27, v42, v31
	s_waitcnt vmcnt(0)
	v_mul_f32_e32 v28, v43, v32
	v_mul_f32_e32 v29, v44, v33
	v_mul_f32_e32 v30, v45, v34
	v_mul_f32_e32 v31, v46, v35
	v_cvt_pk_bf16_f32 v34, v24, v25
	v_cvt_pk_bf16_f32 v35, v26, v27
	v_cvt_pk_bf16_f32 v36, v28, v29
	v_cvt_pk_bf16_f32 v37, v30, v31
	global_load_dwordx4 v[42:45], v152, s[4:5] offset:256
	global_load_dwordx4 v[46:49], v152, s[4:5] offset:272
	v_or_b32_e32 v25, 4, v159
	v_lshlrev_b32_e32 v31, 3, v202
	v_bitop3_b32 v25, v97, v25, v96 bitop3:0x36
	v_and_b32_e32 v123, 8, v31
	v_and_b32_e32 v31, 0xf00, v38
	v_lshlrev_b32_e32 v124, 4, v25
	v_lshlrev_b32_e32 v38, 16, v16
	v_and_b32_e32 v39, 0xffff0000, v16
	v_add_u32_e32 v25, v121, v124
	v_mul_f32_e32 v38, v77, v38
	v_mul_f32_e32 v39, v77, v39
	ds_write_b128 v25, v[34:37] offset:34816
	v_or_b32_e32 v26, 8, v159
	v_lshlrev_b32_e32 v29, 2, v202
	v_bfe_u32 v30, v202, 1, 1
	v_bitop3_b32 v33, v97, v26, v96 bitop3:0x36
	v_and_b32_e32 v86, 28, v29
	v_bitop3_b32 v29, v97, v30, v96 bitop3:0x36
	v_or_b32_e32 v99, 2, v30
	v_lshlrev_b32_e32 v126, 4, v33
	v_xor_b32_e32 v33, 32, v41
	v_or_b32_e32 v27, 12, v159
	v_or_b32_e32 v100, 4, v30
	v_or_b32_e32 v101, 6, v30
	v_or_b32_e32 v118, 8, v30
	v_or_b32_e32 v119, 10, v30
	v_or_b32_e32 v129, 12, v30
	v_or_b32_e32 v30, 14, v30
	v_lshlrev_b32_e32 v128, 4, v29
	v_bitop3_b32 v29, v97, v99, v96 bitop3:0x36
	v_bitop3_b32 v98, v97, v27, v96 bitop3:0x36
	v_bitop3_b32 v30, v97, v30, v96 bitop3:0x36
	v_lshlrev_b32_e32 v130, 4, v29
	v_lshlrev_b32_e32 v26, 2, v74
	v_mov_b32_e32 v27, v153
	v_lshlrev_b32_e32 v127, 4, v98
	v_bitop3_b32 v98, v97, v129, v96 bitop3:0x36
	v_add_u32_e32 v129, 0, v31
	v_lshlrev_b32_e32 v136, 4, v30
	v_lshlrev_b32_e32 v30, 16, v21
	v_and_b32_e32 v31, 0xffff0000, v21
	v_mul_f32_e32 v30, v77, v30
	v_mul_f32_e32 v31, v77, v31
	v_lshlrev_b32_e32 v135, 4, v98
	v_lshl_add_u64 v[98:99], s[40:41], 0, v[152:153]
	s_waitcnt vmcnt(1)
	v_mul_f32_e32 v25, v38, v42
	v_mul_f32_e32 v34, v39, v43
	v_mul_f32_e32 v35, v50, v44
	v_mul_f32_e32 v36, v51, v45
	s_waitcnt vmcnt(0)
	v_mul_f32_e32 v37, v52, v46
	v_mul_f32_e32 v38, v53, v47
	v_mul_f32_e32 v39, v54, v48
	v_mul_f32_e32 v42, v55, v49
	v_cvt_pk_bf16_f32 v140, v25, v34
	v_cvt_pk_bf16_f32 v141, v35, v36
	v_cvt_pk_bf16_f32 v142, v37, v38
	v_cvt_pk_bf16_f32 v143, v39, v42
	global_load_dwordx4 v[144:147], v152, s[4:5] offset:400
	global_load_dwordx4 v[154:157], v152, s[4:5] offset:384
	v_xor_b32_e32 v25, 16, v41
	v_cmp_lt_i32_e32 vcc, v25, v71
	v_bitop3_b32 v34, v97, v100, v96 bitop3:0x36
	v_bitop3_b32 v35, v97, v101, v96 bitop3:0x36
	v_cndmask_b32_e32 v25, v41, v25, vcc
	v_cmp_lt_i32_e32 vcc, v33, v71
	v_lshlrev_b32_e32 v131, 4, v34
	v_lshlrev_b32_e32 v132, 4, v35
	v_cndmask_b32_e32 v29, v41, v33, vcc
	v_lshlrev_b32_e32 v137, 2, v25
	v_lshlrev_b32_e32 v138, 2, v29
	v_lshlrev_b32_e32 v25, 16, v20
	v_and_b32_e32 v29, 0xffff0000, v20
	v_lshlrev_b32_e32 v33, 16, v22
	v_and_b32_e32 v34, 0xffff0000, v22
	v_lshlrev_b32_e32 v35, 16, v23
	v_and_b32_e32 v41, 0xffff0000, v23
	v_bitop3_b32 v42, v97, v118, v96 bitop3:0x36
	v_bitop3_b32 v43, v97, v119, v96 bitop3:0x36
	v_lshl_add_u64 v[96:97], s[14:15], 0, v[26:27]
	v_add_u32_e32 v26, v121, v126
	v_mul_f32_e32 v25, v77, v25
	v_mul_f32_e32 v29, v77, v29
	v_mul_f32_e32 v33, v77, v33
	v_mul_f32_e32 v34, v77, v34
	v_mul_f32_e32 v35, v77, v35
	v_mul_f32_e32 v41, v77, v41
	v_mov_b32_e32 v36, v153
	v_mov_b32_e32 v37, v153
	v_mov_b32_e32 v38, v153
	v_mov_b32_e32 v39, v153
	v_mov_b32_e32 v44, v153
	v_mov_b32_e32 v45, v153
	v_mov_b32_e32 v46, v153
	v_mov_b32_e32 v47, v153
	v_mov_b32_e32 v48, v153
	v_mov_b32_e32 v49, v153
	v_mov_b32_e32 v50, v153
	v_mov_b32_e32 v51, v153
	v_mov_b32_e32 v52, v153
	v_mov_b32_e32 v53, v153
	v_mov_b32_e32 v54, v153
	v_mov_b32_e32 v55, v153
	v_add_u32_e32 v27, v121, v127
	v_lshlrev_b32_e32 v133, 4, v42
	v_lshlrev_b32_e32 v134, 4, v43
	v_lshl_add_u64 v[100:101], s[12:13], 0, v[152:153]
	ds_write_b128 v26, v[140:143] offset:34816
	v_mov_b32_e32 v71, v153
	s_waitcnt vmcnt(0)
	v_mul_f32_e32 v25, v25, v154
	v_mul_f32_e32 v26, v29, v155
	v_mul_f32_e32 v29, v30, v156
	v_mul_f32_e32 v30, v31, v157
	v_mul_f32_e32 v31, v33, v144
	v_mul_f32_e32 v33, v34, v145
	v_mul_f32_e32 v34, v35, v146
	v_mul_f32_e32 v35, v41, v147
	v_cvt_pk_bf16_f32 v140, v25, v26
	v_cvt_pk_bf16_f32 v141, v29, v30
	v_cvt_pk_bf16_f32 v142, v31, v33
	v_cvt_pk_bf16_f32 v143, v34, v35
	ds_write_b128 v27, v[140:143] offset:34816
	s_cmp_eq_u32 s42, s60
	s_cbranch_scc1 .LBB0_183
; __device__ __forceinline__ unsigned cvt_pk_bf16(float lo, float hi) { unsigned r; asm volatile("v_cvt_pk_bf16_f32 %0, %1, %2" : "=v"(r) : "v"(lo), "v"(hi)); return r; }
; #define MIX_LDS_BARRIER() do { asm volatile("s_waitcnt lgkmcnt(0)" ::: "memory"); __builtin_amdgcn_s_barrier(); asm volatile("" ::: "memory"); } while (0)
; __device__ __forceinline__ void conv_load(const ConvJob& J, int idx, f32x4 (&v)[8], int lane) {
;     const bool second = idx >= 32768; const int r = idx & 32767;
;     const float* W = second ? J.w2 : J.w1; const int N = second ? D : FF, nb = second ? 128 : 512;
;     const int k0 = 64 * (r / nb), n0 = 32 * (r % nb);
;     const float* p = W + (size_t)(k0 + 8 * (lane >> 3)) * N + n0 + 4 * (lane & 7);
; #pragma unroll
;     for (int i = 0; i < 8; ++i) v[i] = __builtin_nontemporal_load((const f32x4*)(p + (size_t)i * N));
; __device__ __forceinline__ void gmlp_stream(LAS unsigned char* lds, const MixArgs& A, ConvJob& J, int vcu, int G, int tid, int wid, int lane) {
;     ...
;             const float* wp = A.ws + ((size_t)hh * 128 + trow) * 128 + 4 * fq;
; #pragma unroll
;             for (int ks = 0; ks < 4; ++ks) { const f32x4 a = *(const f32x4*)(wp + 32 * ks), c = *(const f32x4*)(wp + 32 * ks + 16);
;                 u32x4 w; w.x = cvt_pk_bf16(a[0], a[1]); w.y = cvt_pk_bf16(a[2], a[3]); w.z = cvt_pk_bf16(c[0], c[1]); w.w = cvt_pk_bf16(c[2], c[3]);
;                 wf[ks] = __builtin_bit_cast(bf16x8, w); }
;             bsv = A.bs[hh * 128 + trow]; w_head = hh;
;         }
;         MIX_LDS_BARRIER();
;         const int nu = u + G; const bool nvalid = nu < NU; const int nhh = nu & 15, nbb = nu >> 4;
;         if (nvalid) GM_LOADV(nbb, nhh);
;         f32x4 cv[8]; const int cidx = J.next; const bool cdo = cidx < CONV_BLOCKS;
;         if (cdo) conv_load(J, cidx, cv, lane);
;         const size_t tok = (size_t)bb * 128 + trow;
;         u32x2 un[8];
;         if (nvalid) { const bf16_t* upn = A.Z + ((size_t)nbb * 128 + trow) * INW + O_U + nhh * 128 + 4 * fq;
; #pragma unroll
;             for (int c = 0; c < 8; ++c) un[c] = *(const u32x2*)(upn + 16 * c); }
.LBB0_182:
	v_lshl_add_u32 v152, s42, 7, v150
	v_lshlrev_b64 v[24:25], 9, v[152:153]
	v_lshl_add_u64 v[118:119], v[96:97], 0, v[24:25]
	global_load_dwordx4 v[24:27], v[118:119], off
	global_load_dwordx4 v[28:31], v[118:119], off offset:64
	s_mov_b32 s60, s42
	s_waitcnt vmcnt(1)
	v_cvt_pk_bf16_f32 v24, v24, v25
	v_cvt_pk_bf16_f32 v25, v26, v27
	s_waitcnt vmcnt(0)
	v_cvt_pk_bf16_f32 v26, v28, v29
	v_cvt_pk_bf16_f32 v27, v30, v31
	global_load_dwordx4 v[28:31], v[118:119], off offset:128
	global_load_dwordx4 v[32:35], v[118:119], off offset:192
	s_waitcnt vmcnt(1)
	v_cvt_pk_bf16_f32 v28, v28, v29
	v_cvt_pk_bf16_f32 v29, v30, v31
	s_waitcnt vmcnt(0)
	v_cvt_pk_bf16_f32 v30, v32, v33
	v_cvt_pk_bf16_f32 v31, v34, v35
	global_load_dwordx4 v[32:35], v[118:119], off offset:256
	global_load_dwordx4 v[40:43], v[118:119], off offset:320
	s_waitcnt vmcnt(1)
	v_cvt_pk_bf16_f32 v32, v32, v33
	v_cvt_pk_bf16_f32 v33, v34, v35
	s_waitcnt vmcnt(0)
	v_cvt_pk_bf16_f32 v34, v40, v41
	v_cvt_pk_bf16_f32 v35, v42, v43
	global_load_dwordx4 v[40:43], v[118:119], off offset:384
	global_load_dwordx4 v[140:143], v[118:119], off offset:448
	v_lshl_add_u64 v[118:119], v[152:153], 2, s[16:17]
	s_waitcnt vmcnt(1)
	v_cvt_pk_bf16_f32 v40, v40, v41
	v_cvt_pk_bf16_f32 v41, v42, v43
	s_waitcnt vmcnt(0)
	v_cvt_pk_bf16_f32 v42, v140, v141
	v_cvt_pk_bf16_f32 v43, v142, v143
	global_load_dword v125, v[118:119], off
.LBB0_183:
	s_add_i32 s78, s78, s3
	s_cmpk_lt_i32 s78, 0x800
	s_waitcnt lgkmcnt(0)
	s_barrier
	s_cselect_b64 s[50:51], -1, 0
	s_cmpk_gt_i32 s78, 0x7ff
	s_cselect_b64 s[14:15], -1, 0
	s_and_b32 s64, s78, 15
	s_ashr_i32 s12, s78, 4
	s_and_b64 vcc, exec, s[14:15]
	s_cbranch_vccnz .LBB0_185
	s_ashr_i32 s13, s12, 31
	s_lshl_b64 s[4:5], s[12:13], 7
	v_lshl_add_u64 v[0:1], s[4:5], 0, v[148:149]
	v_mov_b64_e32 v[2:3], s[18:19]
	v_mad_u64_u32 v[2:3], s[4:5], v0, s56, v[2:3]
	v_mad_i32_i24 v3, v1, s56, v3
	s_lshl_b32 s6, s64, 8
	v_lshl_add_u64 v[2:3], v[2:3], 0, s[6:7]
	v_mov_b32_e32 v77, v153
	v_lshl_add_u64 v[2:3], v[2:3], 0, v[76:77]
	v_lshl_add_u64 v[4:5], v[2:3], 0, s[8:9]
	v_add_co_u32_e32 v2, vcc, s57, v2
	v_lshlrev_b64 v[0:1], 7, v[0:1]
	s_nop 0
	v_addc_co_u32_e32 v3, vcc, 0, v3, vcc
	global_load_dwordx4 v[12:15], v[4:5], off offset:64
	global_load_dwordx4 v[16:19], v[4:5], off offset:128
	global_load_dwordx4 v[8:11], v[2:3], off offset:2048
	global_load_dwordx4 v[20:23], v[4:5], off offset:192
	v_lshl_add_u64 v[4:5], v[98:99], 0, v[0:1]
	global_load_dwordx4 v[0:3], v[4:5], off offset:16
	s_nop 0
	global_load_dwordx4 v[4:7], v[4:5], off
.LBB0_185:
	s_cmp_lt_i32 s81, 0x10000
	s_cselect_b64 s[40:41], -1, 0
	s_cmp_gt_i32 s81, 0xffff
	s_cbranch_scc1 .LBB0_187
	s_and_b32 s4, s81, 0x7fff
	s_cmpk_gt_i32 s81, 0x7fff
	s_cselect_b32 s5, s27, s25
	s_cselect_b32 s6, s26, s24
	v_mov_b32_e32 v37, s5
	s_cselect_b32 s5, 7, 9
	v_mov_b32_e32 v36, s6
	s_cselect_b32 s6, s61, 0x1ff
	s_cselect_b32 s13, 12, 14
	s_lshr_b32 s4, s4, s5
	v_lshl_or_b32 v152, s4, 6, v72
	s_and_b32 s4, s6, s81
	v_lshlrev_b64 v[38:39], s13, v[152:153]
	v_lshl_add_u64 v[36:37], v[38:39], 2, v[36:37]
	s_lshl_b32 s6, s4, 7
	v_lshl_add_u64 v[36:37], v[36:37], 0, s[6:7]
	v_lshlrev_b32_e32 v152, 2, v86
	v_lshl_add_u64 v[64:65], v[36:37], 0, v[152:153]
	s_lshl_b64 s[4:5], 1, s13
	v_lshl_add_u64 v[44:45], s[4:5], 2, v[64:65]
	s_lshl_b64 s[4:5], 2, s13
	v_lshl_add_u64 v[48:49], s[4:5], 2, v[64:65]
	s_lshl_b64 s[4:5], 3, s13
	v_lshl_add_u64 v[52:53], s[4:5], 2, v[64:65]
	s_lshl_b64 s[4:5], 4, s13
	v_lshl_add_u64 v[56:57], s[4:5], 2, v[64:65]
	s_lshl_b64 s[4:5], 5, s13
	v_lshl_add_u64 v[60:61], s[4:5], 2, v[64:65]
	s_lshl_b64 s[4:5], 6, s13
	v_lshl_add_u64 v[66:67], s[4:5], 2, v[64:65]
	s_lshl_b64 s[4:5], 7, s13
	v_lshl_add_u64 v[68:69], s[4:5], 2, v[64:65]
	global_load_dwordx4 v[36:39], v[64:65], off nt
	s_nop 0
	global_load_dwordx4 v[44:47], v[44:45], off nt
	s_nop 0
	global_load_dwordx4 v[48:51], v[48:49], off nt
	s_nop 0
	global_load_dwordx4 v[52:55], v[52:53], off nt
	s_nop 0
	global_load_dwordx4 v[56:59], v[56:57], off nt
	s_nop 0
	global_load_dwordx4 v[60:63], v[60:61], off nt
	s_nop 0
	global_load_dwordx4 v[64:67], v[66:67], off nt
	s_nop 0
	global_load_dwordx4 v[68:71], v[68:69], off nt

; __device__ __forceinline__ void gmlp_stream(LAS unsigned char* lds, const MixArgs& A, ConvJob& J, int vcu, int G, int tid, int wid, int lane) {
;     ...
; #pragma unroll
;         for (int ks = 0; ks < 4; ++ks)
; #pragma unroll
;             for (int c = 0; c < 8; ++c) { const bf16x8 a = tr_frag(vbase, 32 * ks, c, lane);
;                 acc[c] = __builtin_amdgcn_mfma_f32_16x16x32_bf16(a, wf[ks], acc[c], 0, 0, 0); }
.LBB0_189:
	s_mul_i32 s6, s63, 0x10800
	v_add_u32_e32 v77, s6, v129
	v_add3_u32 v118, v77, v128, v123
	ds_read_b64_tr_b16 v[140:141], v118 offset:34816
	ds_read_b64_tr_b16 v[142:143], v118 offset:38912
	v_add3_u32 v119, v77, v130, v123
	v_add3_u32 v139, v77, v131, v123
	v_add3_u32 v205, v77, v132, v123
	v_add3_u32 v214, v77, v133, v123
	ds_read_b64_tr_b16 v[144:145], v118 offset:43008
	ds_read_b64_tr_b16 v[146:147], v118 offset:47104
	ds_read_b64_tr_b16 v[154:155], v119 offset:34816
	ds_read_b64_tr_b16 v[156:157], v119 offset:38912
	ds_read_b64_tr_b16 v[158:159], v119 offset:43008
	ds_read_b64_tr_b16 v[160:161], v119 offset:47104
	ds_read_b64_tr_b16 v[162:163], v139 offset:34816
	ds_read_b64_tr_b16 v[164:165], v139 offset:38912
	ds_read_b64_tr_b16 v[166:167], v139 offset:43008
	ds_read_b64_tr_b16 v[168:169], v139 offset:47104
	ds_read_b64_tr_b16 v[170:171], v205 offset:34816
	ds_read_b64_tr_b16 v[172:173], v205 offset:38912
	ds_read_b64_tr_b16 v[174:175], v205 offset:43008
	ds_read_b64_tr_b16 v[176:177], v205 offset:47104
	ds_read_b64_tr_b16 v[178:179], v214 offset:34816
	ds_read_b64_tr_b16 v[180:181], v214 offset:38912
	ds_read_b64_tr_b16 v[182:183], v214 offset:43008
	ds_read_b64_tr_b16 v[184:185], v214 offset:47104
	s_waitcnt lgkmcnt(14)
	v_mfma_f32_16x16x32_bf16 v[140:143], v[140:143], v[24:27], 0
	v_add3_u32 v215, v77, v134, v123
	ds_read_b64_tr_b16 v[186:187], v215 offset:34816
	ds_read_b64_tr_b16 v[188:189], v215 offset:38912
	ds_read_b64_tr_b16 v[190:191], v215 offset:43008
	ds_read_b64_tr_b16 v[192:193], v215 offset:47104
	v_add3_u32 v216, v77, v135, v123
	v_mfma_f32_16x16x32_bf16 v[154:157], v[154:157], v[24:27], 0
	v_add3_u32 v77, v77, v136, v123
	ds_read_b64_tr_b16 v[194:195], v216 offset:34816
	ds_read_b64_tr_b16 v[196:197], v216 offset:38912
	ds_read_b64_tr_b16 v[198:199], v216 offset:43008
	ds_read_b64_tr_b16 v[200:201], v216 offset:47104
	ds_read_b64_tr_b16 v[206:207], v77 offset:34816
	ds_read_b64_tr_b16 v[208:209], v77 offset:38912
	ds_read_b64_tr_b16 v[210:211], v77 offset:43008
	ds_read_b64_tr_b16 v[212:213], v77 offset:47104
	s_waitcnt lgkmcnt(14)
	v_mfma_f32_16x16x32_bf16 v[162:165], v[162:165], v[24:27], 0
	s_ashr_i32 s49, s48, 31
	s_lshl_b64 s[48:49], s[48:49], 7
	s_lshl_b32 s6, s42, 8
	v_mfma_f32_16x16x32_bf16 v[178:181], v[178:181], v[24:27], 0
	s_waitcnt lgkmcnt(10)
	v_mfma_f32_16x16x32_bf16 v[186:189], v[186:189], v[24:27], 0
	v_mfma_f32_16x16x32_bf16 v[140:143], v[144:147], v[28:31], v[140:143]
	v_mfma_f32_16x16x32_bf16 v[144:147], v[158:161], v[28:31], v[154:157]
	v_mfma_f32_16x16x32_bf16 v[154:157], v[166:169], v[28:31], v[162:165]
	v_mfma_f32_16x16x32_bf16 v[162:165], v[182:185], v[28:31], v[178:181]
	s_nop 2
	ds_read_b64_tr_b16 v[178:179], v118 offset:51200
	ds_read_b64_tr_b16 v[180:181], v118 offset:55296
	ds_read_b64_tr_b16 v[182:183], v118 offset:59392
	ds_read_b64_tr_b16 v[184:185], v118 offset:63488
	s_waitcnt lgkmcnt(12)
	v_mfma_f32_16x16x32_bf16 v[166:169], v[190:193], v[28:31], v[186:189]
	s_waitcnt lgkmcnt(2)
	v_mfma_f32_16x16x32_bf16 v[140:143], v[178:181], v[32:35], v[140:143]
	ds_read_b64_tr_b16 v[178:179], v119 offset:51200
	ds_read_b64_tr_b16 v[180:181], v119 offset:55296
	ds_read_b64_tr_b16 v[186:187], v119 offset:59392
	ds_read_b64_tr_b16 v[188:189], v119 offset:63488
	v_lshl_add_u64 v[118:119], s[48:49], 0, v[150:151]
	v_mfma_f32_16x16x32_bf16 v[170:173], v[170:173], v[24:27], 0
	v_mfma_f32_16x16x32_bf16 v[194:197], v[194:197], v[24:27], 0
	s_waitcnt lgkmcnt(2)
	v_mfma_f32_16x16x32_bf16 v[144:147], v[178:181], v[32:35], v[144:147]
	ds_read_b64_tr_b16 v[178:179], v139 offset:51200
	ds_read_b64_tr_b16 v[180:181], v139 offset:55296
	ds_read_b64_tr_b16 v[190:191], v139 offset:59392
	ds_read_b64_tr_b16 v[192:193], v139 offset:63488
	v_mfma_f32_16x16x32_bf16 v[158:161], v[174:177], v[28:31], v[170:173]
	v_mfma_f32_16x16x32_bf16 v[170:173], v[198:201], v[28:31], v[194:197]
	s_waitcnt lgkmcnt(2)
	v_mfma_f32_16x16x32_bf16 v[154:157], v[178:181], v[32:35], v[154:157]
	ds_read_b64_tr_b16 v[178:179], v205 offset:51200
	ds_read_b64_tr_b16 v[180:181], v205 offset:55296
	ds_read_b64_tr_b16 v[194:195], v205 offset:59392
	ds_read_b64_tr_b16 v[196:197], v205 offset:63488
	v_mfma_f32_16x16x32_bf16 v[206:209], v[206:209], v[24:27], 0
	s_waitcnt lgkmcnt(2)
	v_mfma_f32_16x16x32_bf16 v[158:161], v[178:181], v[32:35], v[158:161]
	ds_read_b64_tr_b16 v[178:179], v214 offset:51200
	ds_read_b64_tr_b16 v[180:181], v214 offset:55296
	ds_read_b64_tr_b16 v[198:199], v214 offset:59392
	ds_read_b64_tr_b16 v[200:201], v214 offset:63488
	v_mfma_f32_16x16x32_bf16 v[174:177], v[210:213], v[28:31], v[206:209]
	s_waitcnt lgkmcnt(2)
	v_mfma_f32_16x16x32_bf16 v[162:165], v[178:181], v[32:35], v[162:165]
	ds_read_b64_tr_b16 v[178:179], v215 offset:51200
	ds_read_b64_tr_b16 v[180:181], v215 offset:55296
	ds_read_b64_tr_b16 v[206:207], v215 offset:59392
	ds_read_b64_tr_b16 v[208:209], v215 offset:63488
	s_waitcnt lgkmcnt(2)
	v_mfma_f32_16x16x32_bf16 v[166:169], v[178:181], v[32:35], v[166:169]
	ds_read_b64_tr_b16 v[178:179], v216 offset:51200
	ds_read_b64_tr_b16 v[180:181], v216 offset:55296
	ds_read_b64_tr_b16 v[210:211], v216 offset:59392
	ds_read_b64_tr_b16 v[212:213], v216 offset:63488
	v_mfma_f32_16x16x32_bf16 v[140:143], v[182:185], v[40:43], v[140:143]
	s_waitcnt lgkmcnt(2)
	v_mfma_f32_16x16x32_bf16 v[170:173], v[178:181], v[32:35], v[170:173]
	ds_read_b64_tr_b16 v[178:179], v77 offset:51200
	ds_read_b64_tr_b16 v[180:181], v77 offset:55296
	ds_read_b64_tr_b16 v[214:215], v77 offset:59392
	ds_read_b64_tr_b16 v[216:217], v77 offset:63488
	v_lshlrev_b32_e32 v77, 16, v116
	s_waitcnt vmcnt(0)
	v_add_f32_e32 v139, v125, v140
	s_waitcnt lgkmcnt(2)
; __device__ __forceinline__ unsigned cvt_pk_bf16(float lo, float hi) { unsigned r; asm volatile("v_cvt_pk_bf16_f32 %0, %1, %2" : "=v"(r) : "v"(lo), "v"(hi)); return r; }
; __device__ __forceinline__ float bf_lo(unsigned w) { return __uint_as_float(w << 16); }
; __device__ __forceinline__ float bf_hi(unsigned w) { return __uint_as_float(w & 0xffff0000u); }
; __device__ __forceinline__ void gmlp_stream(LAS unsigned char* lds, const MixArgs& A, ConvJob& J, int vcu, int G, int tid, int wid, int lane) {
;     ...
;         bf16_t* op = A.AG + tok * MIXW + 2048 + hh * 128 + 4 * fq;
;         float ssq = 0.f;
; #pragma unroll
;         for (int c = 0; c < 8; ++c) {
;             f32x4 o; o[0] = bf_lo(uu[c].x) * (acc[c][0] + bsv); o[1] = bf_hi(uu[c].x) * (acc[c][1] + bsv); o[2] = bf_lo(uu[c].y) * (acc[c][2] + bsv); o[3] = bf_hi(uu[c].y) * (acc[c][3] + bsv);
;             ssq += (o[0] * o[0] + o[1] * o[1]) + (o[2] * o[2] + o[3] * o[3]);
;             u32x2 w; w.x = cvt_pk_bf16(o[0], o[1]); w.y = cvt_pk_bf16(o[2], o[3]); *(u32x2*)(op + 16 * c) = w; }
;         ssq += __shfl_xor(ssq, 16); ssq += __shfl_xor(ssq, 32);
;         if (fq == 0) A.SS[tok * 32 + 16 + hh] = ssq;
	v_mfma_f32_16x16x32_bf16 v[174:177], v[178:181], v[32:35], v[174:177]
	v_mul_f32_e32 v77, v139, v77
	v_and_b32_e32 v116, 0xffff0000, v116
	v_add_f32_e32 v139, v125, v141
	v_lshlrev_b64 v[178:179], 13, v[118:119]
	v_mul_f32_e32 v116, v139, v116
	v_lshlrev_b32_e32 v139, 16, v117
	v_add_f32_e32 v140, v125, v142
	v_lshl_add_u64 v[178:179], s[20:21], 0, v[178:179]
	v_mul_f32_e32 v139, v140, v139
	v_and_b32_e32 v117, 0xffff0000, v117
	v_add_f32_e32 v140, v125, v143
	v_lshl_add_u64 v[178:179], v[178:179], 0, s[6:7]
	v_mul_f32_e32 v117, v140, v117
	v_mfma_f32_16x16x32_bf16 v[144:147], v[186:189], v[40:43], v[144:147]
	v_lshl_add_u64 v[178:179], v[178:179], 0, v[152:153]
	v_mul_f32_e32 v152, v116, v116
	v_fmac_f32_e32 v152, v77, v77
	s_waitcnt lgkmcnt(0)
	v_mfma_f32_16x16x32_bf16 v[140:143], v[214:217], v[40:43], v[174:177]
	v_cvt_pk_bf16_f32 v116, v77, v116
	v_lshlrev_b32_e32 v77, 16, v114
	v_and_b32_e32 v114, 0xffff0000, v114
	v_mfma_f32_16x16x32_bf16 v[154:157], v[190:193], v[40:43], v[154:157]
	v_mul_f32_e32 v174, v117, v117
	v_fmac_f32_e32 v174, v139, v139
	v_add_f32_e32 v152, v152, v174
	v_add_co_u32_e32 v174, vcc, s58, v178
	v_cvt_pk_bf16_f32 v117, v139, v117
	v_lshl_add_u64 v[180:181], v[178:179], 0, s[44:45]
	s_nop 0
	v_addc_co_u32_e32 v175, vcc, 0, v179, vcc
	global_store_dwordx2 v[174:175], v[116:117], off
	v_add_f32_e32 v116, v125, v144
	v_mul_f32_e32 v77, v116, v77
	v_add_f32_e32 v116, v125, v145
	v_mul_f32_e32 v114, v116, v114
	v_lshlrev_b32_e32 v116, 16, v115
	v_add_f32_e32 v117, v125, v146
	v_mul_f32_e32 v116, v117, v116
	v_and_b32_e32 v115, 0xffff0000, v115
	v_add_f32_e32 v117, v125, v147
	v_mul_f32_e32 v115, v117, v115
	v_mul_f32_e32 v117, v114, v114
	v_cvt_pk_bf16_f32 v114, v77, v114
	v_fmac_f32_e32 v117, v77, v77
	v_mul_f32_e32 v139, v115, v115
	v_cvt_pk_bf16_f32 v115, v116, v115
	global_store_dwordx2 v[180:181], v[114:115], off offset:32
	v_lshlrev_b32_e32 v77, 16, v112
	v_add_f32_e32 v114, v125, v154
	v_mfma_f32_16x16x32_bf16 v[158:161], v[194:197], v[40:43], v[158:161]
	v_mul_f32_e32 v77, v114, v77
	v_and_b32_e32 v112, 0xffff0000, v112
	v_add_f32_e32 v114, v125, v155
	v_mul_f32_e32 v112, v114, v112
	v_lshlrev_b32_e32 v114, 16, v113
	v_add_f32_e32 v115, v125, v156
	v_mul_f32_e32 v114, v115, v114
	v_and_b32_e32 v113, 0xffff0000, v113
	v_add_f32_e32 v115, v125, v157
	v_mul_f32_e32 v113, v115, v113
	v_mul_f32_e32 v115, v112, v112
	v_cvt_pk_bf16_f32 v112, v77, v112
	v_fmac_f32_e32 v139, v116, v116
	v_fmac_f32_e32 v115, v77, v77
	v_mul_f32_e32 v116, v113, v113
	v_cvt_pk_bf16_f32 v113, v114, v113
	global_store_dwordx2 v[180:181], v[112:113], off offset:64
	v_lshlrev_b32_e32 v77, 16, v110
	v_add_f32_e32 v112, v125, v158
	v_mfma_f32_16x16x32_bf16 v[162:165], v[198:201], v[40:43], v[162:165]
	v_mul_f32_e32 v77, v112, v77
	v_and_b32_e32 v110, 0xffff0000, v110
	v_add_f32_e32 v112, v125, v159
	v_mul_f32_e32 v110, v112, v110
	v_lshlrev_b32_e32 v112, 16, v111
	v_add_f32_e32 v113, v125, v160
	v_mul_f32_e32 v112, v113, v112
	v_and_b32_e32 v111, 0xffff0000, v111
	v_add_f32_e32 v113, v125, v161
	v_mul_f32_e32 v111, v113, v111
	v_mul_f32_e32 v113, v110, v110
	v_cvt_pk_bf16_f32 v110, v77, v110
	v_fmac_f32_e32 v116, v114, v114
	v_fmac_f32_e32 v113, v77, v77
	v_mul_f32_e32 v114, v111, v111
	v_cvt_pk_bf16_f32 v111, v112, v111
	global_store_dwordx2 v[180:181], v[110:111], off offset:96
	v_lshlrev_b32_e32 v77, 16, v108
	v_add_f32_e32 v110, v125, v162
	v_mfma_f32_16x16x32_bf16 v[166:169], v[206:209], v[40:43], v[166:169]
	v_mul_f32_e32 v77, v110, v77
	v_and_b32_e32 v108, 0xffff0000, v108
	v_add_f32_e32 v110, v125, v163
	v_mul_f32_e32 v108, v110, v108
	v_lshlrev_b32_e32 v110, 16, v109
	v_add_f32_e32 v111, v125, v164
	v_mul_f32_e32 v110, v111, v110
	v_and_b32_e32 v109, 0xffff0000, v109
	v_add_f32_e32 v111, v125, v165
	v_mul_f32_e32 v109, v111, v109
	v_mul_f32_e32 v111, v108, v108
	v_cvt_pk_bf16_f32 v108, v77, v108
	v_fmac_f32_e32 v114, v112, v112
	v_fmac_f32_e32 v111, v77, v77
	v_mul_f32_e32 v112, v109, v109
	v_cvt_pk_bf16_f32 v109, v110, v109
	global_store_dwordx2 v[180:181], v[108:109], off offset:128
	v_lshlrev_b32_e32 v77, 16, v106
	v_add_f32_e32 v108, v125, v166
	v_mul_f32_e32 v77, v108, v77
	v_and_b32_e32 v106, 0xffff0000, v106
	v_add_f32_e32 v108, v125, v167
	v_mul_f32_e32 v106, v108, v106
	v_lshlrev_b32_e32 v108, 16, v107
	v_add_f32_e32 v109, v125, v168
	v_mfma_f32_16x16x32_bf16 v[170:173], v[210:213], v[40:43], v[170:173]
	v_mul_f32_e32 v108, v109, v108
	v_and_b32_e32 v107, 0xffff0000, v107
	v_add_f32_e32 v109, v125, v169
	v_add_f32_e32 v117, v117, v139
	v_mul_f32_e32 v107, v109, v107
	v_add_f32_e32 v117, v152, v117
	v_add_f32_e32 v115, v115, v116
	v_fmac_f32_e32 v112, v110, v110
	v_mul_f32_e32 v109, v106, v106
	v_mul_f32_e32 v110, v107, v107
	v_add_f32_e32 v115, v117, v115
	v_add_f32_e32 v113, v113, v114
	v_fmac_f32_e32 v109, v77, v77
	v_fmac_f32_e32 v110, v108, v108
	v_add_f32_e32 v113, v115, v113
	v_add_f32_e32 v111, v111, v112
	v_add_f32_e32 v109, v109, v110
	v_cvt_pk_bf16_f32 v106, v77, v106
	v_lshlrev_b32_e32 v77, 16, v104
	v_add_f32_e32 v110, v125, v170
	v_add_f32_e32 v111, v113, v111
	v_mul_f32_e32 v77, v110, v77
	v_and_b32_e32 v104, 0xffff0000, v104
	v_add_f32_e32 v110, v125, v171
	v_add_f32_e32 v109, v111, v109
	v_mul_f32_e32 v104, v110, v104
	v_lshlrev_b32_e32 v110, 16, v105
	v_add_f32_e32 v111, v125, v172
	v_mul_f32_e32 v110, v111, v110
	v_and_b32_e32 v105, 0xffff0000, v105
	v_add_f32_e32 v111, v125, v173
	v_mul_f32_e32 v105, v111, v105
	v_mul_f32_e32 v111, v104, v104
	v_mul_f32_e32 v112, v105, v105
	v_fmac_f32_e32 v111, v77, v77
	v_fmac_f32_e32 v112, v110, v110
	v_add_f32_e32 v111, v111, v112
	v_add_f32_e32 v109, v109, v111
	v_lshlrev_b32_e32 v111, 16, v102
	v_add_f32_e32 v112, v125, v140
	v_mul_f32_e32 v111, v112, v111
	v_and_b32_e32 v102, 0xffff0000, v102
	v_add_f32_e32 v112, v125, v141
	v_mul_f32_e32 v112, v112, v102
	v_lshlrev_b32_e32 v102, 16, v103
	v_add_f32_e32 v113, v125, v142
	v_mul_f32_e32 v113, v113, v102
	v_and_b32_e32 v102, 0xffff0000, v103
	v_add_f32_e32 v103, v125, v143
	v_mul_f32_e32 v103, v103, v102
	v_mul_f32_e32 v102, v112, v112
	v_mul_f32_e32 v114, v103, v103
	v_fmac_f32_e32 v102, v111, v111
	v_fmac_f32_e32 v114, v113, v113
	v_add_f32_e32 v102, v102, v114
	v_add_f32_e32 v102, v109, v102
	ds_bpermute_b32 v109, v137, v102
	v_cvt_pk_bf16_f32 v107, v108, v107
	global_store_dwordx2 v[180:181], v[106:107], off offset:160
	v_cvt_pk_bf16_f32 v104, v77, v104
	v_cvt_pk_bf16_f32 v105, v110, v105
	s_waitcnt lgkmcnt(0)
	v_add_f32_e32 v77, v102, v109
	ds_bpermute_b32 v102, v138, v77
	global_store_dwordx2 v[180:181], v[104:105], off offset:192
	v_cvt_pk_bf16_f32 v104, v111, v112
	v_cvt_pk_bf16_f32 v105, v113, v103
	global_store_dwordx2 v[180:181], v[104:105], off offset:224
	s_and_saveexec_b64 s[48:49], s[0:1]
	s_cbranch_execnz .LBB0_193
	s_or_b64 exec, exec, s[48:49]
	s_and_b64 vcc, exec, s[4:5]
	s_cbranch_vccz .LBB0_194

; __device__ __forceinline__ void gmlp_stream(LAS unsigned char* lds, const MixArgs& A, ConvJob& J, int vcu, int G, int tid, int wid, int lane) {
;     ...
;         if (nvalid) GM_WRITEV(buf ^ 1, nhh);
.LBB0_194:
	s_lshl_b32 s6, s64, 9
	v_lshl_add_u64 v[114:115], v[100:101], 0, s[6:7]
	s_waitcnt lgkmcnt(0)
	global_load_dwordx4 v[102:105], v[114:115], off
	global_load_dwordx4 v[106:109], v[114:115], off offset:16
	v_mov_b32_e32 v110, v0
	v_mov_b32_e32 v111, v4
	v_mov_b32_e32 v112, v1
	v_mov_b32_e32 v113, v5
	v_mov_b32_e32 v116, v2
	v_mov_b32_e32 v117, v6
	v_mov_b32_e32 v118, v3
	v_mov_b32_e32 v119, v7
	v_pk_add_f32 v[110:111], v[110:111], v[112:113]
	v_pk_add_f32 v[112:113], v[116:117], v[118:119]
	v_and_b32_e32 v116, 0xffff0000, v9
	v_pk_add_f32 v[110:111], v[110:111], v[112:113]
	v_and_b32_e32 v112, 0xffff0000, v8
	v_add_f32_e32 v77, v110, v111
	ds_bpermute_b32 v110, v73, v77
	v_lshlrev_b32_e32 v111, 16, v8
	v_lshlrev_b32_e32 v113, 16, v9
	v_lshlrev_b32_e32 v117, 16, v10
	v_and_b32_e32 v118, 0xffff0000, v10
	s_waitcnt lgkmcnt(0)
	v_add_f32_e32 v77, v77, v110
	ds_bpermute_b32 v110, v75, v77
	v_lshlrev_b32_e32 v119, 16, v11
	s_waitcnt lgkmcnt(0)
	v_add_f32_e32 v77, v77, v110
	v_fmamk_f32 v77, v77, 0x3a000000, v87
	v_mul_f32_e32 v110, 0x4f800000, v77
	v_cmp_gt_f32_e32 vcc, s59, v77
	s_nop 1
	v_cndmask_b32_e32 v77, v77, v110, vcc
	v_sqrt_f32_e32 v110, v77
	s_nop 0
	v_add_u32_e32 v139, -1, v110
	v_add_u32_e32 v140, 1, v110
	v_fma_f32 v141, -v139, v110, v77
	v_fma_f32 v142, -v140, v110, v77
	v_cmp_ge_f32_e64 s[4:5], 0, v141
	s_nop 1
	v_cndmask_b32_e64 v110, v110, v139, s[4:5]
	v_cmp_lt_f32_e64 s[4:5], 0, v142
	s_nop 1
	v_cndmask_b32_e64 v110, v110, v140, s[4:5]
	v_mul_f32_e32 v139, 0x37800000, v110
	v_cndmask_b32_e32 v110, v110, v139, vcc
	v_cmp_class_f32_e32 vcc, v77, v120
	v_and_b32_e32 v140, 0xffff0000, v11
	s_nop 0
	v_cndmask_b32_e32 v77, v110, v77, vcc
	v_div_scale_f32 v110, s[4:5], v77, v77, 1.0
	v_rcp_f32_e32 v139, v110
	v_div_scale_f32 v141, vcc, 1.0, v77, 1.0
	s_xor_b32 s4, s63, 1
	v_fma_f32 v142, -v110, v139, 1.0
	v_fmac_f32_e32 v139, v142, v139
	v_mul_f32_e32 v142, v141, v139
	v_fma_f32 v143, -v110, v142, v141
	v_fmac_f32_e32 v142, v143, v139
	v_fma_f32 v110, -v110, v142, v141
	v_div_fmas_f32 v110, v110, v139, v142
	v_div_fixup_f32 v77, v110, v77, 1.0
	v_mul_f32_e32 v110, v77, v111
	v_mul_f32_e32 v111, v77, v112
	v_mul_f32_e32 v112, v77, v113
	v_mul_f32_e32 v113, v77, v116
	v_mul_f32_e32 v116, v77, v117
	v_mul_f32_e32 v117, v77, v118
	v_mul_f32_e32 v118, v77, v119
	v_mul_f32_e32 v119, v77, v140
	s_mul_i32 s4, s4, 0x10800
	v_lshlrev_b32_e32 v139, 16, v14
	s_waitcnt vmcnt(1)
	v_mul_f32_e32 v102, v102, v110
	v_mul_f32_e32 v103, v103, v111
	v_mul_f32_e32 v104, v104, v112
	v_mul_f32_e32 v105, v105, v113
	s_waitcnt vmcnt(0)
	v_mul_f32_e32 v106, v106, v116
	v_mul_f32_e32 v107, v107, v117
	v_mul_f32_e32 v108, v108, v118
	v_mul_f32_e32 v109, v109, v119
	v_cvt_pk_bf16_f32 v102, v102, v103
	v_cvt_pk_bf16_f32 v103, v104, v105
	v_cvt_pk_bf16_f32 v104, v106, v107
	v_cvt_pk_bf16_f32 v105, v108, v109
	global_load_dwordx4 v[106:109], v[114:115], off offset:128
	global_load_dwordx4 v[110:113], v[114:115], off offset:144
	v_lshlrev_b32_e32 v116, 16, v12
	v_and_b32_e32 v117, 0xffff0000, v12
	v_lshlrev_b32_e32 v118, 16, v13
	v_and_b32_e32 v119, 0xffff0000, v13
	v_and_b32_e32 v140, 0xffff0000, v14
	v_lshlrev_b32_e32 v141, 16, v15
	v_and_b32_e32 v142, 0xffff0000, v15
	v_add_u32_e32 v143, s4, v121
	v_add_u32_e32 v144, v143, v122
	v_mul_f32_e32 v116, v77, v116
	v_mul_f32_e32 v117, v77, v117
	v_mul_f32_e32 v118, v77, v118
	v_mul_f32_e32 v119, v77, v119
	v_mul_f32_e32 v139, v77, v139
	v_mul_f32_e32 v140, v77, v140
	v_mul_f32_e32 v141, v77, v141
	v_mul_f32_e32 v142, v77, v142
	ds_write_b128 v144, v[102:105] offset:34816
	v_add_u32_e32 v144, v143, v124
	s_waitcnt vmcnt(1)
	v_mul_f32_e32 v102, v116, v106
	v_mul_f32_e32 v103, v117, v107
	v_mul_f32_e32 v104, v118, v108
	v_mul_f32_e32 v105, v119, v109
	s_waitcnt vmcnt(0)
	v_mul_f32_e32 v106, v139, v110
	v_mul_f32_e32 v107, v140, v111
	v_mul_f32_e32 v108, v141, v112
	v_mul_f32_e32 v109, v142, v113
	v_cvt_pk_bf16_f32 v102, v102, v103
	v_cvt_pk_bf16_f32 v103, v104, v105
	v_cvt_pk_bf16_f32 v104, v106, v107
	v_cvt_pk_bf16_f32 v105, v108, v109
	global_load_dwordx4 v[106:109], v[114:115], off offset:256
	global_load_dwordx4 v[110:113], v[114:115], off offset:272
	v_lshlrev_b32_e32 v116, 16, v16
	v_and_b32_e32 v117, 0xffff0000, v16
	v_lshlrev_b32_e32 v118, 16, v17
	v_and_b32_e32 v119, 0xffff0000, v17
	v_lshlrev_b32_e32 v139, 16, v18
	v_and_b32_e32 v140, 0xffff0000, v18
	v_lshlrev_b32_e32 v141, 16, v19
	v_and_b32_e32 v142, 0xffff0000, v19
	v_mul_f32_e32 v116, v77, v116
	v_mul_f32_e32 v117, v77, v117
	v_mul_f32_e32 v118, v77, v118
	v_mul_f32_e32 v119, v77, v119
	v_mul_f32_e32 v139, v77, v139
	v_mul_f32_e32 v140, v77, v140
	v_mul_f32_e32 v141, v77, v141
	v_mul_f32_e32 v142, v77, v142
	ds_write_b128 v144, v[102:105] offset:34816
	s_waitcnt vmcnt(1)
	v_mul_f32_e32 v102, v116, v106
	v_mul_f32_e32 v103, v117, v107
	v_mul_f32_e32 v104, v118, v108
	v_mul_f32_e32 v105, v119, v109
	s_waitcnt vmcnt(0)
	v_mul_f32_e32 v106, v139, v110
	v_mul_f32_e32 v107, v140, v111
	v_mul_f32_e32 v108, v141, v112
	v_mul_f32_e32 v109, v142, v113
	v_cvt_pk_bf16_f32 v102, v102, v103
	v_cvt_pk_bf16_f32 v103, v104, v105
	v_cvt_pk_bf16_f32 v104, v106, v107
	v_cvt_pk_bf16_f32 v105, v108, v109
	global_load_dwordx4 v[106:109], v[114:115], off offset:384
	global_load_dwordx4 v[110:113], v[114:115], off offset:400
	v_lshlrev_b32_e32 v114, 16, v20
	v_and_b32_e32 v115, 0xffff0000, v20
	v_lshlrev_b32_e32 v116, 16, v21
	v_and_b32_e32 v117, 0xffff0000, v21
	v_lshlrev_b32_e32 v118, 16, v22
	v_and_b32_e32 v119, 0xffff0000, v22
	v_lshlrev_b32_e32 v139, 16, v23
	v_and_b32_e32 v140, 0xffff0000, v23
	v_add_u32_e32 v141, v143, v126
	v_mul_f32_e32 v114, v77, v114
	v_mul_f32_e32 v115, v77, v115
	v_mul_f32_e32 v116, v77, v116
	v_mul_f32_e32 v117, v77, v117
	v_mul_f32_e32 v118, v77, v118
	v_mul_f32_e32 v119, v77, v119
	v_mul_f32_e32 v139, v77, v139
	v_mul_f32_e32 v77, v77, v140
	ds_write_b128 v141, v[102:105] offset:34816
	s_waitcnt vmcnt(1)
	v_mul_f32_e32 v102, v114, v106
	v_mul_f32_e32 v103, v115, v107
	v_mul_f32_e32 v104, v116, v108
	v_mul_f32_e32 v105, v117, v109
	s_waitcnt vmcnt(0)
	v_mul_f32_e32 v77, v77, v113
	v_mul_f32_e32 v106, v118, v110
	v_mul_f32_e32 v107, v119, v111
	v_mul_f32_e32 v108, v139, v112
	v_cvt_pk_bf16_f32 v102, v102, v103
	v_cvt_pk_bf16_f32 v103, v104, v105
	v_cvt_pk_bf16_f32 v104, v106, v107
	v_cvt_pk_bf16_f32 v105, v108, v77
	v_add_u32_e32 v77, v143, v127
	ds_write_b128 v77, v[102:105] offset:34816
	s_andn2_b64 vcc, exec, s[40:41]
	s_cbranch_vccnz .LBB0_192
; __device__ __forceinline__ unsigned cvt_pk_bf16(float lo, float hi) { unsigned r; asm volatile("v_cvt_pk_bf16_f32 %0, %1, %2" : "=v"(r) : "v"(lo), "v"(hi)); return r; }
; __device__ __forceinline__ void conv_store(const ConvJob& J, int idx, const f32x4 (&v)[8], int lane) {
;     const bool second = idx >= 32768; const int r = idx & 32767;
;     bf16_t* WT = second ? J.w2t : J.w1t; const int ldt = second ? LDK16 : LDK4, nb = second ? 128 : 512;
;     const int k0 = 64 * (r / nb), n0 = 32 * (r % nb);
;     bf16_t* q = WT + (size_t)(n0 + 4 * (lane & 7)) * ldt + k0 + 8 * (lane >> 3);
; #pragma unroll
;     for (int j = 0; j < 4; ++j) { u32x4 o; o.x = cvt_pk_bf16(v[0][j], v[1][j]); o.y = cvt_pk_bf16(v[2][j], v[3][j]); o.z = cvt_pk_bf16(v[4][j], v[5][j]); o.w = cvt_pk_bf16(v[6][j], v[7][j]);
;         __builtin_nontemporal_store(o, (u32x4*)(q + (size_t)j * ldt)); }
; __device__ __forceinline__ void gmlp_stream(LAS unsigned char* lds, const MixArgs& A, ConvJob& J, int vcu, int G, int tid, int wid, int lane) {
;     ...
;         if (cdo) { conv_store(J, cidx, cv, lane); J.next = cidx + J.stride; }
;         if (!nvalid) break;
; #pragma unroll
;         for (int c = 0; c < 8; ++c) uu[c] = un[c];
;         buf ^= 1; u = nu; hh = nhh; bb = nbb;
.LBB0_195:
	s_and_b32 s6, s81, 0x7fff
	s_cmpk_gt_i32 s81, 0x7fff
	s_cselect_b32 s13, 7, 9
	s_cselect_b32 s40, s61, 0x1ff
	s_cselect_b32 s5, s77, s80
	s_cselect_b32 s4, s76, s79
	s_cselect_b32 s41, s62, 0x1040
	s_lshr_b32 s6, s6, s13
	s_and_b32 s13, s40, s81
	v_lshl_or_b32 v77, s13, 5, v86
	v_mul_u32_u24_e32 v77, s41, v77
	v_lshlrev_b32_e32 v152, 1, v77
	s_waitcnt lgkmcnt(0)
	v_lshl_add_u64 v[102:103], s[4:5], 0, v[152:153]
	s_lshl_b32 s6, s6, 7
	v_lshl_add_u64 v[102:103], v[102:103], 0, s[6:7]
	v_lshlrev_b32_e32 v152, 1, v72
	v_lshl_add_u64 v[106:107], v[102:103], 0, v[152:153]
	s_lshl_b32 s6, s41, 1
	v_cvt_pk_bf16_f32 v102, v36, v44
	v_cvt_pk_bf16_f32 v103, v48, v52
	v_cvt_pk_bf16_f32 v104, v56, v60
	v_cvt_pk_bf16_f32 v105, v64, v68
	global_store_dwordx4 v[106:107], v[102:105], off nt
	v_lshl_add_u64 v[106:107], v[106:107], 0, s[6:7]
	s_add_i32 s81, s81, s82
	v_cvt_pk_bf16_f32 v102, v37, v45
	v_cvt_pk_bf16_f32 v103, v49, v53
	v_cvt_pk_bf16_f32 v104, v57, v61
	v_cvt_pk_bf16_f32 v105, v65, v69
	global_store_dwordx4 v[106:107], v[102:105], off nt
	v_lshl_add_u64 v[106:107], v[106:107], 0, s[6:7]
	s_nop 0
	v_cvt_pk_bf16_f32 v102, v38, v46
	v_cvt_pk_bf16_f32 v103, v50, v54
	v_cvt_pk_bf16_f32 v104, v58, v62
	v_cvt_pk_bf16_f32 v105, v66, v70
	global_store_dwordx4 v[106:107], v[102:105], off nt
	v_lshl_add_u64 v[106:107], v[106:107], 0, s[6:7]
	s_nop 0
	v_cvt_pk_bf16_f32 v102, v39, v47
	v_cvt_pk_bf16_f32 v103, v51, v55
	v_cvt_pk_bf16_f32 v104, v59, v63
	v_cvt_pk_bf16_f32 v105, v67, v71
	global_store_dwordx4 v[106:107], v[102:105], off nt
	s_andn2_b64 vcc, exec, s[14:15]
	s_xor_b32 s63, s63, 1
	s_cbranch_vccz .LBB0_197
.LBB0_196:
	s_waitcnt lgkmcnt(0)
	v_mov_b64_e32 v[102:103], v[88:89]
	v_mov_b64_e32 v[104:105], v[90:91]
	v_mov_b64_e32 v[106:107], v[92:93]
	v_mov_b64_e32 v[108:109], v[78:79]
	v_mov_b64_e32 v[110:111], v[80:81]
	v_mov_b64_e32 v[112:113], v[82:83]
	v_mov_b64_e32 v[114:115], v[84:85]
	v_mov_b64_e32 v[116:117], v[94:95]
	s_mov_b32 s48, s12
	s_mov_b32 s42, s64
	s_cmp_eq_u32 s42, s60
	s_cbranch_scc0 .LBB0_182
	s_branch .LBB0_183
.LBB0_197:
	s_cmp_gt_i32 s81, 0xffff
	s_cbranch_scc1 .LBB0_200
	v_lshlrev_b32_e32 v0, 2, v202
	v_and_b32_e32 v0, 28, v0
	v_mov_b32_e32 v3, 0
	s_movk_i32 s6, 0x7f
	s_movk_i32 s7, 0x4040
	s_mov_b32 s1, 0
	v_lshlrev_b32_e32 v4, 2, v0
	v_mov_b32_e32 v5, v3
	v_lshlrev_b32_e32 v6, 1, v72
	v_mov_b32_e32 v7, v3

; template <class Epi, class Sched, bool ALIGN_EPI = false, bool SP2 = false>
; __device__ __forceinline__ void gemm_phase(LAS unsigned char* lds, const Gemm g, const Sched& S, const Epi& E) {
;     const int tid = threadIdx.x, wid = __builtin_amdgcn_readfirstlane(tid >> 6), lane = tid & 63, wr = wid >> 2, wc = wid & 3, fr = lane & 15, fq = lane >> 4;
;     const int K = g.K, nt = K / BK;
;     unsigned voffA[2], voffB[2];
; #pragma unroll
;     for (int i = 0; i < 2; ++i) { int R, C; stage_rc(tid * 16 + i * 8192, R, C); const int Rq = Epi::PERM ? perm32(R & 31) : (R & 31); const int Rb = Epi::COLS64 ? (64 * (R >> 5) + Rq) : ((R & ~31) + Rq);
;         voffA[i] = (unsigned)(R * g.lda + C) * 2u; voffB[i] = (unsigned)(Rb * g.ldb + C) * 2u; }
;     const size_t kstep = (size_t)(BK * 2);
;     const size_t hsA = (size_t)HALF * g.lda * 2, hsB = (size_t)(Epi::COLS64 ? 32 : HALF) * g.ldb * 2;
;     const size_t tsA = 2 * hsA, tsB = (size_t)BM * g.ldb * 2;
;     const unsigned ldsw = (unsigned)wid * 1024u;
;     const int aoff = lds_byte(wr * 64 + fr, fq * 8), boff = lds_byte(wc * 32 + fr, fq * 8);
;     ...
;     Unit cur, nxt; int ui = 0;
;     if (!S.next(0, cur)) return;
;     f32x4 acc[2][2][4][2];
; #pragma unroll
;     for (int a = 0; a < 2; ++a)
; #pragma unroll
;         for (int b = 0; b < 2; ++b)
; #pragma unroll
;             for (int m = 0; m < 4; ++m)
; #pragma unroll
;                 for (int n = 0; n < 2; ++n) acc[a][b][m][n] = (f32x4){0.f, 0.f, 0.f, 0.f};
;     bf16x8 At[4][2], B0[2][2], B1[2][2];
;     const char* cA = (const char*)g.A + (size_t)cur.pm * tsA; const char* cB = (const char*)g.Bt + (size_t)cur.pn * tsB;
;     S.a_ready(cur);
;     if constexpr (SP2) {
;         PG8_STAGE(PG8_SB(0, 0), cB, voffB); PG8_STAGE(PG8_SB(0, 1), cB + hsB, voffB); PG8_STAGE(PG8_SA(0, 0), cA, voffA); PG8_STAGE(PG8_SA(0, 1), cA + hsA, voffA);
;         if (wr == 1) PG8_BAR;
;         PG8_WAIT_V(2); PG8_BAR;
;         PG8_STAGE(PG8_SB(1, 0), cB + kstep, voffB); PG8_STAGE(PG8_SA(1, 0), cA + kstep, voffA); PG8_STAGE(PG8_SB(1, 1), cB + hsB + kstep, voffB);
;         PG8_WAIT_V(6); PG8_BAR;
;     } else {
;         PG8_STAGE(PG8_SB(0, 0), cB, voffB); PG8_STAGE(PG8_SA(0, 0), cA, voffA); PG8_STAGE(PG8_SB(0, 1), cB + hsB, voffB); PG8_STAGE(PG8_SA(0, 1), cA + hsA, voffA);
;         if (wr == 1) PG8_BAR;
;         PG8_WAIT_V(4); PG8_BAR;
.LBB0_219:
	s_andn2_b64 vcc, exec, s[0:1]
	s_cbranch_vccnz .LBB0_275
	s_waitcnt vmcnt(0)
	v_lshlrev_b32_e32 v13, 4, v202
	v_and_b32_e32 v0, 32, v202
	v_bfe_u32 v11, v202, 2, 4
	s_waitcnt lgkmcnt(0)
	v_bitop3_b32 v1, v13, v0, 48 bitop3:0x6c
	v_and_b32_e32 v10, 64, v202
	v_lshrrev_b32_e32 v14, 3, v202
	s_movk_i32 s1, 0x70
	v_or_b32_e32 v0, v1, v10
	v_and_or_b32 v2, v14, s1, v11
	v_mul_u32_u24_e32 v2, 0x2080, v2
	v_add_u32_e32 v12, 0x2000, v13
	v_lshrrev_b32_e32 v2, 7, v12
	s_movk_i32 s1, 0xf0
	v_and_or_b32 v2, v2, s1, v11
	s_lshr_b32 s1, s6, 6
	s_ashr_i32 s9, s8, 31
	s_lshr_b32 s0, s6, 8
	s_lshl_b32 s31, s1, 10
	s_lshl_b64 s[4:5], s[8:9], 21
	s_mul_i32 s9, s14, 0x208000
	s_mul_hi_i32 s7, s14, 0x208000
	s_add_u32 s66, s74, s9
	s_addc_u32 s67, s75, s7
	s_add_i32 s41, s31, 0
	s_add_i32 m0, s41, 0x10000
	v_mul_u32_u24_e32 v2, 0x2080, v2
	v_lshrrev_b32_e32 v247, 6, v202
	v_bfe_u32 v242, v202, 3, 3
	v_and_b32_e32 v243, 7, v202
	v_xor_b32_e32 v243, v243, v242
	v_lshlrev_b32_e32 v243, 4, v243
	v_lshl_add_u32 v244, v247, 3, v242
	v_mul_u32_u24_e32 v244, 0x2000, v244
	v_add_u32_e32 v164, v244, v243
	v_add_u32_e32 v168, 0x80000, v164
	v_lshl_add_u32 v245, v247, 3, v242
	v_mul_u32_u24_e32 v245, 0x2080, v245
	v_add_u32_e32 v166, v245, v243
	v_add_u32_e32 v170, 0x82000, v166
	global_load_lds_dwordx4 v166, s[66:67]
	s_add_i32 m0, s41, 0x12000
	s_add_u32 s16, s66, 0x104000
	global_load_lds_dwordx4 v170, s[66:67]
	s_addc_u32 s17, s67, 0
	s_add_i32 m0, s41, 0x14000
	v_mov_b32_e32 v0, 0
	global_load_lds_dwordx4 v166, s[16:17]
	s_add_i32 m0, s41, 0x16000
	s_add_u32 s64, s20, s4
	s_addc_u32 s65, s21, s5
	s_add_i32 s68, s41, 0x2000
	global_load_lds_dwordx4 v170, s[16:17]
	s_mov_b32 m0, s41
	s_add_u32 s4, s64, 0x100000
	global_load_lds_dwordx4 v164, s[64:65]
	s_mov_b32 m0, s68
	s_addc_u32 s5, s65, 0
	s_add_i32 s69, s41, 0x4000
	global_load_lds_dwordx4 v168, s[64:65]
	s_mov_b32 m0, s69
	s_add_i32 s70, s41, 0x6000
	global_load_lds_dwordx4 v164, s[4:5]
	s_mov_b32 m0, s70
	v_mov_b32_e32 v167, v0
	global_load_lds_dwordx4 v168, s[4:5]
	v_mov_b32_e32 v171, v0
	v_mov_b32_e32 v165, v0
	v_mov_b32_e32 v169, v0
	s_cmp_eq_u32 s0, 1
	s_movk_i32 s71, 0x2080
	s_mov_b32 s72, 0
	v_lshl_add_u64 v[8:9], s[66:67], 0, v[166:167]
	v_lshl_add_u64 v[6:7], s[66:67], 0, v[170:171]
	v_lshl_add_u64 v[4:5], s[64:65], 0, v[164:165]
	v_lshl_add_u64 v[2:3], s[64:65], 0, v[168:169]
	s_cselect_b64 s[16:17], -1, 0
	s_cmp_lg_u32 s0, 1
	s_movk_i32 s73, 0x4000
	s_cbranch_scc1 .LBB0_222
	s_barrier
.LBB0_222:
	s_lshl_b32 s4, s33, 11
	s_lshl_b32 s78, s0, 6
	s_lshl_b32 s5, s0, 13
	s_lshl_b32 s0, s1, 5
	s_mov_b64 s[24:25], 0x80
	s_add_i32 s4, s4, 0
	s_and_b32 s7, s0, 0x60
	s_add_i32 m0, s41, 0x18000
	v_lshl_add_u64 v[8:9], v[8:9], 0, s[24:25]
	s_add_i32 s4, s4, 0x20000
	s_lshl_b32 s9, s7, 7
	s_waitcnt vmcnt(2)
	s_barrier
	global_load_lds_dwordx4 v[8:9], off
	v_lshl_add_u64 v[6:7], v[6:7], 0, s[24:25]
	s_add_i32 m0, s41, 0x1a000
	s_add_i32 s81, s41, 0x8000
	s_add_i32 s82, s41, 0xa000
	global_load_lds_dwordx4 v[6:7], off
	v_lshl_add_u64 v[4:5], v[4:5], 0, s[24:25]
	s_mov_b32 m0, s81
	s_add_u32 s0, s66, 0x104080
	global_load_lds_dwordx4 v[4:5], off
	v_lshl_add_u64 v[2:3], v[2:3], 0, s[24:25]
	s_mov_b32 m0, s82
	s_addc_u32 s1, s67, 0
	global_load_lds_dwordx4 v[2:3], off
	s_add_i32 m0, s41, 0x1c000
	v_lshl_add_u64 v[2:3], s[0:1], 0, v[166:167]
	global_load_lds_dwordx4 v[2:3], off
	v_lshl_add_u64 v[2:3], s[0:1], 0, v[170:171]
	s_add_i32 m0, s41, 0x1e000
	v_bfe_u32 v193, v202, 4, 2
	global_load_lds_dwordx4 v[2:3], off
	v_and_b32_e32 v192, 15, v202
	v_lshlrev_b32_e32 v3, 4, v193
	v_lshlrev_b32_e32 v5, 2, v202
	v_lshlrev_b32_e32 v6, 6, v202
	s_movk_i32 s0, 0x3c0
	v_lshl_or_b32 v4, v192, 6, v3
	v_and_b32_e32 v5, 32, v5
	v_and_or_b32 v3, v6, s0, v3
	v_lshrrev_b32_e32 v2, 4, v202
	v_bitop3_b32 v4, v4, s5, v5 bitop3:0xde
	v_bitop3_b32 v194, s9, v3, v5 bitop3:0xf6
	v_and_b32_e32 v5, 7, v202
	v_bitop3_b32 v2, v2, v5, 3 bitop3:0x6c
	v_bfe_u32 v3, v202, 3, 3
	v_lshlrev_b32_e32 v7, 4, v2
	v_bitop3_b32 v2, v193, v5, 4 bitop3:0x36
	v_bitop3_b32 v6, v14, v202, 7 bitop3:0x28
	v_or_b32_e32 v195, s78, v3
	v_lshlrev_b32_e32 v8, 4, v2
	v_lshl_add_u32 v14, v3, 7, s4
	v_and_b32_e32 v2, 48, v13
	v_mov_b32_e32 v3, v0
	v_lshl_add_u64 v[172:173], s[38:39], 0, v[2:3]
	v_lshlrev_b32_e32 v2, 10, v202
	v_cmp_eq_u32_e64 s[0:1], 0, v5
	v_lshl_or_b32 v196, v5, 2, s7
	v_and_b32_e32 v2, 0xe0000, v2
	v_lshlrev_b32_e32 v5, 13, v11
	v_or3_b32 v2, v1, v2, v5
	v_lshl_add_u32 v9, v192, 7, s4
	v_add_u32_e32 v2, v2, v10
	s_mov_b64 s[4:5], 0x100080
	v_add_u32_e32 v174, 0x100080, v164
	v_mov_b32_e32 v175, 0
	v_lshlrev_b32_e32 v2, 6, v12
	v_and_b32_e32 v2, 0x1e0000, v2
	s_waitcnt vmcnt(6)
	v_or3_b32 v1, v1, v2, v5
	s_cmpk_lt_u32 s6, 0x100
	v_lshlrev_b32_e32 v6, 4, v6
	v_add_u32_e32 v2, v1, v10
	v_mbcnt_lo_u32_b32 v1, -1, 0
	s_cselect_b64 s[26:27], -1, 0
	s_ashr_i32 s83, s3, 31
	s_ashr_i32 s84, s2, 31
	v_add_u32_e32 v176, 0x100080, v168
	v_mov_b32_e32 v177, 0
	v_mov_b64_e32 v[178:179], 0x400
	v_mov_b64_e32 v[180:181], 0x3ff
	s_movk_i32 s85, 0x1000
	s_mov_b32 s30, 0x3a000000
	s_mov_b32 s40, 0x358637bd
	s_mov_b32 s86, 0xf800000
	v_mov_b32_e32 v197, 0x260
	s_mov_b64 s[42:43], 0x1000
	s_mov_b64 s[44:45], 0x1800
	s_mov_b64 s[46:47], 0x4000
	s_mov_b64 s[48:49], 0x4800
	s_mov_b64 s[50:51], 0x5000
	s_movk_i32 s87, 0x5000
	s_mov_b64 s[56:57], 0x5800
	s_add_i32 s88, 0, 0x10000
	s_add_i32 s89, 0, 0x14000
	v_add_u32_e32 v198, 0, v4
	v_and_b32_e32 v242, 15, v202
	v_bfe_u32 v243, v202, 4, 2
	v_and_b32_e32 v244, 7, v242
	v_xor_b32_e32 v243, v243, v244
	v_lshlrev_b32_e32 v243, 4, v243
	v_lshl_add_u32 v243, v244, 7, v243
	v_lshrrev_b32_e32 v244, 3, v242
	v_lshl_add_u32 v243, v244, 10, v243
	v_lshrrev_b32_e32 v247, 6, v202
	v_lshrrev_b32_e32 v244, 2, v247
	v_lshl_add_u32 v198, v244, 13, v243
	v_and_b32_e32 v244, 3, v247
	v_lshl_add_u32 v194, v244, 12, v243
	v_xor_b32_e32 v250, 64, v198
	v_mov_b32_e32 v199, 0x358637bd
	v_mbcnt_hi_u32_b32 v200, -1, v1
	v_add_u32_e32 v201, v9, v7
	v_add_u32_e32 v205, v9, v8
	v_add_u32_e32 v206, v14, v6
	s_barrier
	s_branch .LBB0_225

; #define PG8_STAGE(bufoff, gbase, voff) do { _Pragma("unroll") for (int _i = 0; _i < 2; ++_i) \
;         __builtin_amdgcn_global_load_lds((const unsigned*)((const char*)(gbase) + (voff)[_i]), (LAS unsigned*)(lds + (bufoff) + ldsw + _i * 8192), 16, 0, 0); } while (0)
; #define PG8_LDA(dst, b, h) do { _Pragma("unroll") for (int m = 0; m < 4; ++m) _Pragma("unroll") for (int k = 0; k < 2; ++k) dst[m][k] = *(const LAS bf16x8*)(lds + PG8_SA(b, h) + aoff + m * 2048 + k * 1024); } while (0)
; #define PG8_LDB(dst, b, h) do { _Pragma("unroll") for (int n = 0; n < 2; ++n) _Pragma("unroll") for (int k = 0; k < 2; ++k) dst[n][k] = *(const LAS bf16x8*)(lds + PG8_SB(b, h) + boff + n * 2048 + k * 1024); } while (0)
; #define PG8_MMA(ai, bj, At, Bt) do { __builtin_amdgcn_s_setprio(3); _Pragma("unroll") for (int m = 0; m < 4; ++m) _Pragma("unroll") for (int n = 0; n < 2; ++n) _Pragma("unroll") for (int k = 0; k < 2; ++k) \
;         acc[ai][bj][m][n] = __builtin_amdgcn_mfma_f32_16x16x32_bf16(Bt[n][k], At[m][k], acc[ai][bj][m][n], 0, 0, 0); __builtin_amdgcn_s_setprio(0); } while (0)
; #define PG8_WAIT_V(n) asm volatile("s_waitcnt vmcnt(" #n ")" ::: "memory")
; #define PG8_WAIT_L(n) asm volatile("s_waitcnt lgkmcnt(" #n ")" ::: "memory")
; #define PG8_BAR __builtin_amdgcn_s_barrier()
; #define PG8_SCHED __builtin_amdgcn_sched_barrier(0)
; template <class Epi, class Sched, bool ALIGN_EPI = false, bool SP2 = false>
; __device__ __forceinline__ void gemm_phase(LAS unsigned char* lds, const Gemm g, const Sched& S, const Epi& E) {
;     ...
;             PG8_LDB(B0, 0, 0); PG8_LDB(B1, 0, 1); PG8_SCHED; PG8_LDA(At, 0, 0); PG8_STAGE(PG8_SA(1, 1), a1 + hsA, voffA);
;             PG8_WAIT_V(8); PG8_WAIT_L(0); PG8_BAR; PG8_MMA(0, 0, At, B0); PG8_MMA(0, 1, At, B1); PG8_BAR; PG8_SCHED;
;             PG8_LDA(At, 0, 1); PG8_STAGE(PG8_SB(0, 0), b2, voffB); PG8_STAGE(PG8_SB(0, 1), b2 + hsB, voffB); PG8_STAGE(PG8_SA(0, 0), a2, voffA);
.LBB0_234:
	v_add_u32_e32 v1, s88, v194
	v_xor_b32_e32 v253, 64, v1
	ds_read_b128 v[84:87], v1
	ds_read_b128 v[96:99], v253
	ds_read_b128 v[140:143], v1 offset:2048
	ds_read_b128 v[144:147], v253 offset:2048
	v_add_u32_e32 v1, s89, v194
	v_xor_b32_e32 v253, 64, v1
	s_add_u32 s4, s64, s66
	ds_read_b128 v[152:155], v1
	ds_read_b128 v[156:159], v253
	ds_read_b128 v[160:163], v1 offset:2048
	ds_read_b128 v[182:185], v253 offset:2048
	s_addc_u32 s5, s65, s67
	s_add_u32 s4, s4, 0x100
	s_addc_u32 s5, s5, 0
	s_add_u32 s96, s93, s66
	s_addc_u32 s97, s94, s67
	s_cmpk_eq_i32 s66, 0x1f00
	s_cselect_b32 s9, s59, s5
	s_cselect_b32 s8, s91, s4
	s_cselect_b32 s5, s61, s97
	s_cselect_b32 s4, s60, s96
	v_lshl_add_u64 v[2:3], v[148:149], 0, s[66:67]
	s_add_i32 m0, s41, 0xc000
	ds_read_b128 v[186:189], v198
	ds_read_b128 v[208:211], v250
	ds_read_b128 v[212:215], v198 offset:2048
	ds_read_b128 v[216:219], v250 offset:2048
	ds_read_b128 v[220:223], v198 offset:4096
	ds_read_b128 v[224:227], v250 offset:4096
	ds_read_b128 v[228:231], v198 offset:6144
	ds_read_b128 v[232:235], v250 offset:6144
	global_load_lds_dwordx4 v[2:3], off
	v_lshl_add_u64 v[2:3], v[150:151], 0, s[66:67]
	s_add_i32 m0, s41, 0xe000
	s_nop 0
	global_load_lds_dwordx4 v[2:3], off
	s_waitcnt vmcnt(8)
	s_waitcnt lgkmcnt(0)
	s_barrier
	s_setprio 3
	s_waitcnt lgkmcnt(0)
	v_mfma_f32_16x16x32_bf16 v[136:139], v[84:87], v[186:189], v[136:139]
	v_mfma_f32_16x16x32_bf16 v[132:135], v[140:143], v[186:189], v[132:135]
	v_mfma_f32_16x16x32_bf16 v[120:123], v[84:87], v[212:215], v[120:123]
	v_mfma_f32_16x16x32_bf16 v[116:119], v[140:143], v[212:215], v[116:119]
	v_mfma_f32_16x16x32_bf16 v[104:107], v[84:87], v[220:223], v[104:107]
	v_mfma_f32_16x16x32_bf16 v[100:103], v[140:143], v[220:223], v[100:103]
	v_mfma_f32_16x16x32_bf16 v[80:83], v[84:87], v[228:231], v[80:83]
	v_mfma_f32_16x16x32_bf16 v[76:79], v[140:143], v[228:231], v[76:79]
	v_mfma_f32_16x16x32_bf16 v[136:139], v[96:99], v[208:211], v[136:139]
	v_mfma_f32_16x16x32_bf16 v[132:135], v[144:147], v[208:211], v[132:135]
	v_mfma_f32_16x16x32_bf16 v[120:123], v[96:99], v[216:219], v[120:123]
	v_mfma_f32_16x16x32_bf16 v[116:119], v[144:147], v[216:219], v[116:119]
	v_mfma_f32_16x16x32_bf16 v[104:107], v[96:99], v[224:227], v[104:107]
	v_mfma_f32_16x16x32_bf16 v[100:103], v[144:147], v[224:227], v[100:103]
	v_mfma_f32_16x16x32_bf16 v[80:83], v[96:99], v[232:235], v[80:83]
	v_mfma_f32_16x16x32_bf16 v[76:79], v[144:147], v[232:235], v[76:79]
	s_setprio 0
	s_setprio 3
	v_mfma_f32_16x16x32_bf16 v[128:131], v[152:155], v[186:189], v[128:131]
	v_mfma_f32_16x16x32_bf16 v[124:127], v[160:163], v[186:189], v[124:127]
	v_mfma_f32_16x16x32_bf16 v[112:115], v[152:155], v[212:215], v[112:115]
	v_mfma_f32_16x16x32_bf16 v[108:111], v[160:163], v[212:215], v[108:111]
	v_mfma_f32_16x16x32_bf16 v[92:95], v[152:155], v[220:223], v[92:95]
	v_mfma_f32_16x16x32_bf16 v[88:91], v[160:163], v[220:223], v[88:91]
	v_mfma_f32_16x16x32_bf16 v[72:75], v[152:155], v[228:231], v[72:75]
	v_mfma_f32_16x16x32_bf16 v[68:71], v[160:163], v[228:231], v[68:71]
	v_mfma_f32_16x16x32_bf16 v[128:131], v[156:159], v[208:211], v[128:131]
	v_mfma_f32_16x16x32_bf16 v[124:127], v[182:185], v[208:211], v[124:127]
	v_mfma_f32_16x16x32_bf16 v[112:115], v[156:159], v[216:219], v[112:115]
	v_mfma_f32_16x16x32_bf16 v[108:111], v[182:185], v[216:219], v[108:111]
	v_mfma_f32_16x16x32_bf16 v[92:95], v[156:159], v[224:227], v[92:95]
	v_mfma_f32_16x16x32_bf16 v[88:91], v[182:185], v[224:227], v[88:91]
	v_mfma_f32_16x16x32_bf16 v[72:75], v[156:159], v[232:235], v[72:75]
	v_mfma_f32_16x16x32_bf16 v[68:71], v[182:185], v[232:235], v[68:71]
	s_setprio 0
	s_barrier
	s_add_i32 s96, s88, s31
	v_lshl_add_u64 v[190:191], s[4:5], 0, v[166:167]
	s_mov_b32 m0, s96
	ds_read_b128 v[186:189], v198 offset:16384
	ds_read_b128 v[208:211], v250 offset:16384
	ds_read_b128 v[212:215], v198 offset:18432
	ds_read_b128 v[216:219], v250 offset:18432
	ds_read_b128 v[220:223], v198 offset:20480
	ds_read_b128 v[224:227], v250 offset:20480
	ds_read_b128 v[228:231], v198 offset:22528
	ds_read_b128 v[232:235], v250 offset:22528
	global_load_lds_dwordx4 v[190:191], off
	s_add_i32 m0, s96, 0x2000
	s_add_u32 s96, s4, 0x104000
	v_lshl_add_u64 v[236:237], s[4:5], 0, v[170:171]
	s_addc_u32 s97, s5, 0
	s_add_i32 s98, s89, s31
	global_load_lds_dwordx4 v[236:237], off
	v_lshl_add_u64 v[2:3], s[96:97], 0, v[166:167]
	s_mov_b32 m0, s98
	v_lshl_add_u64 v[238:239], s[8:9], 0, v[164:165]
	global_load_lds_dwordx4 v[2:3], off
	v_lshl_add_u64 v[2:3], s[96:97], 0, v[170:171]
	s_add_i32 m0, s98, 0x2000
	v_lshl_add_u64 v[240:241], s[8:9], 0, v[168:169]
	global_load_lds_dwordx4 v[2:3], off
	s_mov_b32 m0, s41
	s_nop 0
	global_load_lds_dwordx4 v[238:239], off
	s_mov_b32 m0, s68
	s_nop 0
	global_load_lds_dwordx4 v[240:241], off
	s_waitcnt vmcnt(8)
	s_waitcnt lgkmcnt(0)
	s_barrier
; #define PG8_STAGE(bufoff, gbase, voff) do { _Pragma("unroll") for (int _i = 0; _i < 2; ++_i) \
;         __builtin_amdgcn_global_load_lds((const unsigned*)((const char*)(gbase) + (voff)[_i]), (LAS unsigned*)(lds + (bufoff) + ldsw + _i * 8192), 16, 0, 0); } while (0)
; #define PG8_LDA(dst, b, h) do { _Pragma("unroll") for (int m = 0; m < 4; ++m) _Pragma("unroll") for (int k = 0; k < 2; ++k) dst[m][k] = *(const LAS bf16x8*)(lds + PG8_SA(b, h) + aoff + m * 2048 + k * 1024); } while (0)
; #define PG8_LDB(dst, b, h) do { _Pragma("unroll") for (int n = 0; n < 2; ++n) _Pragma("unroll") for (int k = 0; k < 2; ++k) dst[n][k] = *(const LAS bf16x8*)(lds + PG8_SB(b, h) + boff + n * 2048 + k * 1024); } while (0)
; #define PG8_MMA(ai, bj, At, Bt) do { __builtin_amdgcn_s_setprio(3); _Pragma("unroll") for (int m = 0; m < 4; ++m) _Pragma("unroll") for (int n = 0; n < 2; ++n) _Pragma("unroll") for (int k = 0; k < 2; ++k) \
;         acc[ai][bj][m][n] = __builtin_amdgcn_mfma_f32_16x16x32_bf16(Bt[n][k], At[m][k], acc[ai][bj][m][n], 0, 0, 0); __builtin_amdgcn_s_setprio(0); } while (0)
; #define PG8_WAIT_V(n) asm volatile("s_waitcnt vmcnt(" #n ")" ::: "memory")
; #define PG8_WAIT_L(n) asm volatile("s_waitcnt lgkmcnt(" #n ")" ::: "memory")
; #define PG8_BAR __builtin_amdgcn_s_barrier()
; #define PG8_SCHED __builtin_amdgcn_sched_barrier(0)
; template <class Epi, class Sched, bool ALIGN_EPI = false, bool SP2 = false>
; __device__ __forceinline__ void gemm_phase(LAS unsigned char* lds, const Gemm g, const Sched& S, const Epi& E) {
;     ...
;             PG8_WAIT_V(8); PG8_WAIT_L(0); PG8_BAR; PG8_MMA(1, 0, At, B0); PG8_MMA(1, 1, At, B1); PG8_BAR; PG8_SCHED;
;             PG8_LDB(B0, 1, 0); PG8_LDB(B1, 1, 1); PG8_SCHED; PG8_LDA(At, 1, 0); PG8_STAGE(PG8_SA(0, 1), a2 + hsA, voffA);
;             PG8_WAIT_V(8); PG8_WAIT_L(0); PG8_BAR; PG8_MMA(0, 0, At, B0); PG8_MMA(0, 1, At, B1); PG8_BAR; PG8_SCHED;
	s_setprio 3
	s_waitcnt lgkmcnt(0)
	v_mfma_f32_16x16x32_bf16 v[64:67], v[84:87], v[186:189], v[64:67]
	v_mfma_f32_16x16x32_bf16 v[60:63], v[140:143], v[186:189], v[60:63]
	v_mfma_f32_16x16x32_bf16 v[48:51], v[84:87], v[212:215], v[48:51]
	v_mfma_f32_16x16x32_bf16 v[44:47], v[140:143], v[212:215], v[44:47]
	v_mfma_f32_16x16x32_bf16 v[32:35], v[84:87], v[220:223], v[32:35]
	v_mfma_f32_16x16x32_bf16 v[28:31], v[140:143], v[220:223], v[28:31]
	v_mfma_f32_16x16x32_bf16 v[16:19], v[84:87], v[228:231], v[16:19]
	v_mfma_f32_16x16x32_bf16 v[12:15], v[140:143], v[228:231], v[12:15]
	v_mfma_f32_16x16x32_bf16 v[64:67], v[96:99], v[208:211], v[64:67]
	v_mfma_f32_16x16x32_bf16 v[60:63], v[144:147], v[208:211], v[60:63]
	v_mfma_f32_16x16x32_bf16 v[48:51], v[96:99], v[216:219], v[48:51]
	v_mfma_f32_16x16x32_bf16 v[44:47], v[144:147], v[216:219], v[44:47]
	v_mfma_f32_16x16x32_bf16 v[32:35], v[96:99], v[224:227], v[32:35]
	v_mfma_f32_16x16x32_bf16 v[28:31], v[144:147], v[224:227], v[28:31]
	v_mfma_f32_16x16x32_bf16 v[16:19], v[96:99], v[232:235], v[16:19]
	v_mfma_f32_16x16x32_bf16 v[12:15], v[144:147], v[232:235], v[12:15]
	s_setprio 0
	s_setprio 3
	v_mfma_f32_16x16x32_bf16 v[56:59], v[152:155], v[186:189], v[56:59]
	v_mfma_f32_16x16x32_bf16 v[52:55], v[160:163], v[186:189], v[52:55]
	v_mfma_f32_16x16x32_bf16 v[40:43], v[152:155], v[212:215], v[40:43]
	v_mfma_f32_16x16x32_bf16 v[36:39], v[160:163], v[212:215], v[36:39]
	v_mfma_f32_16x16x32_bf16 v[24:27], v[152:155], v[220:223], v[24:27]
	v_mfma_f32_16x16x32_bf16 v[20:23], v[160:163], v[220:223], v[20:23]
	v_mfma_f32_16x16x32_bf16 v[8:11], v[152:155], v[228:231], v[8:11]
	v_mfma_f32_16x16x32_bf16 v[2:5], v[160:163], v[228:231], v[4:7]
	v_mfma_f32_16x16x32_bf16 v[56:59], v[156:159], v[208:211], v[56:59]
	v_mfma_f32_16x16x32_bf16 v[52:55], v[182:185], v[208:211], v[52:55]
	v_mfma_f32_16x16x32_bf16 v[40:43], v[156:159], v[216:219], v[40:43]
	v_mfma_f32_16x16x32_bf16 v[36:39], v[182:185], v[216:219], v[36:39]
	v_mfma_f32_16x16x32_bf16 v[24:27], v[156:159], v[224:227], v[24:27]
	v_mfma_f32_16x16x32_bf16 v[20:23], v[182:185], v[224:227], v[20:23]
	v_mfma_f32_16x16x32_bf16 v[8:11], v[156:159], v[232:235], v[8:11]
	v_mfma_f32_16x16x32_bf16 v[2:5], v[182:185], v[232:235], v[2:5]
	s_setprio 0
	s_barrier
	s_add_i32 s96, 0, 0x18000
	v_add_u32_e32 v1, s96, v194
	v_xor_b32_e32 v253, 64, v1
	s_add_i32 s97, 0, 0x1c000
	ds_read_b128 v[84:87], v1
	ds_read_b128 v[96:99], v253
	ds_read_b128 v[140:143], v1 offset:2048
	ds_read_b128 v[144:147], v253 offset:2048
	v_add_u32_e32 v1, s97, v194
	v_xor_b32_e32 v253, 64, v1
	ds_read_b128 v[152:155], v1
	ds_read_b128 v[156:159], v253
	ds_read_b128 v[160:163], v1 offset:2048
	ds_read_b128 v[182:185], v253 offset:2048
	s_add_u32 s8, s8, 0x100000
	s_addc_u32 s9, s9, 0
	s_mov_b32 m0, s69
	v_lshl_add_u64 v[6:7], s[8:9], 0, v[164:165]
	ds_read_b128 v[186:189], v198 offset:32768
	ds_read_b128 v[208:211], v250 offset:32768
	ds_read_b128 v[212:215], v198 offset:34816
	ds_read_b128 v[216:219], v250 offset:34816
	ds_read_b128 v[220:223], v198 offset:36864
	ds_read_b128 v[224:227], v250 offset:36864
	ds_read_b128 v[228:231], v198 offset:38912
	ds_read_b128 v[232:235], v250 offset:38912
	global_load_lds_dwordx4 v[6:7], off
	v_lshl_add_u64 v[6:7], s[8:9], 0, v[168:169]
	s_mov_b32 m0, s70
	s_nop 0
	global_load_lds_dwordx4 v[6:7], off
	s_waitcnt vmcnt(8)
	s_waitcnt lgkmcnt(0)
	s_barrier
	s_setprio 3
	s_waitcnt lgkmcnt(0)
	v_mfma_f32_16x16x32_bf16 v[136:139], v[84:87], v[186:189], v[136:139]
	v_mfma_f32_16x16x32_bf16 v[132:135], v[140:143], v[186:189], v[132:135]
	v_mfma_f32_16x16x32_bf16 v[120:123], v[84:87], v[212:215], v[120:123]
	v_mfma_f32_16x16x32_bf16 v[116:119], v[140:143], v[212:215], v[116:119]
	v_mfma_f32_16x16x32_bf16 v[104:107], v[84:87], v[220:223], v[104:107]
	v_mfma_f32_16x16x32_bf16 v[100:103], v[140:143], v[220:223], v[100:103]
	v_mfma_f32_16x16x32_bf16 v[80:83], v[84:87], v[228:231], v[80:83]
	v_mfma_f32_16x16x32_bf16 v[76:79], v[140:143], v[228:231], v[76:79]
	v_mfma_f32_16x16x32_bf16 v[136:139], v[96:99], v[208:211], v[136:139]
	v_mfma_f32_16x16x32_bf16 v[132:135], v[144:147], v[208:211], v[132:135]
	v_mfma_f32_16x16x32_bf16 v[120:123], v[96:99], v[216:219], v[120:123]
	v_mfma_f32_16x16x32_bf16 v[116:119], v[144:147], v[216:219], v[116:119]
	v_mfma_f32_16x16x32_bf16 v[104:107], v[96:99], v[224:227], v[104:107]
	v_mfma_f32_16x16x32_bf16 v[100:103], v[144:147], v[224:227], v[100:103]
	v_mfma_f32_16x16x32_bf16 v[80:83], v[96:99], v[232:235], v[80:83]
	v_mfma_f32_16x16x32_bf16 v[76:79], v[144:147], v[232:235], v[76:79]
	s_setprio 0
	s_setprio 3
	v_mfma_f32_16x16x32_bf16 v[128:131], v[152:155], v[186:189], v[128:131]
	v_mfma_f32_16x16x32_bf16 v[124:127], v[160:163], v[186:189], v[124:127]
	v_mfma_f32_16x16x32_bf16 v[112:115], v[152:155], v[212:215], v[112:115]
	v_mfma_f32_16x16x32_bf16 v[108:111], v[160:163], v[212:215], v[108:111]
	v_mfma_f32_16x16x32_bf16 v[92:95], v[152:155], v[220:223], v[92:95]
	v_mfma_f32_16x16x32_bf16 v[88:91], v[160:163], v[220:223], v[88:91]
	v_mfma_f32_16x16x32_bf16 v[72:75], v[152:155], v[228:231], v[72:75]
	v_mfma_f32_16x16x32_bf16 v[68:71], v[160:163], v[228:231], v[68:71]
	v_mfma_f32_16x16x32_bf16 v[128:131], v[156:159], v[208:211], v[128:131]
	v_mfma_f32_16x16x32_bf16 v[124:127], v[182:185], v[208:211], v[124:127]
	v_mfma_f32_16x16x32_bf16 v[112:115], v[156:159], v[216:219], v[112:115]
	v_mfma_f32_16x16x32_bf16 v[108:111], v[182:185], v[216:219], v[108:111]
	v_mfma_f32_16x16x32_bf16 v[92:95], v[156:159], v[224:227], v[92:95]
	v_mfma_f32_16x16x32_bf16 v[88:91], v[182:185], v[224:227], v[88:91]
	v_mfma_f32_16x16x32_bf16 v[72:75], v[156:159], v[232:235], v[72:75]
	v_mfma_f32_16x16x32_bf16 v[68:71], v[182:185], v[232:235], v[68:71]
	s_setprio 0
	s_barrier
; #define PG8_STAGE(bufoff, gbase, voff) do { _Pragma("unroll") for (int _i = 0; _i < 2; ++_i) \
;         __builtin_amdgcn_global_load_lds((const unsigned*)((const char*)(gbase) + (voff)[_i]), (LAS unsigned*)(lds + (bufoff) + ldsw + _i * 8192), 16, 0, 0); } while (0)
; #define PG8_LDA(dst, b, h) do { _Pragma("unroll") for (int m = 0; m < 4; ++m) _Pragma("unroll") for (int k = 0; k < 2; ++k) dst[m][k] = *(const LAS bf16x8*)(lds + PG8_SA(b, h) + aoff + m * 2048 + k * 1024); } while (0)
; #define PG8_MMA(ai, bj, At, Bt) do { __builtin_amdgcn_s_setprio(3); _Pragma("unroll") for (int m = 0; m < 4; ++m) _Pragma("unroll") for (int n = 0; n < 2; ++n) _Pragma("unroll") for (int k = 0; k < 2; ++k) \
;         acc[ai][bj][m][n] = __builtin_amdgcn_mfma_f32_16x16x32_bf16(Bt[n][k], At[m][k], acc[ai][bj][m][n], 0, 0, 0); __builtin_amdgcn_s_setprio(0); } while (0)
; #define PG8_WAIT_V(n) asm volatile("s_waitcnt vmcnt(" #n ")" ::: "memory")
; #define PG8_WAIT_L(n) asm volatile("s_waitcnt lgkmcnt(" #n ")" ::: "memory")
; #define PG8_BAR __builtin_amdgcn_s_barrier()
; #define PG8_SCHED __builtin_amdgcn_sched_barrier(0)
; template <class Epi, class Sched, bool ALIGN_EPI = false, bool SP2 = false>
; __device__ __forceinline__ void gemm_phase(LAS unsigned char* lds, const Gemm g, const Sched& S, const Epi& E) {
;     ...
;             PG8_LDA(At, 1, 1); PG8_STAGE(PG8_SB(1, 0), b3, voffB); PG8_STAGE(PG8_SB(1, 1), b3 + hsB, voffB); PG8_STAGE(PG8_SA(1, 0), a3, voffA);
;             PG8_WAIT_V(8); PG8_WAIT_L(0); PG8_BAR; PG8_MMA(1, 0, At, B0); PG8_MMA(1, 1, At, B1); PG8_BAR; PG8_SCHED;
	s_add_i32 s8, s96, s31
	v_lshl_add_u64 v[6:7], v[190:191], 0, s[24:25]
	s_mov_b32 m0, s8
	ds_read_b128 v[186:189], v198 offset:49152
	ds_read_b128 v[208:211], v250 offset:49152
	ds_read_b128 v[212:215], v198 offset:51200
	ds_read_b128 v[216:219], v250 offset:51200
	ds_read_b128 v[220:223], v198 offset:53248
	ds_read_b128 v[224:227], v250 offset:53248
	ds_read_b128 v[228:231], v198 offset:55296
	ds_read_b128 v[232:235], v250 offset:55296
	global_load_lds_dwordx4 v[6:7], off
	s_add_i32 m0, s8, 0x2000
	s_add_u32 s4, s4, 0x104080
	v_lshl_add_u64 v[6:7], v[236:237], 0, s[24:25]
	s_addc_u32 s5, s5, 0
	s_add_i32 s8, s97, s31
	global_load_lds_dwordx4 v[6:7], off
	v_lshl_add_u64 v[6:7], s[4:5], 0, v[166:167]
	s_mov_b32 m0, s8
	s_nop 0
	global_load_lds_dwordx4 v[6:7], off
	v_lshl_add_u64 v[6:7], s[4:5], 0, v[170:171]
	s_add_i32 m0, s8, 0x2000
	s_nop 0
	global_load_lds_dwordx4 v[6:7], off
	v_lshl_add_u64 v[6:7], v[238:239], 0, s[24:25]
	s_mov_b32 m0, s81
	s_nop 0
	global_load_lds_dwordx4 v[6:7], off
	v_lshl_add_u64 v[6:7], v[240:241], 0, s[24:25]
	s_mov_b32 m0, s82
	s_nop 0
	global_load_lds_dwordx4 v[6:7], off
	s_waitcnt vmcnt(8)
	s_waitcnt lgkmcnt(0)
	s_barrier
	s_setprio 3
	s_waitcnt lgkmcnt(0)
	v_mfma_f32_16x16x32_bf16 v[64:67], v[84:87], v[186:189], v[64:67]
	v_mfma_f32_16x16x32_bf16 v[60:63], v[140:143], v[186:189], v[60:63]
	v_mfma_f32_16x16x32_bf16 v[48:51], v[84:87], v[212:215], v[48:51]
	v_mfma_f32_16x16x32_bf16 v[44:47], v[140:143], v[212:215], v[44:47]
	v_mfma_f32_16x16x32_bf16 v[32:35], v[84:87], v[220:223], v[32:35]
	v_mfma_f32_16x16x32_bf16 v[28:31], v[140:143], v[220:223], v[28:31]
	v_mfma_f32_16x16x32_bf16 v[16:19], v[84:87], v[228:231], v[16:19]
	v_mfma_f32_16x16x32_bf16 v[12:15], v[140:143], v[228:231], v[12:15]
	v_mfma_f32_16x16x32_bf16 v[64:67], v[96:99], v[208:211], v[64:67]
	v_mfma_f32_16x16x32_bf16 v[60:63], v[144:147], v[208:211], v[60:63]
	v_mfma_f32_16x16x32_bf16 v[48:51], v[96:99], v[216:219], v[48:51]
	v_mfma_f32_16x16x32_bf16 v[44:47], v[144:147], v[216:219], v[44:47]
	v_mfma_f32_16x16x32_bf16 v[32:35], v[96:99], v[224:227], v[32:35]
	v_mfma_f32_16x16x32_bf16 v[28:31], v[144:147], v[224:227], v[28:31]
	v_mfma_f32_16x16x32_bf16 v[16:19], v[96:99], v[232:235], v[16:19]
	v_mfma_f32_16x16x32_bf16 v[12:15], v[144:147], v[232:235], v[12:15]
	s_setprio 0
	s_setprio 3
	v_mfma_f32_16x16x32_bf16 v[56:59], v[152:155], v[186:189], v[56:59]
	v_mfma_f32_16x16x32_bf16 v[52:55], v[160:163], v[186:189], v[52:55]
	v_mfma_f32_16x16x32_bf16 v[40:43], v[152:155], v[212:215], v[40:43]
	v_mfma_f32_16x16x32_bf16 v[36:39], v[160:163], v[212:215], v[36:39]
	v_mfma_f32_16x16x32_bf16 v[24:27], v[152:155], v[220:223], v[24:27]
	v_mfma_f32_16x16x32_bf16 v[20:23], v[160:163], v[220:223], v[20:23]
	v_mfma_f32_16x16x32_bf16 v[6:9], v[152:155], v[228:231], v[8:11]
	v_mfma_f32_16x16x32_bf16 v[2:5], v[160:163], v[228:231], v[2:5]
	v_mfma_f32_16x16x32_bf16 v[56:59], v[156:159], v[208:211], v[56:59]
	v_mfma_f32_16x16x32_bf16 v[52:55], v[182:185], v[208:211], v[52:55]
	v_mfma_f32_16x16x32_bf16 v[40:43], v[156:159], v[216:219], v[40:43]
	v_mfma_f32_16x16x32_bf16 v[36:39], v[182:185], v[216:219], v[36:39]
	v_mfma_f32_16x16x32_bf16 v[24:27], v[156:159], v[224:227], v[24:27]
	v_mfma_f32_16x16x32_bf16 v[20:23], v[182:185], v[224:227], v[20:23]
	v_mfma_f32_16x16x32_bf16 v[8:11], v[156:159], v[232:235], v[6:9]
	v_mfma_f32_16x16x32_bf16 v[4:7], v[182:185], v[232:235], v[2:5]
	s_setprio 0
	s_barrier
	s_add_i32 s95, s95, 2
	s_add_u32 s66, s66, 0x100
	s_addc_u32 s67, s67, 0
	s_cmp_gt_u32 s95, 61
	s_cbranch_scc1 .LBB0_237

; #define PG8_STAGE(bufoff, gbase, voff) do { _Pragma("unroll") for (int _i = 0; _i < 2; ++_i) \
;         __builtin_amdgcn_global_load_lds((const unsigned*)((const char*)(gbase) + (voff)[_i]), (LAS unsigned*)(lds + (bufoff) + ldsw + _i * 8192), 16, 0, 0); } while (0)
; #define PG8_BAR __builtin_amdgcn_s_barrier()
; template <class Epi, class Sched, bool ALIGN_EPI = false, bool SP2 = false>
; __device__ __forceinline__ void gemm_phase(LAS unsigned char* lds, const Gemm g, const Sched& S, const Epi& E) {
;     const int tid = threadIdx.x, wid = __builtin_amdgcn_readfirstlane(tid >> 6), lane = tid & 63, wr = wid >> 2, wc = wid & 3, fr = lane & 15, fq = lane >> 4;
;     const int K = g.K, nt = K / BK;
;     unsigned voffA[2], voffB[2];
; #pragma unroll
;     for (int i = 0; i < 2; ++i) { int R, C; stage_rc(tid * 16 + i * 8192, R, C); const int Rq = Epi::PERM ? perm32(R & 31) : (R & 31); const int Rb = Epi::COLS64 ? (64 * (R >> 5) + Rq) : ((R & ~31) + Rq);
;         voffA[i] = (unsigned)(R * g.lda + C) * 2u; voffB[i] = (unsigned)(Rb * g.ldb + C) * 2u; }
;     const size_t kstep = (size_t)(BK * 2);
;     const size_t hsA = (size_t)HALF * g.lda * 2, hsB = (size_t)(Epi::COLS64 ? 32 : HALF) * g.ldb * 2;
;     const size_t tsA = 2 * hsA, tsB = (size_t)BM * g.ldb * 2;
;     const unsigned ldsw = (unsigned)wid * 1024u;
;     const int aoff = lds_byte(wr * 64 + fr, fq * 8), boff = lds_byte(wc * 32 + fr, fq * 8);
;     ...
;     Unit cur, nxt; int ui = 0;
;     if (!S.next(0, cur)) return;
;     f32x4 acc[2][2][4][2];
; #pragma unroll
;     for (int a = 0; a < 2; ++a)
; #pragma unroll
;         for (int b = 0; b < 2; ++b)
; #pragma unroll
;             for (int m = 0; m < 4; ++m)
; #pragma unroll
;                 for (int n = 0; n < 2; ++n) acc[a][b][m][n] = (f32x4){0.f, 0.f, 0.f, 0.f};
;     bf16x8 At[4][2], B0[2][2], B1[2][2];
;     const char* cA = (const char*)g.A + (size_t)cur.pm * tsA; const char* cB = (const char*)g.Bt + (size_t)cur.pn * tsB;
;     S.a_ready(cur);
;     if constexpr (SP2) {
;         PG8_STAGE(PG8_SB(0, 0), cB, voffB); PG8_STAGE(PG8_SB(0, 1), cB + hsB, voffB); PG8_STAGE(PG8_SA(0, 0), cA, voffA); PG8_STAGE(PG8_SA(0, 1), cA + hsA, voffA);
;         if (wr == 1) PG8_BAR;
;         PG8_WAIT_V(2); PG8_BAR;
;         PG8_STAGE(PG8_SB(1, 0), cB + kstep, voffB); PG8_STAGE(PG8_SA(1, 0), cA + kstep, voffA); PG8_STAGE(PG8_SB(1, 1), cB + hsB + kstep, voffB);
.LBB0_293:
	s_ashr_i32 s1, s5, 3
	s_add_i32 s1, s8, s1
	s_ashr_i32 s8, s1, 31
	s_lshr_b32 s8, s8, 24
	s_add_i32 s8, s1, s8
	s_ashr_i32 s9, s8, 8
	s_and_b32 s8, s8, 0xffffff00
	v_lshrrev_b32_e32 v4, 1, v202
	v_lshrrev_b32_e32 v5, 5, v202
	s_sub_i32 s8, s1, s8
	v_lshlrev_b32_e32 v0, 4, v202
	s_waitcnt lgkmcnt(0)
	v_and_b32_e32 v1, 32, v202
	v_bfe_u32 v3, v202, 2, 4
	v_and_b32_e32 v4, 24, v4
	v_and_b32_e32 v5, 4, v5
	v_bfe_u32 v6, v202, 2, 2
	s_waitcnt vmcnt(0)
	v_lshrrev_b32_e32 v11, 3, v202
	s_movk_i32 s5, 0x70
	s_sext_i32_i16 s1, s8
	v_lshrrev_b32_e32 v2, 2, v202
	v_bitop3_b32 v8, v0, v1, 48 bitop3:0x6c
	v_and_b32_e32 v9, 64, v202
	v_or3_b32 v4, v5, v6, v4
	v_and_or_b32 v5, v11, s5, v3
	s_movk_i32 s5, 0xc0
	s_bfe_u32 s1, s1, 0x2001d
	v_or_b32_e32 v1, v8, v9
	v_and_or_b32 v2, v2, s5, v4
	s_add_i32 s12, s8, s1
	v_lshrrev_b32_e32 v1, 1, v1
	v_mul_u32_u24_e32 v2, 0x1040, v2
	s_sext_i32_i16 s13, s12
	s_and_b32 s12, s12, 0xfffc
	v_or_b32_e32 v2, v2, v1
	v_add_u32_e32 v0, 0x2000, v0
	s_sub_i32 s8, s8, s12
	v_lshrrev_b32_e32 v2, 7, v0
	s_movk_i32 s5, 0xf0
	s_lshl_b32 s9, s9, 2
	s_sext_i32_i16 s8, s8
	s_lshr_b32 s0, s4, 6
	v_and_or_b32 v2, v2, s5, v3
	v_lshrrev_b32_e32 v0, 6, v0
	s_movk_i32 s5, 0x1c0
	s_add_i32 s69, s9, s8
	s_ashr_i32 s8, s13, 2
	v_and_or_b32 v0, v0, s5, v4
	s_lshr_b32 s5, s4, 8
	s_lshl_b32 s31, s0, 10
	s_lshr_b32 s1, s13, 2
	s_mul_hi_i32 s9, s8, 0x208000
	s_mul_i32 s8, s8, 0x208000
	s_add_u32 s24, s79, s8
	s_addc_u32 s25, s80, s9
	s_add_i32 s36, s31, 0
	v_mul_u32_u24_e32 v0, 0x1040, v0
	s_add_i32 m0, s36, 0x10000
	v_or_b32_e32 v0, v0, v1
	v_lshrrev_b32_e32 v247, 6, v202
	v_bfe_u32 v242, v202, 3, 3
	v_and_b32_e32 v243, 7, v202
	v_xor_b32_e32 v243, v243, v242
	v_lshlrev_b32_e32 v243, 4, v243
	v_lshl_add_u32 v244, v247, 3, v242
	v_mul_u32_u24_e32 v244, 0x2080, v244
	v_add_u32_e32 v152, v244, v243
	v_add_u32_e32 v156, 0x82000, v152
	v_lshrrev_b32_e32 v245, 2, v247
	v_lshlrev_b32_e32 v245, 6, v245
	v_and_b32_e32 v246, 1, v247
	v_lshl_add_u32 v245, v246, 4, v245
	v_bfe_u32 v246, v247, 1, 1
	v_lshl_add_u32 v245, v246, 2, v245
	v_lshrrev_b32_e32 v246, 2, v242
	v_lshl_add_u32 v245, v246, 3, v245
	v_and_b32_e32 v246, 3, v242
	v_add_u32_e32 v245, v245, v246
	v_mul_u32_u24_e32 v245, 0x2080, v245
	v_add_u32_e32 v154, v245, v243
	v_add_u32_e32 v158, 0x104000, v154
	global_load_lds_dwordx4 v154, s[24:25]
	s_add_i32 m0, s36, 0x12000
	s_add_u32 s8, s24, 0x41000
	global_load_lds_dwordx4 v158, s[24:25]
	s_addc_u32 s9, s25, 0
	s_add_i32 m0, s36, 0x14000
	s_mul_i32 s14, s69, 0x208000
	global_load_lds_dwordx4 v154, s[8:9]
	s_add_i32 m0, s36, 0x16000
	v_mul_u32_u24_e32 v10, 0x1040, v5
	s_mul_hi_i32 s12, s69, 0x208000
	s_add_u32 s26, s34, s14
	v_or_b32_e32 v5, v1, v10
	v_mul_u32_u24_e32 v12, 0x1040, v2
	s_addc_u32 s27, s35, s12
	s_add_i32 s37, s36, 0x2000
	v_or_b32_e32 v2, v12, v1
	global_load_lds_dwordx4 v158, s[8:9]
	s_mov_b32 m0, s36
	s_add_u32 s8, s26, 0x104000
	global_load_lds_dwordx4 v152, s[26:27]
	s_mov_b32 m0, s37
	s_addc_u32 s9, s27, 0
	s_add_i32 s38, s36, 0x4000
	global_load_lds_dwordx4 v156, s[26:27]
	s_mov_b32 m0, s38
	s_add_i32 s39, s36, 0x6000
	global_load_lds_dwordx4 v152, s[8:9]
	s_mov_b32 m0, s39
	v_mov_b32_e32 v161, 0
	global_load_lds_dwordx4 v156, s[8:9]
	v_mov_b32_e32 v155, v161
	v_mov_b32_e32 v159, v161
	v_mov_b32_e32 v153, v161
	v_mov_b32_e32 v157, v161
	s_cmp_eq_u32 s5, 1
	s_movk_i32 s40, 0x2000
	s_mov_b32 s9, 0
	v_lshl_add_u64 v[6:7], s[24:25], 0, v[154:155]
	v_lshl_add_u64 v[4:5], s[24:25], 0, v[158:159]
	v_lshl_add_u64 v[0:1], s[26:27], 0, v[152:153]
	s_cselect_b64 s[12:13], -1, 0
	s_cmp_lg_u32 s5, 1
	v_lshl_add_u64 v[2:3], s[26:27], 0, v[156:157]
	s_cbranch_scc1 .LBB0_295
	s_barrier
; #define PG8_STAGE(bufoff, gbase, voff) do { _Pragma("unroll") for (int _i = 0; _i < 2; ++_i) \
;         __builtin_amdgcn_global_load_lds((const unsigned*)((const char*)(gbase) + (voff)[_i]), (LAS unsigned*)(lds + (bufoff) + ldsw + _i * 8192), 16, 0, 0); } while (0)
; #define PG8_WAIT_V(n) asm volatile("s_waitcnt vmcnt(" #n ")" ::: "memory")
; #define PG8_BAR __builtin_amdgcn_s_barrier()
; template <class Epi, class Sched, bool ALIGN_EPI = false, bool SP2 = false>
; __device__ __forceinline__ void gemm_phase(LAS unsigned char* lds, const Gemm g, const Sched& S, const Epi& E) {
;     ...
;     const int aoff = lds_byte(wr * 64 + fr, fq * 8), boff = lds_byte(wc * 32 + fr, fq * 8);
;     ...
;         PG8_STAGE(PG8_SB(1, 0), cB + kstep, voffB); PG8_STAGE(PG8_SA(1, 0), cA + kstep, voffA); PG8_STAGE(PG8_SB(1, 1), cB + hsB + kstep, voffB);
;         PG8_WAIT_V(6); PG8_BAR;
.LBB0_295:
	s_lshl_b32 s8, s33, 11
	s_mov_b64 s[14:15], 0x80
	s_add_i32 s8, s8, 0
	s_and_b32 s0, s0, 3
	s_add_i32 m0, s36, 0x18000
	v_lshl_add_u64 v[6:7], v[6:7], 0, s[14:15]
	s_add_i32 s8, s8, 0x20000
	s_lshl_b32 s41, s5, 6
	s_lshl_b32 s5, s5, 13
	s_lshl_b32 s20, s0, 12
	s_waitcnt vmcnt(2)
	s_barrier
	global_load_lds_dwordx4 v[6:7], off
	v_lshl_add_u64 v[4:5], v[4:5], 0, s[14:15]
	s_add_i32 m0, s36, 0x1a000
	s_add_i32 s42, s36, 0x8000
	s_add_i32 s43, s36, 0xa000
	global_load_lds_dwordx4 v[4:5], off
	v_lshl_add_u64 v[0:1], v[0:1], 0, s[14:15]
	s_mov_b32 m0, s42
	s_add_u32 s16, s24, 0x41080
	global_load_lds_dwordx4 v[0:1], off
	v_lshl_add_u64 v[0:1], v[2:3], 0, s[14:15]
	s_mov_b32 m0, s43
	s_addc_u32 s17, s25, 0
	global_load_lds_dwordx4 v[0:1], off
	s_add_i32 m0, s36, 0x1c000
	v_lshl_add_u64 v[0:1], s[16:17], 0, v[154:155]
	global_load_lds_dwordx4 v[0:1], off
	v_lshl_add_u64 v[0:1], s[16:17], 0, v[158:159]
	s_add_i32 m0, s36, 0x1e000
	v_bfe_u32 v2, v202, 4, 2
	global_load_lds_dwordx4 v[0:1], off
	v_and_b32_e32 v172, 15, v202
	v_lshlrev_b32_e32 v160, 4, v2
	v_lshlrev_b32_e32 v3, 2, v202
	v_lshl_or_b32 v0, v172, 6, v160
	v_and_b32_e32 v3, 32, v3
	s_sext_i32_i16 s70, s1
	v_bitop3_b32 v4, v0, s5, v3 bitop3:0xde
	v_lshlrev_b32_e32 v0, 6, v202
	s_movk_i32 s1, 0x3c0
	v_and_or_b32 v0, v0, s1, v160
	v_lshrrev_b32_e32 v1, 4, v202
	v_bitop3_b32 v173, s20, v0, v3 bitop3:0xf6
	v_and_b32_e32 v3, 7, v202
	s_waitcnt vmcnt(6)
	s_cmpk_lt_u32 s4, 0x100
	v_bfe_u32 v174, v202, 3, 3
	v_lshlrev_b32_e32 v0, 3, v3
	v_bitop3_b32 v1, v1, v3, 3 bitop3:0x6c
	v_bitop3_b32 v2, v2, v3, 4 bitop3:0x36
	v_bitop3_b32 v3, v11, v202, 7 bitop3:0x28
	v_add_u16_e32 v7, v8, v9
	s_cselect_b64 s[16:17], -1, 0
	s_lshl_b32 s0, s0, 6
	v_lshlrev_b32_e32 v1, 4, v1
	v_lshlrev_b32_e32 v2, 4, v2
	v_lshlrev_b32_e32 v3, 4, v3
	v_lshl_add_u64 v[162:163], s[10:11], 0, v[160:161]
	v_lshl_add_u32 v5, v172, 7, s8
	v_lshl_add_u32 v6, v174, 7, s8
	v_lshrrev_b16_e32 v7, 1, v7
	s_add_i32 s45, 0, 0x10000
	s_add_i32 s46, 0, 0x14000
	v_lshlrev_b32_e32 v160, 1, v0
	v_mbcnt_lo_u32_b32 v0, -1, 0
	s_ashr_i32 s44, s3, 31
	v_mov_b32_e32 v164, v152
	v_mov_b32_e32 v165, v161
	v_mov_b32_e32 v166, v156
	v_mov_b32_e32 v167, v161
	v_mov_b64_e32 v[168:169], 0x1000
	v_mov_b64_e32 v[170:171], 0xfff
	v_add_u32_e32 v175, s45, v173
	v_add_u32_e32 v176, s46, v173
	v_add_u32_e32 v177, 0, v4
	v_and_b32_e32 v242, 15, v202
	v_bfe_u32 v243, v202, 4, 2
	v_and_b32_e32 v244, 7, v242
	v_xor_b32_e32 v243, v243, v244
	v_lshlrev_b32_e32 v243, 4, v243
	v_lshl_add_u32 v243, v244, 7, v243
	v_lshrrev_b32_e32 v244, 3, v242
	v_lshl_add_u32 v243, v244, 10, v243
	v_lshrrev_b32_e32 v247, 6, v202
	v_lshrrev_b32_e32 v244, 2, v247
	v_lshl_add_u32 v177, v244, 13, v243
	v_and_b32_e32 v244, 3, v247
	v_lshl_add_u32 v173, v244, 12, v243
	v_xor_b32_e32 v250, 64, v177
	v_add_u32_e32 v175, 0x10000, v173
	v_add_u32_e32 v176, 0x14000, v173
	v_xor_b32_e32 v251, 64, v175
	v_xor_b32_e32 v252, 64, v176
	s_mov_b32 s47, 0x8080
	s_lshl_b32 s8, s0, 1
	v_mbcnt_hi_u32_b32 v178, -1, v0
	v_mov_b32_e32 v179, 0x358637bd
	s_mov_b32 s48, 0xf800000
	v_mov_b32_e32 v180, 0x260
	v_add_u32_e32 v181, v5, v1
	v_add_u32_e32 v182, v5, v2
	v_add_u32_e32 v183, v6, v3
	s_mov_b32 s49, 0x40000
	s_mov_b32 s50, 0x80000
	s_mov_b32 s51, 0xc0000
	s_mov_b32 s56, 0x101000
	s_mov_b32 s57, 0x141000
	s_mov_b32 s58, 0x181000
	s_mov_b32 s59, 0x1c1000
	s_mov_b32 s60, 0x404000
	s_mov_b32 s61, 0x444000
	s_mov_b32 s62, 0x484000
	s_mov_b32 s63, 0x4c4000
	s_mov_b32 s64, 0x505000
	s_mov_b32 s65, 0x545000
	s_mov_b32 s66, s9
	s_barrier
	s_branch .LBB0_298

; #define PG8_STAGE(bufoff, gbase, voff) do { _Pragma("unroll") for (int _i = 0; _i < 2; ++_i) \
;         __builtin_amdgcn_global_load_lds((const unsigned*)((const char*)(gbase) + (voff)[_i]), (LAS unsigned*)(lds + (bufoff) + ldsw + _i * 8192), 16, 0, 0); } while (0)
; #define PG8_LDA(dst, b, h) do { _Pragma("unroll") for (int m = 0; m < 4; ++m) _Pragma("unroll") for (int k = 0; k < 2; ++k) dst[m][k] = *(const LAS bf16x8*)(lds + PG8_SA(b, h) + aoff + m * 2048 + k * 1024); } while (0)
; #define PG8_LDB(dst, b, h) do { _Pragma("unroll") for (int n = 0; n < 2; ++n) _Pragma("unroll") for (int k = 0; k < 2; ++k) dst[n][k] = *(const LAS bf16x8*)(lds + PG8_SB(b, h) + boff + n * 2048 + k * 1024); } while (0)
; #define PG8_MMA(ai, bj, At, Bt) do { __builtin_amdgcn_s_setprio(3); _Pragma("unroll") for (int m = 0; m < 4; ++m) _Pragma("unroll") for (int n = 0; n < 2; ++n) _Pragma("unroll") for (int k = 0; k < 2; ++k) \
;         acc[ai][bj][m][n] = __builtin_amdgcn_mfma_f32_16x16x32_bf16(Bt[n][k], At[m][k], acc[ai][bj][m][n], 0, 0, 0); __builtin_amdgcn_s_setprio(0); } while (0)
; #define PG8_WAIT_V(n) asm volatile("s_waitcnt vmcnt(" #n ")" ::: "memory")
; #define PG8_WAIT_L(n) asm volatile("s_waitcnt lgkmcnt(" #n ")" ::: "memory")
; #define PG8_BAR __builtin_amdgcn_s_barrier()
; #define PG8_SCHED __builtin_amdgcn_sched_barrier(0)
; template <class Epi, class Sched, bool ALIGN_EPI = false, bool SP2 = false>
; __device__ __forceinline__ void gemm_phase(LAS unsigned char* lds, const Gemm g, const Sched& S, const Epi& E) {
;     ...
;             PG8_LDB(B0, 0, 0); PG8_LDB(B1, 0, 1); PG8_SCHED; PG8_LDA(At, 0, 0); PG8_STAGE(PG8_SA(1, 1), a1 + hsA, voffA);
;             PG8_WAIT_V(8); PG8_WAIT_L(0); PG8_BAR; PG8_MMA(0, 0, At, B0); PG8_MMA(0, 1, At, B1); PG8_BAR; PG8_SCHED;
;             PG8_LDA(At, 0, 1); PG8_STAGE(PG8_SB(0, 0), b2, voffB); PG8_STAGE(PG8_SB(0, 1), b2 + hsB, voffB); PG8_STAGE(PG8_SA(0, 0), a2, voffA);
.LBB0_309:
	ds_read_b128 v[112:115], v175
	ds_read_b128 v[132:135], v251
	ds_read_b128 v[136:139], v175 offset:2048
	ds_read_b128 v[140:143], v251 offset:2048
	ds_read_b128 v[144:147], v176
	ds_read_b128 v[148:151], v252
	ds_read_b128 v[184:187], v176 offset:2048
	ds_read_b128 v[188:191], v252 offset:2048
	s_add_u32 s24, s4, 0xffefc080
	s_addc_u32 s25, s5, -1
	s_cmp_eq_u32 s73, 60
	s_cselect_b32 s27, s11, s25
	s_cselect_b32 s26, s10, s24
	s_cselect_b32 s25, s21, s72
	s_cselect_b32 s24, s20, s71
	v_lshl_add_u64 v[200:201], s[4:5], 0, v[164:165]
	s_add_i32 m0, s36, 0xc000
	ds_read_b128 v[192:195], v177
	ds_read_b128 v[196:199], v250
	ds_read_b128 v[206:209], v177 offset:2048
	ds_read_b128 v[210:213], v250 offset:2048
	ds_read_b128 v[214:217], v177 offset:4096
	ds_read_b128 v[218:221], v250 offset:4096
	ds_read_b128 v[222:225], v177 offset:6144
	ds_read_b128 v[226:229], v250 offset:6144
	global_load_lds_dwordx4 v[200:201], off
	v_lshl_add_u64 v[200:201], s[4:5], 0, v[166:167]
	s_add_i32 m0, s36, 0xe000
	s_nop 0
	global_load_lds_dwordx4 v[200:201], off
	s_waitcnt vmcnt(8)
	s_waitcnt lgkmcnt(0)
	s_barrier
	s_setprio 3
	s_waitcnt lgkmcnt(0)
	v_mfma_f32_16x16x32_bf16 v[128:131], v[112:115], v[192:195], v[128:131]
	v_mfma_f32_16x16x32_bf16 v[124:127], v[136:139], v[192:195], v[124:127]
	v_mfma_f32_16x16x32_bf16 v[108:111], v[112:115], v[206:209], v[108:111]
	v_mfma_f32_16x16x32_bf16 v[104:107], v[136:139], v[206:209], v[104:107]
	v_mfma_f32_16x16x32_bf16 v[92:95], v[112:115], v[214:217], v[92:95]
	v_mfma_f32_16x16x32_bf16 v[88:91], v[136:139], v[214:217], v[88:91]
	v_mfma_f32_16x16x32_bf16 v[76:79], v[112:115], v[222:225], v[76:79]
	v_mfma_f32_16x16x32_bf16 v[72:75], v[136:139], v[222:225], v[72:75]
	v_mfma_f32_16x16x32_bf16 v[128:131], v[132:135], v[196:199], v[128:131]
	v_mfma_f32_16x16x32_bf16 v[124:127], v[140:143], v[196:199], v[124:127]
	v_mfma_f32_16x16x32_bf16 v[108:111], v[132:135], v[210:213], v[108:111]
	v_mfma_f32_16x16x32_bf16 v[104:107], v[140:143], v[210:213], v[104:107]
	v_mfma_f32_16x16x32_bf16 v[92:95], v[132:135], v[218:221], v[92:95]
	v_mfma_f32_16x16x32_bf16 v[88:91], v[140:143], v[218:221], v[88:91]
	v_mfma_f32_16x16x32_bf16 v[76:79], v[132:135], v[226:229], v[76:79]
	v_mfma_f32_16x16x32_bf16 v[72:75], v[140:143], v[226:229], v[72:75]
	s_setprio 0
	s_setprio 3
	v_mfma_f32_16x16x32_bf16 v[120:123], v[144:147], v[192:195], v[120:123]
	v_mfma_f32_16x16x32_bf16 v[116:119], v[184:187], v[192:195], v[116:119]
	v_mfma_f32_16x16x32_bf16 v[100:103], v[144:147], v[206:209], v[100:103]
	v_mfma_f32_16x16x32_bf16 v[96:99], v[184:187], v[206:209], v[96:99]
	v_mfma_f32_16x16x32_bf16 v[84:87], v[144:147], v[214:217], v[84:87]
	v_mfma_f32_16x16x32_bf16 v[80:83], v[184:187], v[214:217], v[80:83]
	v_mfma_f32_16x16x32_bf16 v[68:71], v[144:147], v[222:225], v[68:71]
	v_mfma_f32_16x16x32_bf16 v[64:67], v[184:187], v[222:225], v[64:67]
	v_mfma_f32_16x16x32_bf16 v[120:123], v[148:151], v[196:199], v[120:123]
	v_mfma_f32_16x16x32_bf16 v[116:119], v[188:191], v[196:199], v[116:119]
	v_mfma_f32_16x16x32_bf16 v[100:103], v[148:151], v[210:213], v[100:103]
	v_mfma_f32_16x16x32_bf16 v[96:99], v[188:191], v[210:213], v[96:99]
	v_mfma_f32_16x16x32_bf16 v[84:87], v[148:151], v[218:221], v[84:87]
	v_mfma_f32_16x16x32_bf16 v[80:83], v[188:191], v[218:221], v[80:83]
	v_mfma_f32_16x16x32_bf16 v[68:71], v[148:151], v[226:229], v[68:71]
	v_mfma_f32_16x16x32_bf16 v[64:67], v[188:191], v[226:229], v[64:67]
	s_setprio 0
	s_barrier
	s_add_i32 s74, s45, s31
	v_lshl_add_u64 v[200:201], s[24:25], 0, v[154:155]
	s_mov_b32 m0, s74
	ds_read_b128 v[192:195], v177 offset:16384
	ds_read_b128 v[196:199], v250 offset:16384
	ds_read_b128 v[206:209], v177 offset:18432
	ds_read_b128 v[210:213], v250 offset:18432
	ds_read_b128 v[214:217], v177 offset:20480
	ds_read_b128 v[218:221], v250 offset:20480
	ds_read_b128 v[222:225], v177 offset:22528
	ds_read_b128 v[226:229], v250 offset:22528
	global_load_lds_dwordx4 v[200:201], off
	s_add_i32 m0, s74, 0x2000
	s_add_u32 s74, s24, 0x41000
	v_lshl_add_u64 v[230:231], s[24:25], 0, v[158:159]
	s_addc_u32 s75, s25, 0
	s_add_i32 s78, s46, s31
	global_load_lds_dwordx4 v[230:231], off
	v_lshl_add_u64 v[232:233], s[74:75], 0, v[154:155]
	s_mov_b32 m0, s78
	v_lshl_add_u64 v[234:235], s[26:27], 0, v[156:157]
	global_load_lds_dwordx4 v[232:233], off
	v_lshl_add_u64 v[232:233], s[74:75], 0, v[158:159]
	s_add_i32 m0, s78, 0x2000
	s_nop 0
	global_load_lds_dwordx4 v[232:233], off
	v_lshl_add_u64 v[232:233], s[26:27], 0, v[152:153]
	s_mov_b32 m0, s36
	s_nop 0
	global_load_lds_dwordx4 v[232:233], off
	s_mov_b32 m0, s37
	s_nop 0
	global_load_lds_dwordx4 v[234:235], off
	s_waitcnt vmcnt(8)
	s_waitcnt lgkmcnt(0)
	s_barrier
; #define PG8_STAGE(bufoff, gbase, voff) do { _Pragma("unroll") for (int _i = 0; _i < 2; ++_i) \
;         __builtin_amdgcn_global_load_lds((const unsigned*)((const char*)(gbase) + (voff)[_i]), (LAS unsigned*)(lds + (bufoff) + ldsw + _i * 8192), 16, 0, 0); } while (0)
; #define PG8_LDA(dst, b, h) do { _Pragma("unroll") for (int m = 0; m < 4; ++m) _Pragma("unroll") for (int k = 0; k < 2; ++k) dst[m][k] = *(const LAS bf16x8*)(lds + PG8_SA(b, h) + aoff + m * 2048 + k * 1024); } while (0)
; #define PG8_LDB(dst, b, h) do { _Pragma("unroll") for (int n = 0; n < 2; ++n) _Pragma("unroll") for (int k = 0; k < 2; ++k) dst[n][k] = *(const LAS bf16x8*)(lds + PG8_SB(b, h) + boff + n * 2048 + k * 1024); } while (0)
; #define PG8_MMA(ai, bj, At, Bt) do { __builtin_amdgcn_s_setprio(3); _Pragma("unroll") for (int m = 0; m < 4; ++m) _Pragma("unroll") for (int n = 0; n < 2; ++n) _Pragma("unroll") for (int k = 0; k < 2; ++k) \
;         acc[ai][bj][m][n] = __builtin_amdgcn_mfma_f32_16x16x32_bf16(Bt[n][k], At[m][k], acc[ai][bj][m][n], 0, 0, 0); __builtin_amdgcn_s_setprio(0); } while (0)
; #define PG8_WAIT_V(n) asm volatile("s_waitcnt vmcnt(" #n ")" ::: "memory")
; #define PG8_WAIT_L(n) asm volatile("s_waitcnt lgkmcnt(" #n ")" ::: "memory")
; #define PG8_BAR __builtin_amdgcn_s_barrier()
; #define PG8_SCHED __builtin_amdgcn_sched_barrier(0)
; template <class Epi, class Sched, bool ALIGN_EPI = false, bool SP2 = false>
; __device__ __forceinline__ void gemm_phase(LAS unsigned char* lds, const Gemm g, const Sched& S, const Epi& E) {
;     ...
;             PG8_WAIT_V(8); PG8_WAIT_L(0); PG8_BAR; PG8_MMA(1, 0, At, B0); PG8_MMA(1, 1, At, B1); PG8_BAR; PG8_SCHED;
;             PG8_LDB(B0, 1, 0); PG8_LDB(B1, 1, 1); PG8_SCHED; PG8_LDA(At, 1, 0); PG8_STAGE(PG8_SA(0, 1), a2 + hsA, voffA);
;             PG8_WAIT_V(8); PG8_WAIT_L(0); PG8_BAR; PG8_MMA(0, 0, At, B0); PG8_MMA(0, 1, At, B1); PG8_BAR; PG8_SCHED;
	s_setprio 3
	s_waitcnt lgkmcnt(0)
	v_mfma_f32_16x16x32_bf16 v[60:63], v[112:115], v[192:195], v[60:63]
	v_mfma_f32_16x16x32_bf16 v[56:59], v[136:139], v[192:195], v[56:59]
	v_mfma_f32_16x16x32_bf16 v[44:47], v[112:115], v[206:209], v[44:47]
	v_mfma_f32_16x16x32_bf16 v[40:43], v[136:139], v[206:209], v[40:43]
	v_mfma_f32_16x16x32_bf16 v[28:31], v[112:115], v[214:217], v[28:31]
	v_mfma_f32_16x16x32_bf16 v[24:27], v[136:139], v[214:217], v[24:27]
	v_mfma_f32_16x16x32_bf16 v[12:15], v[112:115], v[222:225], v[12:15]
	v_mfma_f32_16x16x32_bf16 v[8:11], v[136:139], v[222:225], v[8:11]
	v_mfma_f32_16x16x32_bf16 v[60:63], v[132:135], v[196:199], v[60:63]
	v_mfma_f32_16x16x32_bf16 v[56:59], v[140:143], v[196:199], v[56:59]
	v_mfma_f32_16x16x32_bf16 v[44:47], v[132:135], v[210:213], v[44:47]
	v_mfma_f32_16x16x32_bf16 v[40:43], v[140:143], v[210:213], v[40:43]
	v_mfma_f32_16x16x32_bf16 v[28:31], v[132:135], v[218:221], v[28:31]
	v_mfma_f32_16x16x32_bf16 v[24:27], v[140:143], v[218:221], v[24:27]
	v_mfma_f32_16x16x32_bf16 v[12:15], v[132:135], v[226:229], v[12:15]
	v_mfma_f32_16x16x32_bf16 v[8:11], v[140:143], v[226:229], v[8:11]
	s_setprio 0
	s_setprio 3
	v_mfma_f32_16x16x32_bf16 v[52:55], v[144:147], v[192:195], v[52:55]
	v_mfma_f32_16x16x32_bf16 v[48:51], v[184:187], v[192:195], v[48:51]
	v_mfma_f32_16x16x32_bf16 v[36:39], v[144:147], v[206:209], v[36:39]
	v_mfma_f32_16x16x32_bf16 v[32:35], v[184:187], v[206:209], v[32:35]
	v_mfma_f32_16x16x32_bf16 v[20:23], v[144:147], v[214:217], v[20:23]
	v_mfma_f32_16x16x32_bf16 v[16:19], v[184:187], v[214:217], v[16:19]
	v_mfma_f32_16x16x32_bf16 v[4:7], v[144:147], v[222:225], v[4:7]
	v_mfma_f32_16x16x32_bf16 v[0:3], v[184:187], v[222:225], v[0:3]
	v_mfma_f32_16x16x32_bf16 v[52:55], v[148:151], v[196:199], v[52:55]
	v_mfma_f32_16x16x32_bf16 v[48:51], v[188:191], v[196:199], v[48:51]
	v_mfma_f32_16x16x32_bf16 v[36:39], v[148:151], v[210:213], v[36:39]
	v_mfma_f32_16x16x32_bf16 v[32:35], v[188:191], v[210:213], v[32:35]
	v_mfma_f32_16x16x32_bf16 v[20:23], v[148:151], v[218:221], v[20:23]
	v_mfma_f32_16x16x32_bf16 v[16:19], v[188:191], v[218:221], v[16:19]
	v_mfma_f32_16x16x32_bf16 v[4:7], v[148:151], v[226:229], v[4:7]
	v_mfma_f32_16x16x32_bf16 v[0:3], v[188:191], v[226:229], v[0:3]
	s_setprio 0
	s_barrier
	s_add_i32 s74, 0, 0x18000
	s_add_i32 s75, 0, 0x1c000
	v_add_u32_e32 v140, s74, v173
	v_xor_b32_e32 v253, 64, v140
	v_add_u32_e32 v188, s75, v173
	v_xor_b32_e32 v254, 64, v188
	ds_read_b128 v[112:115], v140
	ds_read_b128 v[132:135], v253
	ds_read_b128 v[136:139], v140 offset:2048
	ds_read_b128 v[140:143], v253 offset:2048
	ds_read_b128 v[144:147], v188
	ds_read_b128 v[148:151], v254
	ds_read_b128 v[184:187], v188 offset:2048
	ds_read_b128 v[188:191], v254 offset:2048
	s_add_u32 s26, s26, 0x104000
	s_addc_u32 s27, s27, 0
	s_mov_b32 m0, s38
	v_lshl_add_u64 v[236:237], s[26:27], 0, v[152:153]
	ds_read_b128 v[192:195], v177 offset:32768
	ds_read_b128 v[196:199], v250 offset:32768
	ds_read_b128 v[206:209], v177 offset:34816
	ds_read_b128 v[210:213], v250 offset:34816
	ds_read_b128 v[214:217], v177 offset:36864
	ds_read_b128 v[218:221], v250 offset:36864
	ds_read_b128 v[222:225], v177 offset:38912
	ds_read_b128 v[226:229], v250 offset:38912
	global_load_lds_dwordx4 v[236:237], off
	v_lshl_add_u64 v[236:237], s[26:27], 0, v[156:157]
	s_mov_b32 m0, s39
	s_nop 0
	global_load_lds_dwordx4 v[236:237], off
	s_waitcnt vmcnt(8)
	s_waitcnt lgkmcnt(0)
	s_barrier
	s_setprio 3
	s_waitcnt lgkmcnt(0)
	v_mfma_f32_16x16x32_bf16 v[128:131], v[112:115], v[192:195], v[128:131]
	v_mfma_f32_16x16x32_bf16 v[124:127], v[136:139], v[192:195], v[124:127]
	v_mfma_f32_16x16x32_bf16 v[108:111], v[112:115], v[206:209], v[108:111]
	v_mfma_f32_16x16x32_bf16 v[104:107], v[136:139], v[206:209], v[104:107]
	v_mfma_f32_16x16x32_bf16 v[92:95], v[112:115], v[214:217], v[92:95]
	v_mfma_f32_16x16x32_bf16 v[88:91], v[136:139], v[214:217], v[88:91]
	v_mfma_f32_16x16x32_bf16 v[76:79], v[112:115], v[222:225], v[76:79]
	v_mfma_f32_16x16x32_bf16 v[72:75], v[136:139], v[222:225], v[72:75]
	v_mfma_f32_16x16x32_bf16 v[128:131], v[132:135], v[196:199], v[128:131]
	v_mfma_f32_16x16x32_bf16 v[124:127], v[140:143], v[196:199], v[124:127]
	v_mfma_f32_16x16x32_bf16 v[108:111], v[132:135], v[210:213], v[108:111]
	v_mfma_f32_16x16x32_bf16 v[104:107], v[140:143], v[210:213], v[104:107]
	v_mfma_f32_16x16x32_bf16 v[92:95], v[132:135], v[218:221], v[92:95]
	v_mfma_f32_16x16x32_bf16 v[88:91], v[140:143], v[218:221], v[88:91]
	v_mfma_f32_16x16x32_bf16 v[76:79], v[132:135], v[226:229], v[76:79]
	v_mfma_f32_16x16x32_bf16 v[72:75], v[140:143], v[226:229], v[72:75]
	s_setprio 0
	s_setprio 3
	v_mfma_f32_16x16x32_bf16 v[120:123], v[144:147], v[192:195], v[120:123]
	v_mfma_f32_16x16x32_bf16 v[116:119], v[184:187], v[192:195], v[116:119]
	v_mfma_f32_16x16x32_bf16 v[100:103], v[144:147], v[206:209], v[100:103]
	v_mfma_f32_16x16x32_bf16 v[96:99], v[184:187], v[206:209], v[96:99]
	v_mfma_f32_16x16x32_bf16 v[84:87], v[144:147], v[214:217], v[84:87]
	v_mfma_f32_16x16x32_bf16 v[80:83], v[184:187], v[214:217], v[80:83]
	v_mfma_f32_16x16x32_bf16 v[68:71], v[144:147], v[222:225], v[68:71]
	v_mfma_f32_16x16x32_bf16 v[64:67], v[184:187], v[222:225], v[64:67]
	v_mfma_f32_16x16x32_bf16 v[120:123], v[148:151], v[196:199], v[120:123]
	v_mfma_f32_16x16x32_bf16 v[116:119], v[188:191], v[196:199], v[116:119]
	v_mfma_f32_16x16x32_bf16 v[100:103], v[148:151], v[210:213], v[100:103]
	v_mfma_f32_16x16x32_bf16 v[96:99], v[188:191], v[210:213], v[96:99]
	v_mfma_f32_16x16x32_bf16 v[84:87], v[148:151], v[218:221], v[84:87]
	v_mfma_f32_16x16x32_bf16 v[80:83], v[188:191], v[218:221], v[80:83]
	v_mfma_f32_16x16x32_bf16 v[68:71], v[148:151], v[226:229], v[68:71]
	v_mfma_f32_16x16x32_bf16 v[64:67], v[188:191], v[226:229], v[64:67]
	s_setprio 0
	s_barrier
; #define PG8_STAGE(bufoff, gbase, voff) do { _Pragma("unroll") for (int _i = 0; _i < 2; ++_i) \
;         __builtin_amdgcn_global_load_lds((const unsigned*)((const char*)(gbase) + (voff)[_i]), (LAS unsigned*)(lds + (bufoff) + ldsw + _i * 8192), 16, 0, 0); } while (0)
; #define PG8_LDA(dst, b, h) do { _Pragma("unroll") for (int m = 0; m < 4; ++m) _Pragma("unroll") for (int k = 0; k < 2; ++k) dst[m][k] = *(const LAS bf16x8*)(lds + PG8_SA(b, h) + aoff + m * 2048 + k * 1024); } while (0)
; #define PG8_MMA(ai, bj, At, Bt) do { __builtin_amdgcn_s_setprio(3); _Pragma("unroll") for (int m = 0; m < 4; ++m) _Pragma("unroll") for (int n = 0; n < 2; ++n) _Pragma("unroll") for (int k = 0; k < 2; ++k) \
;         acc[ai][bj][m][n] = __builtin_amdgcn_mfma_f32_16x16x32_bf16(Bt[n][k], At[m][k], acc[ai][bj][m][n], 0, 0, 0); __builtin_amdgcn_s_setprio(0); } while (0)
; #define PG8_WAIT_V(n) asm volatile("s_waitcnt vmcnt(" #n ")" ::: "memory")
; #define PG8_WAIT_L(n) asm volatile("s_waitcnt lgkmcnt(" #n ")" ::: "memory")
; #define PG8_BAR __builtin_amdgcn_s_barrier()
; #define PG8_SCHED __builtin_amdgcn_sched_barrier(0)
; template <class Epi, class Sched, bool ALIGN_EPI = false, bool SP2 = false>
; __device__ __forceinline__ void gemm_phase(LAS unsigned char* lds, const Gemm g, const Sched& S, const Epi& E) {
;     ...
;             PG8_LDA(At, 1, 1); PG8_STAGE(PG8_SB(1, 0), b3, voffB); PG8_STAGE(PG8_SB(1, 1), b3 + hsB, voffB); PG8_STAGE(PG8_SA(1, 0), a3, voffA);
;             PG8_WAIT_V(8); PG8_WAIT_L(0); PG8_BAR; PG8_MMA(1, 0, At, B0); PG8_MMA(1, 1, At, B1); PG8_BAR; PG8_SCHED;
	s_add_i32 s26, s74, s31
	v_lshl_add_u64 v[200:201], v[200:201], 0, s[14:15]
	s_mov_b32 m0, s26
	ds_read_b128 v[192:195], v177 offset:49152
	ds_read_b128 v[196:199], v250 offset:49152
	ds_read_b128 v[206:209], v177 offset:51200
	ds_read_b128 v[210:213], v250 offset:51200
	ds_read_b128 v[214:217], v177 offset:53248
	ds_read_b128 v[218:221], v250 offset:53248
	ds_read_b128 v[222:225], v177 offset:55296
	ds_read_b128 v[226:229], v250 offset:55296
	global_load_lds_dwordx4 v[200:201], off
	s_add_i32 m0, s26, 0x2000
	s_add_u32 s24, s24, 0x41080
	v_lshl_add_u64 v[200:201], v[230:231], 0, s[14:15]
	s_addc_u32 s25, s25, 0
	s_add_i32 s26, s75, s31
	global_load_lds_dwordx4 v[200:201], off
	v_lshl_add_u64 v[200:201], s[24:25], 0, v[154:155]
	s_mov_b32 m0, s26
	s_nop 0
	global_load_lds_dwordx4 v[200:201], off
	v_lshl_add_u64 v[200:201], s[24:25], 0, v[158:159]
	s_add_i32 m0, s26, 0x2000
	s_nop 0
	global_load_lds_dwordx4 v[200:201], off
	v_lshl_add_u64 v[200:201], v[232:233], 0, s[14:15]
	s_mov_b32 m0, s42
	s_nop 0
	global_load_lds_dwordx4 v[200:201], off
	v_lshl_add_u64 v[200:201], v[234:235], 0, s[14:15]
	s_mov_b32 m0, s43
	s_nop 0
	global_load_lds_dwordx4 v[200:201], off
	s_waitcnt vmcnt(8)
	s_waitcnt lgkmcnt(0)
	s_barrier
	s_setprio 3
	s_waitcnt lgkmcnt(0)
	v_mfma_f32_16x16x32_bf16 v[60:63], v[112:115], v[192:195], v[60:63]
	v_mfma_f32_16x16x32_bf16 v[56:59], v[136:139], v[192:195], v[56:59]
	v_mfma_f32_16x16x32_bf16 v[44:47], v[112:115], v[206:209], v[44:47]
	v_mfma_f32_16x16x32_bf16 v[40:43], v[136:139], v[206:209], v[40:43]
	v_mfma_f32_16x16x32_bf16 v[28:31], v[112:115], v[214:217], v[28:31]
	v_mfma_f32_16x16x32_bf16 v[24:27], v[136:139], v[214:217], v[24:27]
	v_mfma_f32_16x16x32_bf16 v[12:15], v[112:115], v[222:225], v[12:15]
	v_mfma_f32_16x16x32_bf16 v[8:11], v[136:139], v[222:225], v[8:11]
	v_mfma_f32_16x16x32_bf16 v[60:63], v[132:135], v[196:199], v[60:63]
	v_mfma_f32_16x16x32_bf16 v[56:59], v[140:143], v[196:199], v[56:59]
	v_mfma_f32_16x16x32_bf16 v[44:47], v[132:135], v[210:213], v[44:47]
	v_mfma_f32_16x16x32_bf16 v[40:43], v[140:143], v[210:213], v[40:43]
	v_mfma_f32_16x16x32_bf16 v[28:31], v[132:135], v[218:221], v[28:31]
	v_mfma_f32_16x16x32_bf16 v[24:27], v[140:143], v[218:221], v[24:27]
	v_mfma_f32_16x16x32_bf16 v[12:15], v[132:135], v[226:229], v[12:15]
	v_mfma_f32_16x16x32_bf16 v[8:11], v[140:143], v[226:229], v[8:11]
	s_setprio 0
	s_setprio 3
	v_mfma_f32_16x16x32_bf16 v[52:55], v[144:147], v[192:195], v[52:55]
	v_mfma_f32_16x16x32_bf16 v[48:51], v[184:187], v[192:195], v[48:51]
	v_mfma_f32_16x16x32_bf16 v[36:39], v[144:147], v[206:209], v[36:39]
	v_mfma_f32_16x16x32_bf16 v[32:35], v[184:187], v[206:209], v[32:35]
	v_mfma_f32_16x16x32_bf16 v[20:23], v[144:147], v[214:217], v[20:23]
	v_mfma_f32_16x16x32_bf16 v[16:19], v[184:187], v[214:217], v[16:19]
	v_mfma_f32_16x16x32_bf16 v[4:7], v[144:147], v[222:225], v[4:7]
	v_mfma_f32_16x16x32_bf16 v[0:3], v[184:187], v[222:225], v[0:3]
	v_mfma_f32_16x16x32_bf16 v[52:55], v[148:151], v[196:199], v[52:55]
	v_mfma_f32_16x16x32_bf16 v[48:51], v[188:191], v[196:199], v[48:51]
	v_mfma_f32_16x16x32_bf16 v[36:39], v[148:151], v[210:213], v[36:39]
	v_mfma_f32_16x16x32_bf16 v[32:35], v[188:191], v[210:213], v[32:35]
	v_mfma_f32_16x16x32_bf16 v[20:23], v[148:151], v[218:221], v[20:23]
	v_mfma_f32_16x16x32_bf16 v[16:19], v[188:191], v[218:221], v[16:19]
	v_mfma_f32_16x16x32_bf16 v[4:7], v[148:151], v[226:229], v[4:7]
	v_mfma_f32_16x16x32_bf16 v[0:3], v[188:191], v[226:229], v[0:3]
	s_setprio 0
	s_barrier
	s_add_i32 s73, s73, 2
	s_add_u32 s4, s4, 0x100
	s_addc_u32 s5, s5, 0
	s_add_u32 s71, s71, 0x100
	s_addc_u32 s72, s72, 0
	s_cmp_gt_u32 s73, 61
	s_cbranch_scc0 .LBB0_309
	s_and_b64 vcc, exec, s[16:17]
	s_cbranch_vccz .LBB0_312
	s_barrier

; #define PG8_STAGE(bufoff, gbase, voff) do { _Pragma("unroll") for (int _i = 0; _i < 2; ++_i) \
;         __builtin_amdgcn_global_load_lds((const unsigned*)((const char*)(gbase) + (voff)[_i]), (LAS unsigned*)(lds + (bufoff) + ldsw + _i * 8192), 16, 0, 0); } while (0)
; #define PG8_WAIT_V(n) asm volatile("s_waitcnt vmcnt(" #n ")" ::: "memory")
; #define PG8_BAR __builtin_amdgcn_s_barrier()
; template <class Epi, class Sched, bool ALIGN_EPI = false, bool SP2 = false>
; __device__ __forceinline__ void gemm_phase(LAS unsigned char* lds, const Gemm g, const Sched& S, const Epi& E) {
;     const int tid = threadIdx.x, wid = __builtin_amdgcn_readfirstlane(tid >> 6), lane = tid & 63, wr = wid >> 2, wc = wid & 3, fr = lane & 15, fq = lane >> 4;
;     const int K = g.K, nt = K / BK;
;     unsigned voffA[2], voffB[2];
; #pragma unroll
;     for (int i = 0; i < 2; ++i) { int R, C; stage_rc(tid * 16 + i * 8192, R, C); const int Rq = Epi::PERM ? perm32(R & 31) : (R & 31); const int Rb = Epi::COLS64 ? (64 * (R >> 5) + Rq) : ((R & ~31) + Rq);
;         voffA[i] = (unsigned)(R * g.lda + C) * 2u; voffB[i] = (unsigned)(Rb * g.ldb + C) * 2u; }
;     const size_t kstep = (size_t)(BK * 2);
;     const size_t hsA = (size_t)HALF * g.lda * 2, hsB = (size_t)(Epi::COLS64 ? 32 : HALF) * g.ldb * 2;
;     const size_t tsA = 2 * hsA, tsB = (size_t)BM * g.ldb * 2;
;     const unsigned ldsw = (unsigned)wid * 1024u;
;     const int aoff = lds_byte(wr * 64 + fr, fq * 8), boff = lds_byte(wc * 32 + fr, fq * 8);
;     ...
;     if constexpr (SP2) {
;         PG8_STAGE(PG8_SB(0, 0), cB, voffB); PG8_STAGE(PG8_SB(0, 1), cB + hsB, voffB); PG8_STAGE(PG8_SA(0, 0), cA, voffA); PG8_STAGE(PG8_SA(0, 1), cA + hsA, voffA);
;         if (wr == 1) PG8_BAR;
;         PG8_WAIT_V(2); PG8_BAR;
;         PG8_STAGE(PG8_SB(1, 0), cB + kstep, voffB); PG8_STAGE(PG8_SA(1, 0), cA + kstep, voffA); PG8_STAGE(PG8_SB(1, 1), cB + hsB + kstep, voffB);
;         PG8_WAIT_V(6); PG8_BAR;
.LBB0_334:
	s_add_i32 s1, s6, s1
	s_ashr_i32 s6, s1, 31
	s_lshr_b32 s6, s6, 26
	s_add_i32 s6, s1, s6
	s_ashr_i32 s7, s6, 6
	s_and_b32 s6, s6, 0xffc0
	s_sub_i32 s6, s1, s6
	s_bfe_i32 s1, s6, 0x80000
	s_bfe_u32 s1, s1, 0x2000d
	s_add_i32 s8, s6, s1
	v_lshlrev_b32_e32 v0, 4, v202
	s_waitcnt lgkmcnt(0)
	v_and_b32_e32 v1, 32, v202
	s_bfe_i32 s1, s8, 0x80000
	s_and_b32 s8, s8, 0xfc
	v_bfe_u32 v2, v202, 2, 4
	v_bitop3_b32 v8, v0, v1, 48 bitop3:0x6c
	s_waitcnt vmcnt(0)
	v_lshrrev_b32_e32 v12, 3, v202
	s_movk_i32 s5, 0x70
	v_add_u32_e32 v0, 0x2000, v0
	s_sub_i32 s6, s6, s8
	v_and_or_b32 v3, v12, s5, v2
	v_lshrrev_b32_e32 v0, 7, v0
	s_movk_i32 s5, 0xf0
	s_lshl_b32 s7, s7, 2
	s_sext_i32_i16 s9, s1
	s_sext_i32_i8 s6, s6
	v_and_or_b32 v0, v0, s5, v2
	s_lshr_b32 s5, s4, 6
	s_add_i32 s46, s7, s6
	s_ashr_i32 s6, s9, 2
	s_lshr_b32 s0, s4, 8
	s_lshl_b32 s25, s5, 10
	s_lshr_b32 s1, s9, 2
	s_mul_hi_i32 s7, s6, 0x808000
	s_mul_i32 s6, s6, 0x808000
	v_and_b32_e32 v9, 64, v202
	s_add_u32 s16, s76, s6
	v_or_b32_e32 v1, v8, v9
	v_mul_u32_u24_e32 v10, 0x8080, v3
	s_addc_u32 s17, s77, s7
	s_add_i32 s26, s25, 0
	s_add_i32 m0, s26, 0x10000
	v_mul_u32_u24_e32 v11, 0x8080, v0
	v_lshrrev_b32_e32 v247, 6, v202
	v_bfe_u32 v242, v202, 3, 3
	v_and_b32_e32 v243, 7, v202
	v_xor_b32_e32 v243, v243, v242
	v_lshlrev_b32_e32 v243, 4, v243
	v_lshl_add_u32 v244, v247, 3, v242
	v_mul_u32_u24_e32 v244, 0x8080, v244
	v_add_u32_e32 v128, v244, v243
	v_add_u32_e32 v130, 0x202000, v128
	v_lshl_add_u32 v245, v247, 3, v242
	v_mul_u32_u24_e32 v245, 0x8080, v245
	v_add_u32_e32 v128, v245, v243
	v_add_u32_e32 v130, 0x202000, v128
	global_load_lds_dwordx4 v128, s[16:17]
	s_add_i32 m0, s26, 0x12000
	s_add_u32 s6, s16, 0x404000
	global_load_lds_dwordx4 v130, s[16:17]
	s_addc_u32 s7, s17, 0
	s_add_i32 m0, s26, 0x14000
	s_mul_i32 s10, s46, 0x808000
	global_load_lds_dwordx4 v128, s[6:7]
	s_add_i32 m0, s26, 0x16000
	s_mul_hi_i32 s8, s46, 0x808000
	s_add_u32 s14, s18, s10
	s_addc_u32 s15, s19, s8
	s_add_i32 s27, s26, 0x2000
	global_load_lds_dwordx4 v130, s[6:7]
	s_mov_b32 m0, s26
	s_add_u32 s6, s14, 0x404000
	global_load_lds_dwordx4 v128, s[14:15]
	s_mov_b32 m0, s27
	s_addc_u32 s7, s15, 0
	s_add_i32 s30, s26, 0x4000
	global_load_lds_dwordx4 v130, s[14:15]
	s_mov_b32 m0, s30
	s_add_i32 s31, s26, 0x6000
	global_load_lds_dwordx4 v128, s[6:7]
	s_mov_b32 m0, s31
	v_mov_b32_e32 v129, 0
	global_load_lds_dwordx4 v130, s[6:7]
	v_mov_b32_e32 v131, v129
	s_cmp_eq_u32 s0, 1
	s_mov_b32 s36, 0
	s_mov_b32 s37, 0x10000
	v_lshl_add_u64 v[6:7], s[16:17], 0, v[128:129]
	v_lshl_add_u64 v[4:5], s[16:17], 0, v[130:131]
	v_lshl_add_u64 v[0:1], s[14:15], 0, v[128:129]
	s_cselect_b64 s[6:7], -1, 0
	s_cmp_lg_u32 s0, 1
	v_lshl_add_u64 v[2:3], s[14:15], 0, v[130:131]
	s_cbranch_scc1 .LBB0_336
	s_barrier
.LBB0_336:
	s_lshl_b32 s8, s33, 11
	s_add_i32 s8, s8, 0
	s_add_i32 s12, s8, 0x20000
	s_lshl_b32 s5, s5, 5
	s_mov_b64 s[8:9], 0x80
	s_and_b32 s5, s5, 0x60
	s_add_i32 m0, s26, 0x18000
	v_lshl_add_u64 v[6:7], v[6:7], 0, s[8:9]
	s_lshl_b32 s13, s0, 13
	s_lshl_b32 s20, s5, 7
	s_waitcnt vmcnt(2)
	s_barrier
	global_load_lds_dwordx4 v[6:7], off
	v_lshl_add_u64 v[4:5], v[4:5], 0, s[8:9]
	s_add_i32 m0, s26, 0x1a000
	s_add_i32 s33, s26, 0x8000
	s_add_i32 s38, s26, 0xa000
	global_load_lds_dwordx4 v[4:5], off
	v_lshl_add_u64 v[0:1], v[0:1], 0, s[8:9]
	s_mov_b32 m0, s33
	s_add_u32 s10, s16, 0x404080
	global_load_lds_dwordx4 v[0:1], off
	v_lshl_add_u64 v[0:1], v[2:3], 0, s[8:9]
	s_mov_b32 m0, s38
	s_addc_u32 s11, s17, 0
	global_load_lds_dwordx4 v[0:1], off
	s_add_i32 m0, s26, 0x1c000
	v_lshl_add_u64 v[0:1], s[10:11], 0, v[128:129]
	global_load_lds_dwordx4 v[0:1], off
	v_lshl_add_u64 v[0:1], s[10:11], 0, v[130:131]
	s_add_i32 m0, s26, 0x1e000
	v_bfe_u32 v2, v202, 4, 2
	global_load_lds_dwordx4 v[0:1], off
	s_sext_i32_i8 s47, s1
	v_and_b32_e32 v1, 15, v202
	v_lshlrev_b32_e32 v3, 4, v2
	v_lshlrev_b32_e32 v5, 2, v202
	v_lshlrev_b32_e32 v6, 6, v202
	s_movk_i32 s1, 0x3c0
	v_lshl_or_b32 v4, v1, 6, v3
	v_and_b32_e32 v5, 32, v5
	v_and_or_b32 v3, v6, s1, v3
	v_lshrrev_b32_e32 v0, 4, v202
	v_bitop3_b32 v4, v4, s13, v5 bitop3:0xde
	v_bitop3_b32 v146, s20, v3, v5 bitop3:0xf6
	v_and_b32_e32 v5, 7, v202
	s_waitcnt vmcnt(6)
	s_cmpk_lt_u32 s4, 0x100
	v_bfe_u32 v3, v202, 3, 3
	v_bitop3_b32 v6, v12, v202, 7 bitop3:0x28
	v_bitop3_b32 v0, v0, v5, 3 bitop3:0x6c
	v_bitop3_b32 v2, v2, v5, 4 bitop3:0x36
	s_cselect_b64 s[10:11], -1, 0
	v_lshlrev_b32_e32 v6, 4, v6
	v_lshl_or_b32 v147, s0, 6, v3
	v_lshlrev_b32_e32 v0, 4, v0
	v_lshlrev_b32_e32 v2, 4, v2
	v_lshl_add_u32 v1, v1, 7, s12
	v_lshl_add_u32 v3, v3, 7, s12
	s_add_i32 s41, 0, 0x10000
	s_add_i32 s42, 0, 0x14000
	s_mov_b32 s39, 0x20000
	s_ashr_i32 s40, s3, 31
	v_lshl_or_b32 v148, v5, 2, s5
	v_mov_b32_e32 v132, v128
	v_mov_b32_e32 v133, v129
	v_mov_b32_e32 v134, v130
	v_mov_b32_e32 v135, v129
	v_mov_b64_e32 v[136:137], 0x400
	v_mov_b64_e32 v[138:139], 0x3ff
	v_add_u32_e32 v149, s41, v146
	v_add_u32_e32 v150, s42, v146
	v_add_u32_e32 v151, 0, v4
	v_and_b32_e32 v242, 15, v202
	v_bfe_u32 v243, v202, 4, 2
	v_and_b32_e32 v244, 7, v242
	v_xor_b32_e32 v243, v243, v244
	v_lshlrev_b32_e32 v243, 4, v243
	v_lshl_add_u32 v243, v244, 7, v243
	v_lshrrev_b32_e32 v244, 3, v242
	v_lshl_add_u32 v243, v244, 10, v243
	v_lshrrev_b32_e32 v247, 6, v202
	v_lshrrev_b32_e32 v244, 2, v247
	v_lshl_add_u32 v151, v244, 13, v243
	v_and_b32_e32 v244, 3, v247
	v_lshl_add_u32 v146, v244, 12, v243
	v_xor_b32_e32 v250, 64, v151
	v_add_u32_e32 v149, 0x10000, v146
	v_add_u32_e32 v150, 0x14000, v146
	v_xor_b32_e32 v251, 64, v149
	v_xor_b32_e32 v252, 64, v150
	s_movk_i32 s43, 0x2080
	v_add_u32_e32 v152, v1, v0
	v_add_u32_e32 v153, v1, v2
	v_add_u32_e32 v154, v3, v6
	s_barrier
	s_branch .LBB0_339

; #define PG8_STAGE(bufoff, gbase, voff) do { _Pragma("unroll") for (int _i = 0; _i < 2; ++_i) \
;         __builtin_amdgcn_global_load_lds((const unsigned*)((const char*)(gbase) + (voff)[_i]), (LAS unsigned*)(lds + (bufoff) + ldsw + _i * 8192), 16, 0, 0); } while (0)
; #define PG8_LDA(dst, b, h) do { _Pragma("unroll") for (int m = 0; m < 4; ++m) _Pragma("unroll") for (int k = 0; k < 2; ++k) dst[m][k] = *(const LAS bf16x8*)(lds + PG8_SA(b, h) + aoff + m * 2048 + k * 1024); } while (0)
; #define PG8_LDB(dst, b, h) do { _Pragma("unroll") for (int n = 0; n < 2; ++n) _Pragma("unroll") for (int k = 0; k < 2; ++k) dst[n][k] = *(const LAS bf16x8*)(lds + PG8_SB(b, h) + boff + n * 2048 + k * 1024); } while (0)
; #define PG8_MMA(ai, bj, At, Bt) do { __builtin_amdgcn_s_setprio(3); _Pragma("unroll") for (int m = 0; m < 4; ++m) _Pragma("unroll") for (int n = 0; n < 2; ++n) _Pragma("unroll") for (int k = 0; k < 2; ++k) \
;         acc[ai][bj][m][n] = __builtin_amdgcn_mfma_f32_16x16x32_bf16(Bt[n][k], At[m][k], acc[ai][bj][m][n], 0, 0, 0); __builtin_amdgcn_s_setprio(0); } while (0)
; #define PG8_WAIT_V(n) asm volatile("s_waitcnt vmcnt(" #n ")" ::: "memory")
; #define PG8_WAIT_L(n) asm volatile("s_waitcnt lgkmcnt(" #n ")" ::: "memory")
; #define PG8_BAR __builtin_amdgcn_s_barrier()
; #define PG8_SCHED __builtin_amdgcn_sched_barrier(0)
; template <class Epi, class Sched, bool ALIGN_EPI = false, bool SP2 = false>
; __device__ __forceinline__ void gemm_phase(LAS unsigned char* lds, const Gemm g, const Sched& S, const Epi& E) {
;     ...
;             PG8_LDB(B0, 0, 0); PG8_LDB(B1, 0, 1); PG8_SCHED; PG8_LDA(At, 0, 0); PG8_STAGE(PG8_SA(1, 1), a1 + hsA, voffA);
;             PG8_WAIT_V(8); PG8_WAIT_L(0); PG8_BAR; PG8_MMA(0, 0, At, B0); PG8_MMA(0, 1, At, B1); PG8_BAR; PG8_SCHED;
;             PG8_LDA(At, 0, 1); PG8_STAGE(PG8_SB(0, 0), b2, voffB); PG8_STAGE(PG8_SB(0, 1), b2 + hsB, voffB); PG8_STAGE(PG8_SA(0, 0), a2, voffA);
;             PG8_WAIT_V(8); PG8_WAIT_L(0); PG8_BAR; PG8_MMA(1, 0, At, B0); PG8_MMA(1, 1, At, B1); PG8_BAR; PG8_SCHED;
.LBB0_350:
	ds_read_b128 v[140:143], v149
	ds_read_b128 v[156:159], v251
	ds_read_b128 v[160:163], v149 offset:2048
	ds_read_b128 v[164:167], v251 offset:2048
	ds_read_b128 v[168:171], v150
	ds_read_b128 v[172:175], v252
	ds_read_b128 v[176:179], v150 offset:2048
	ds_read_b128 v[180:183], v252 offset:2048
	s_add_u32 s16, s14, 0xffbfc080
	s_addc_u32 s17, s15, -1
	s_cmpk_eq_i32 s50, 0xfc
	s_cselect_b32 s21, s5, s17
	s_cselect_b32 s20, s4, s16
	s_cselect_b32 s17, s13, s49
	s_cselect_b32 s16, s12, s48
	v_lshl_add_u64 v[144:145], s[14:15], 0, v[132:133]
	s_add_i32 m0, s26, 0xc000
	ds_read_b128 v[184:187], v151
	ds_read_b128 v[188:191], v250
	ds_read_b128 v[192:195], v151 offset:2048
	ds_read_b128 v[196:199], v250 offset:2048
	ds_read_b128 v[200:203], v151 offset:4096
	ds_read_b128 v[204:207], v250 offset:4096
	ds_read_b128 v[208:211], v151 offset:6144
	ds_read_b128 v[212:215], v250 offset:6144
	global_load_lds_dwordx4 v[144:145], off
	v_lshl_add_u64 v[144:145], s[14:15], 0, v[134:135]
	s_add_i32 m0, s26, 0xe000
	s_nop 0
	global_load_lds_dwordx4 v[144:145], off
	s_waitcnt vmcnt(8)
	s_waitcnt lgkmcnt(0)
	s_barrier
	s_setprio 3
	s_waitcnt lgkmcnt(0)
	v_mfma_f32_16x16x32_bf16 v[124:127], v[140:143], v[184:187], v[124:127]
	v_mfma_f32_16x16x32_bf16 v[120:123], v[160:163], v[184:187], v[120:123]
	v_mfma_f32_16x16x32_bf16 v[108:111], v[140:143], v[192:195], v[108:111]
	v_mfma_f32_16x16x32_bf16 v[104:107], v[160:163], v[192:195], v[104:107]
	v_mfma_f32_16x16x32_bf16 v[92:95], v[140:143], v[200:203], v[92:95]
	v_mfma_f32_16x16x32_bf16 v[88:91], v[160:163], v[200:203], v[88:91]
	v_mfma_f32_16x16x32_bf16 v[76:79], v[140:143], v[208:211], v[76:79]
	v_mfma_f32_16x16x32_bf16 v[72:75], v[160:163], v[208:211], v[72:75]
	v_mfma_f32_16x16x32_bf16 v[124:127], v[156:159], v[188:191], v[124:127]
	v_mfma_f32_16x16x32_bf16 v[120:123], v[164:167], v[188:191], v[120:123]
	v_mfma_f32_16x16x32_bf16 v[108:111], v[156:159], v[196:199], v[108:111]
	v_mfma_f32_16x16x32_bf16 v[104:107], v[164:167], v[196:199], v[104:107]
	v_mfma_f32_16x16x32_bf16 v[92:95], v[156:159], v[204:207], v[92:95]
	v_mfma_f32_16x16x32_bf16 v[88:91], v[164:167], v[204:207], v[88:91]
	v_mfma_f32_16x16x32_bf16 v[76:79], v[156:159], v[212:215], v[76:79]
	v_mfma_f32_16x16x32_bf16 v[72:75], v[164:167], v[212:215], v[72:75]
	s_setprio 0
	s_setprio 3
	v_mfma_f32_16x16x32_bf16 v[116:119], v[168:171], v[184:187], v[116:119]
	v_mfma_f32_16x16x32_bf16 v[112:115], v[176:179], v[184:187], v[112:115]
	v_mfma_f32_16x16x32_bf16 v[100:103], v[168:171], v[192:195], v[100:103]
	v_mfma_f32_16x16x32_bf16 v[96:99], v[176:179], v[192:195], v[96:99]
	v_mfma_f32_16x16x32_bf16 v[84:87], v[168:171], v[200:203], v[84:87]
	v_mfma_f32_16x16x32_bf16 v[80:83], v[176:179], v[200:203], v[80:83]
	v_mfma_f32_16x16x32_bf16 v[68:71], v[168:171], v[208:211], v[68:71]
	v_mfma_f32_16x16x32_bf16 v[64:67], v[176:179], v[208:211], v[64:67]
	v_mfma_f32_16x16x32_bf16 v[116:119], v[172:175], v[188:191], v[116:119]
	v_mfma_f32_16x16x32_bf16 v[112:115], v[180:183], v[188:191], v[112:115]
	v_mfma_f32_16x16x32_bf16 v[100:103], v[172:175], v[196:199], v[100:103]
	v_mfma_f32_16x16x32_bf16 v[96:99], v[180:183], v[196:199], v[96:99]
	v_mfma_f32_16x16x32_bf16 v[84:87], v[172:175], v[204:207], v[84:87]
	v_mfma_f32_16x16x32_bf16 v[80:83], v[180:183], v[204:207], v[80:83]
	v_mfma_f32_16x16x32_bf16 v[68:71], v[172:175], v[212:215], v[68:71]
	v_mfma_f32_16x16x32_bf16 v[64:67], v[180:183], v[212:215], v[64:67]
	s_setprio 0
	s_barrier
	s_add_i32 s51, s41, s25
	v_lshl_add_u64 v[144:145], s[16:17], 0, v[128:129]
	s_mov_b32 m0, s51
	ds_read_b128 v[184:187], v151 offset:16384
	ds_read_b128 v[188:191], v250 offset:16384
	ds_read_b128 v[192:195], v151 offset:18432
	ds_read_b128 v[196:199], v250 offset:18432
	ds_read_b128 v[200:203], v151 offset:20480
	ds_read_b128 v[204:207], v250 offset:20480
	ds_read_b128 v[208:211], v151 offset:22528
	ds_read_b128 v[212:215], v250 offset:22528
	global_load_lds_dwordx4 v[144:145], off
	s_add_i32 m0, s51, 0x2000
	s_add_u32 s52, s16, 0x404000
	v_lshl_add_u64 v[216:217], s[16:17], 0, v[130:131]
	s_addc_u32 s53, s17, 0
	s_add_i32 s51, s42, s25
	global_load_lds_dwordx4 v[216:217], off
	v_lshl_add_u64 v[218:219], s[52:53], 0, v[128:129]
	s_mov_b32 m0, s51
	v_lshl_add_u64 v[220:221], s[20:21], 0, v[130:131]
	global_load_lds_dwordx4 v[218:219], off
	v_lshl_add_u64 v[218:219], s[52:53], 0, v[130:131]
	s_add_i32 m0, s51, 0x2000
	s_nop 0
	global_load_lds_dwordx4 v[218:219], off
	v_lshl_add_u64 v[218:219], s[20:21], 0, v[128:129]
	s_mov_b32 m0, s26
	s_nop 0
	global_load_lds_dwordx4 v[218:219], off
	s_mov_b32 m0, s27
	s_nop 0
	global_load_lds_dwordx4 v[220:221], off
	s_waitcnt vmcnt(8)
	s_waitcnt lgkmcnt(0)
	s_barrier
; #define PG8_STAGE(bufoff, gbase, voff) do { _Pragma("unroll") for (int _i = 0; _i < 2; ++_i) \
;         __builtin_amdgcn_global_load_lds((const unsigned*)((const char*)(gbase) + (voff)[_i]), (LAS unsigned*)(lds + (bufoff) + ldsw + _i * 8192), 16, 0, 0); } while (0)
; #define PG8_LDA(dst, b, h) do { _Pragma("unroll") for (int m = 0; m < 4; ++m) _Pragma("unroll") for (int k = 0; k < 2; ++k) dst[m][k] = *(const LAS bf16x8*)(lds + PG8_SA(b, h) + aoff + m * 2048 + k * 1024); } while (0)
; #define PG8_LDB(dst, b, h) do { _Pragma("unroll") for (int n = 0; n < 2; ++n) _Pragma("unroll") for (int k = 0; k < 2; ++k) dst[n][k] = *(const LAS bf16x8*)(lds + PG8_SB(b, h) + boff + n * 2048 + k * 1024); } while (0)
; #define PG8_MMA(ai, bj, At, Bt) do { __builtin_amdgcn_s_setprio(3); _Pragma("unroll") for (int m = 0; m < 4; ++m) _Pragma("unroll") for (int n = 0; n < 2; ++n) _Pragma("unroll") for (int k = 0; k < 2; ++k) \
;         acc[ai][bj][m][n] = __builtin_amdgcn_mfma_f32_16x16x32_bf16(Bt[n][k], At[m][k], acc[ai][bj][m][n], 0, 0, 0); __builtin_amdgcn_s_setprio(0); } while (0)
; #define PG8_WAIT_V(n) asm volatile("s_waitcnt vmcnt(" #n ")" ::: "memory")
; #define PG8_WAIT_L(n) asm volatile("s_waitcnt lgkmcnt(" #n ")" ::: "memory")
; #define PG8_BAR __builtin_amdgcn_s_barrier()
; #define PG8_SCHED __builtin_amdgcn_sched_barrier(0)
; template <class Epi, class Sched, bool ALIGN_EPI = false, bool SP2 = false>
; __device__ __forceinline__ void gemm_phase(LAS unsigned char* lds, const Gemm g, const Sched& S, const Epi& E) {
;     ...
;             PG8_WAIT_V(8); PG8_WAIT_L(0); PG8_BAR; PG8_MMA(1, 0, At, B0); PG8_MMA(1, 1, At, B1); PG8_BAR; PG8_SCHED;
;             PG8_LDB(B0, 1, 0); PG8_LDB(B1, 1, 1); PG8_SCHED; PG8_LDA(At, 1, 0); PG8_STAGE(PG8_SA(0, 1), a2 + hsA, voffA);
;             PG8_WAIT_V(8); PG8_WAIT_L(0); PG8_BAR; PG8_MMA(0, 0, At, B0); PG8_MMA(0, 1, At, B1); PG8_BAR; PG8_SCHED;
	s_setprio 3
	s_waitcnt lgkmcnt(0)
	v_mfma_f32_16x16x32_bf16 v[60:63], v[140:143], v[184:187], v[60:63]
	v_mfma_f32_16x16x32_bf16 v[56:59], v[160:163], v[184:187], v[56:59]
	v_mfma_f32_16x16x32_bf16 v[44:47], v[140:143], v[192:195], v[44:47]
	v_mfma_f32_16x16x32_bf16 v[40:43], v[160:163], v[192:195], v[40:43]
	v_mfma_f32_16x16x32_bf16 v[28:31], v[140:143], v[200:203], v[28:31]
	v_mfma_f32_16x16x32_bf16 v[24:27], v[160:163], v[200:203], v[24:27]
	v_mfma_f32_16x16x32_bf16 v[12:15], v[140:143], v[208:211], v[12:15]
	v_mfma_f32_16x16x32_bf16 v[8:11], v[160:163], v[208:211], v[8:11]
	v_mfma_f32_16x16x32_bf16 v[60:63], v[156:159], v[188:191], v[60:63]
	v_mfma_f32_16x16x32_bf16 v[56:59], v[164:167], v[188:191], v[56:59]
	v_mfma_f32_16x16x32_bf16 v[44:47], v[156:159], v[196:199], v[44:47]
	v_mfma_f32_16x16x32_bf16 v[40:43], v[164:167], v[196:199], v[40:43]
	v_mfma_f32_16x16x32_bf16 v[28:31], v[156:159], v[204:207], v[28:31]
	v_mfma_f32_16x16x32_bf16 v[24:27], v[164:167], v[204:207], v[24:27]
	v_mfma_f32_16x16x32_bf16 v[12:15], v[156:159], v[212:215], v[12:15]
	v_mfma_f32_16x16x32_bf16 v[8:11], v[164:167], v[212:215], v[8:11]
	s_setprio 0
	s_setprio 3
	v_mfma_f32_16x16x32_bf16 v[52:55], v[168:171], v[184:187], v[52:55]
	v_mfma_f32_16x16x32_bf16 v[48:51], v[176:179], v[184:187], v[48:51]
	v_mfma_f32_16x16x32_bf16 v[36:39], v[168:171], v[192:195], v[36:39]
	v_mfma_f32_16x16x32_bf16 v[32:35], v[176:179], v[192:195], v[32:35]
	v_mfma_f32_16x16x32_bf16 v[20:23], v[168:171], v[200:203], v[20:23]
	v_mfma_f32_16x16x32_bf16 v[16:19], v[176:179], v[200:203], v[16:19]
	v_mfma_f32_16x16x32_bf16 v[4:7], v[168:171], v[208:211], v[4:7]
	v_mfma_f32_16x16x32_bf16 v[0:3], v[176:179], v[208:211], v[0:3]
	v_mfma_f32_16x16x32_bf16 v[52:55], v[172:175], v[188:191], v[52:55]
	v_mfma_f32_16x16x32_bf16 v[48:51], v[180:183], v[188:191], v[48:51]
	v_mfma_f32_16x16x32_bf16 v[36:39], v[172:175], v[196:199], v[36:39]
	v_mfma_f32_16x16x32_bf16 v[32:35], v[180:183], v[196:199], v[32:35]
	v_mfma_f32_16x16x32_bf16 v[20:23], v[172:175], v[204:207], v[20:23]
	v_mfma_f32_16x16x32_bf16 v[16:19], v[180:183], v[204:207], v[16:19]
	v_mfma_f32_16x16x32_bf16 v[4:7], v[172:175], v[212:215], v[4:7]
	v_mfma_f32_16x16x32_bf16 v[0:3], v[180:183], v[212:215], v[0:3]
	s_setprio 0
	s_barrier
	s_add_i32 s51, 0, 0x18000
	v_add_u32_e32 v155, s51, v146
	v_xor_b32_e32 v253, 64, v155
	s_add_i32 s52, 0, 0x1c000
	ds_read_b128 v[140:143], v155
	ds_read_b128 v[156:159], v253
	ds_read_b128 v[160:163], v155 offset:2048
	ds_read_b128 v[164:167], v253 offset:2048
	v_add_u32_e32 v155, s52, v146
	v_xor_b32_e32 v253, 64, v155
	ds_read_b128 v[168:171], v155
	ds_read_b128 v[172:175], v253
	ds_read_b128 v[176:179], v155 offset:2048
	ds_read_b128 v[180:183], v253 offset:2048
	s_add_u32 s20, s20, 0x404000
	s_addc_u32 s21, s21, 0
	s_mov_b32 m0, s30
	v_lshl_add_u64 v[222:223], s[20:21], 0, v[128:129]
	ds_read_b128 v[184:187], v151 offset:32768
	ds_read_b128 v[188:191], v250 offset:32768
	ds_read_b128 v[192:195], v151 offset:34816
	ds_read_b128 v[196:199], v250 offset:34816
	ds_read_b128 v[200:203], v151 offset:36864
	ds_read_b128 v[204:207], v250 offset:36864
	ds_read_b128 v[208:211], v151 offset:38912
	ds_read_b128 v[212:215], v250 offset:38912
	global_load_lds_dwordx4 v[222:223], off
	v_lshl_add_u64 v[222:223], s[20:21], 0, v[130:131]
	s_mov_b32 m0, s31
	s_nop 0
	global_load_lds_dwordx4 v[222:223], off
	s_waitcnt vmcnt(8)
	s_waitcnt lgkmcnt(0)
	s_barrier
	s_setprio 3
	s_waitcnt lgkmcnt(0)
	v_mfma_f32_16x16x32_bf16 v[124:127], v[140:143], v[184:187], v[124:127]
	v_mfma_f32_16x16x32_bf16 v[120:123], v[160:163], v[184:187], v[120:123]
	v_mfma_f32_16x16x32_bf16 v[108:111], v[140:143], v[192:195], v[108:111]
	v_mfma_f32_16x16x32_bf16 v[104:107], v[160:163], v[192:195], v[104:107]
	v_mfma_f32_16x16x32_bf16 v[92:95], v[140:143], v[200:203], v[92:95]
	v_mfma_f32_16x16x32_bf16 v[88:91], v[160:163], v[200:203], v[88:91]
	v_mfma_f32_16x16x32_bf16 v[76:79], v[140:143], v[208:211], v[76:79]
	v_mfma_f32_16x16x32_bf16 v[72:75], v[160:163], v[208:211], v[72:75]
	v_mfma_f32_16x16x32_bf16 v[124:127], v[156:159], v[188:191], v[124:127]
	v_mfma_f32_16x16x32_bf16 v[120:123], v[164:167], v[188:191], v[120:123]
	v_mfma_f32_16x16x32_bf16 v[108:111], v[156:159], v[196:199], v[108:111]
	v_mfma_f32_16x16x32_bf16 v[104:107], v[164:167], v[196:199], v[104:107]
	v_mfma_f32_16x16x32_bf16 v[92:95], v[156:159], v[204:207], v[92:95]
	v_mfma_f32_16x16x32_bf16 v[88:91], v[164:167], v[204:207], v[88:91]
	v_mfma_f32_16x16x32_bf16 v[76:79], v[156:159], v[212:215], v[76:79]
	v_mfma_f32_16x16x32_bf16 v[72:75], v[164:167], v[212:215], v[72:75]
	s_setprio 0
	s_setprio 3
	v_mfma_f32_16x16x32_bf16 v[116:119], v[168:171], v[184:187], v[116:119]
	v_mfma_f32_16x16x32_bf16 v[112:115], v[176:179], v[184:187], v[112:115]
	v_mfma_f32_16x16x32_bf16 v[100:103], v[168:171], v[192:195], v[100:103]
	v_mfma_f32_16x16x32_bf16 v[96:99], v[176:179], v[192:195], v[96:99]
	v_mfma_f32_16x16x32_bf16 v[84:87], v[168:171], v[200:203], v[84:87]
	v_mfma_f32_16x16x32_bf16 v[80:83], v[176:179], v[200:203], v[80:83]
	v_mfma_f32_16x16x32_bf16 v[68:71], v[168:171], v[208:211], v[68:71]
	v_mfma_f32_16x16x32_bf16 v[64:67], v[176:179], v[208:211], v[64:67]
	v_mfma_f32_16x16x32_bf16 v[116:119], v[172:175], v[188:191], v[116:119]
	v_mfma_f32_16x16x32_bf16 v[112:115], v[180:183], v[188:191], v[112:115]
	v_mfma_f32_16x16x32_bf16 v[100:103], v[172:175], v[196:199], v[100:103]
	v_mfma_f32_16x16x32_bf16 v[96:99], v[180:183], v[196:199], v[96:99]
	v_mfma_f32_16x16x32_bf16 v[84:87], v[172:175], v[204:207], v[84:87]
	v_mfma_f32_16x16x32_bf16 v[80:83], v[180:183], v[204:207], v[80:83]
	v_mfma_f32_16x16x32_bf16 v[68:71], v[172:175], v[212:215], v[68:71]
	v_mfma_f32_16x16x32_bf16 v[64:67], v[180:183], v[212:215], v[64:67]
	s_setprio 0
	s_barrier
; #define PG8_STAGE(bufoff, gbase, voff) do { _Pragma("unroll") for (int _i = 0; _i < 2; ++_i) \
;         __builtin_amdgcn_global_load_lds((const unsigned*)((const char*)(gbase) + (voff)[_i]), (LAS unsigned*)(lds + (bufoff) + ldsw + _i * 8192), 16, 0, 0); } while (0)
; #define PG8_LDA(dst, b, h) do { _Pragma("unroll") for (int m = 0; m < 4; ++m) _Pragma("unroll") for (int k = 0; k < 2; ++k) dst[m][k] = *(const LAS bf16x8*)(lds + PG8_SA(b, h) + aoff + m * 2048 + k * 1024); } while (0)
; #define PG8_MMA(ai, bj, At, Bt) do { __builtin_amdgcn_s_setprio(3); _Pragma("unroll") for (int m = 0; m < 4; ++m) _Pragma("unroll") for (int n = 0; n < 2; ++n) _Pragma("unroll") for (int k = 0; k < 2; ++k) \
;         acc[ai][bj][m][n] = __builtin_amdgcn_mfma_f32_16x16x32_bf16(Bt[n][k], At[m][k], acc[ai][bj][m][n], 0, 0, 0); __builtin_amdgcn_s_setprio(0); } while (0)
; #define PG8_WAIT_V(n) asm volatile("s_waitcnt vmcnt(" #n ")" ::: "memory")
; #define PG8_WAIT_L(n) asm volatile("s_waitcnt lgkmcnt(" #n ")" ::: "memory")
; #define PG8_BAR __builtin_amdgcn_s_barrier()
; #define PG8_SCHED __builtin_amdgcn_sched_barrier(0)
; template <class Epi, class Sched, bool ALIGN_EPI = false, bool SP2 = false>
; __device__ __forceinline__ void gemm_phase(LAS unsigned char* lds, const Gemm g, const Sched& S, const Epi& E) {
;     ...
;             PG8_LDA(At, 1, 1); PG8_STAGE(PG8_SB(1, 0), b3, voffB); PG8_STAGE(PG8_SB(1, 1), b3 + hsB, voffB); PG8_STAGE(PG8_SA(1, 0), a3, voffA);
;             PG8_WAIT_V(8); PG8_WAIT_L(0); PG8_BAR; PG8_MMA(1, 0, At, B0); PG8_MMA(1, 1, At, B1); PG8_BAR; PG8_SCHED;
	s_add_i32 s20, s51, s25
	v_lshl_add_u64 v[144:145], v[144:145], 0, s[8:9]
	s_mov_b32 m0, s20
	ds_read_b128 v[184:187], v151 offset:49152
	ds_read_b128 v[188:191], v250 offset:49152
	ds_read_b128 v[192:195], v151 offset:51200
	ds_read_b128 v[196:199], v250 offset:51200
	ds_read_b128 v[200:203], v151 offset:53248
	ds_read_b128 v[204:207], v250 offset:53248
	ds_read_b128 v[208:211], v151 offset:55296
	ds_read_b128 v[212:215], v250 offset:55296
	global_load_lds_dwordx4 v[144:145], off
	s_add_i32 m0, s20, 0x2000
	s_add_u32 s16, s16, 0x404080
	v_lshl_add_u64 v[144:145], v[216:217], 0, s[8:9]
	s_addc_u32 s17, s17, 0
	s_add_i32 s20, s52, s25
	global_load_lds_dwordx4 v[144:145], off
	v_lshl_add_u64 v[144:145], s[16:17], 0, v[128:129]
	s_mov_b32 m0, s20
	s_nop 0
	global_load_lds_dwordx4 v[144:145], off
	v_lshl_add_u64 v[144:145], s[16:17], 0, v[130:131]
	s_add_i32 m0, s20, 0x2000
	s_nop 0
	global_load_lds_dwordx4 v[144:145], off
	v_lshl_add_u64 v[144:145], v[218:219], 0, s[8:9]
	s_mov_b32 m0, s33
	s_nop 0
	global_load_lds_dwordx4 v[144:145], off
	v_lshl_add_u64 v[144:145], v[220:221], 0, s[8:9]
	s_mov_b32 m0, s38
	s_nop 0
	global_load_lds_dwordx4 v[144:145], off
	s_waitcnt vmcnt(8)
	s_waitcnt lgkmcnt(0)
	s_barrier
	s_setprio 3
	s_waitcnt lgkmcnt(0)
	v_mfma_f32_16x16x32_bf16 v[60:63], v[140:143], v[184:187], v[60:63]
	v_mfma_f32_16x16x32_bf16 v[56:59], v[160:163], v[184:187], v[56:59]
	v_mfma_f32_16x16x32_bf16 v[44:47], v[140:143], v[192:195], v[44:47]
	v_mfma_f32_16x16x32_bf16 v[40:43], v[160:163], v[192:195], v[40:43]
	v_mfma_f32_16x16x32_bf16 v[28:31], v[140:143], v[200:203], v[28:31]
	v_mfma_f32_16x16x32_bf16 v[24:27], v[160:163], v[200:203], v[24:27]
	v_mfma_f32_16x16x32_bf16 v[12:15], v[140:143], v[208:211], v[12:15]
	v_mfma_f32_16x16x32_bf16 v[8:11], v[160:163], v[208:211], v[8:11]
	v_mfma_f32_16x16x32_bf16 v[60:63], v[156:159], v[188:191], v[60:63]
	v_mfma_f32_16x16x32_bf16 v[56:59], v[164:167], v[188:191], v[56:59]
	v_mfma_f32_16x16x32_bf16 v[44:47], v[156:159], v[196:199], v[44:47]
	v_mfma_f32_16x16x32_bf16 v[40:43], v[164:167], v[196:199], v[40:43]
	v_mfma_f32_16x16x32_bf16 v[28:31], v[156:159], v[204:207], v[28:31]
	v_mfma_f32_16x16x32_bf16 v[24:27], v[164:167], v[204:207], v[24:27]
	v_mfma_f32_16x16x32_bf16 v[12:15], v[156:159], v[212:215], v[12:15]
	v_mfma_f32_16x16x32_bf16 v[8:11], v[164:167], v[212:215], v[8:11]
	s_setprio 0
	s_setprio 3
	v_mfma_f32_16x16x32_bf16 v[52:55], v[168:171], v[184:187], v[52:55]
	v_mfma_f32_16x16x32_bf16 v[48:51], v[176:179], v[184:187], v[48:51]
	v_mfma_f32_16x16x32_bf16 v[36:39], v[168:171], v[192:195], v[36:39]
	v_mfma_f32_16x16x32_bf16 v[32:35], v[176:179], v[192:195], v[32:35]
	v_mfma_f32_16x16x32_bf16 v[20:23], v[168:171], v[200:203], v[20:23]
	v_mfma_f32_16x16x32_bf16 v[16:19], v[176:179], v[200:203], v[16:19]
	v_mfma_f32_16x16x32_bf16 v[4:7], v[168:171], v[208:211], v[4:7]
	v_mfma_f32_16x16x32_bf16 v[0:3], v[176:179], v[208:211], v[0:3]
	v_mfma_f32_16x16x32_bf16 v[52:55], v[172:175], v[188:191], v[52:55]
	v_mfma_f32_16x16x32_bf16 v[48:51], v[180:183], v[188:191], v[48:51]
	v_mfma_f32_16x16x32_bf16 v[36:39], v[172:175], v[196:199], v[36:39]
	v_mfma_f32_16x16x32_bf16 v[32:35], v[180:183], v[196:199], v[32:35]
	v_mfma_f32_16x16x32_bf16 v[20:23], v[172:175], v[204:207], v[20:23]
	v_mfma_f32_16x16x32_bf16 v[16:19], v[180:183], v[204:207], v[16:19]
	v_mfma_f32_16x16x32_bf16 v[4:7], v[172:175], v[212:215], v[4:7]
	v_mfma_f32_16x16x32_bf16 v[0:3], v[180:183], v[212:215], v[0:3]
	s_setprio 0
	s_barrier
	s_add_i32 s50, s50, 2
	s_add_u32 s14, s14, 0x100
	s_addc_u32 s15, s15, 0
	s_add_u32 s48, s48, 0x100
	s_addc_u32 s49, s49, 0
	s_cmpk_gt_u32 s50, 0xfd
	s_cbranch_scc0 .LBB0_350
	s_and_b64 vcc, exec, s[10:11]
	s_cbranch_vccz .LBB0_353
	s_barrier

; __global__ void __launch_bounds__(NWAVES * 64, 2) fwd_mega(Args args) {
	.amdhsa_kernel _Z8fwd_mega4Args
		.amdhsa_group_segment_fixed_size 0
		.amdhsa_private_segment_fixed_size 0
		.amdhsa_kernarg_size 408
		.amdhsa_user_sgpr_count 2
		.amdhsa_user_sgpr_dispatch_ptr 0
		.amdhsa_user_sgpr_queue_ptr 0
		.amdhsa_user_sgpr_kernarg_segment_ptr 1
		.amdhsa_user_sgpr_dispatch_id 0
		.amdhsa_user_sgpr_kernarg_preload_length 0
		.amdhsa_user_sgpr_kernarg_preload_offset 0
		.amdhsa_user_sgpr_private_segment_size 0
		.amdhsa_uses_dynamic_stack 0
		.amdhsa_enable_private_segment 0
		.amdhsa_system_sgpr_workgroup_id_x 1
		.amdhsa_system_sgpr_workgroup_id_y 0
		.amdhsa_system_sgpr_workgroup_id_z 0
		.amdhsa_system_sgpr_workgroup_info 0
		.amdhsa_system_vgpr_workitem_id 2
		.amdhsa_next_free_vgpr 256
		.amdhsa_next_free_sgpr 99
		.amdhsa_accum_offset 256
		.amdhsa_reserve_vcc 1
		.amdhsa_float_round_mode_32 0
		.amdhsa_float_round_mode_16_64 0
		.amdhsa_float_denorm_mode_32 3
		.amdhsa_float_denorm_mode_16_64 3
		.amdhsa_dx10_clamp 1
		.amdhsa_ieee_mode 1
		.amdhsa_fp16_overflow 0
		.amdhsa_tg_split 0
		.amdhsa_exception_fp_ieee_invalid_op 0
		.amdhsa_exception_fp_denorm_src 0
		.amdhsa_exception_fp_ieee_div_zero 0
		.amdhsa_exception_fp_ieee_overflow 0
		.amdhsa_exception_fp_ieee_underflow 0
		.amdhsa_exception_fp_ieee_inexact 0
		.amdhsa_exception_int_div_zero 0
	.end_amdhsa_kernel

; __global__ void __launch_bounds__(NWAVES * 64, 2) fwd_mega(Args args) {
amdhsa.kernels:
  - .agpr_count:     0
    .args:
      - .offset:         0
        .size:           152
        .value_kind:     by_value
      - .offset:         152
        .size:           4
        .value_kind:     hidden_block_count_x
      - .offset:         156
        .size:           4
        .value_kind:     hidden_block_count_y
      - .offset:         160
        .size:           4
        .value_kind:     hidden_block_count_z
      - .offset:         164
        .size:           2
        .value_kind:     hidden_group_size_x
      - .offset:         166
        .size:           2
        .value_kind:     hidden_group_size_y
      - .offset:         168
        .size:           2
        .value_kind:     hidden_group_size_z
      - .offset:         170
        .size:           2
        .value_kind:     hidden_remainder_x
      - .offset:         172
        .size:           2
        .value_kind:     hidden_remainder_y
      - .offset:         174
        .size:           2
        .value_kind:     hidden_remainder_z
      - .offset:         192
        .size:           8
        .value_kind:     hidden_global_offset_x
      - .offset:         200
        .size:           8
        .value_kind:     hidden_global_offset_y
      - .offset:         208
        .size:           8
        .value_kind:     hidden_global_offset_z
      - .offset:         216
        .size:           2
        .value_kind:     hidden_grid_dims
      - .offset:         240
        .size:           8
        .value_kind:     hidden_multigrid_sync_arg
      - .offset:         272
        .size:           4
        .value_kind:     hidden_dynamic_lds_size
    .group_segment_fixed_size: 0
    .kernarg_segment_align: 8
    .kernarg_segment_size: 408
    .language:       OpenCL C
    .language_version:
      - 2
      - 0
    .max_flat_workgroup_size: 512
    .name:           _Z8fwd_mega4Args
    .private_segment_fixed_size: 0
    .sgpr_count:     105
    .sgpr_spill_count: 0
    .symbol:         _Z8fwd_mega4Args.kd
    .uniform_work_group_size: 1
    .uses_dynamic_stack: false
    .vgpr_count:     256
    .vgpr_spill_count: 0
    .wavefront_size: 64
